# SSM: B*u MFMAs of the next tile issued inside the current tile (software pipeline), time-contiguous register sets
# baseline (speedup 1.0000x reference)
.LBB0_340:
	s_cmp_lt_i32 s96, 4
	s_cselect_b64 s[0:1], -1, 0
	s_and_b64 s[8:9], s[0:1], s[4:5]
	s_andn2_b64 vcc, exec, s[8:9]
	s_cbranch_vccnz .LBB0_393
	v_cmp_gt_u32_e32 vcc, 2, v190
	s_and_saveexec_b64 s[0:1], vcc
	v_lshlrev_b32_e32 v2, 2, v190
	v_add_u32_e32 v2, 0x21000, v2
	v_mov_b32_e32 v3, 0
	ds_write_b32 v2, v3
	s_mov_b64 exec, s[0:1]
	v_and_b32_e32 v172, 31, v191
	v_lshrrev_b32_e32 v173, 5, v191
	v_and_b32_e32 v174, 1, v191
	v_and_b32_e32 v175, 15, v191
	v_lshrrev_b32_e32 v176, 4, v191
	s_mul_i32 s20, s89, 0x3200
	v_lshl_add_u32 v151, v191, 2, s20
	v_mul_u32_u24_e32 v182, 0x110, v175
	v_lshl_add_u32 v182, v176, 4, v182
	v_add_u32_e32 v152, s20, v182
	v_and_b32_e32 v182, 3, v172
	v_lshrrev_b32_e32 v183, 3, v172
	v_lshl_add_u32 v182, v183, 2, v182
	v_lshlrev_b32_e32 v182, 5, v182
	v_lshl_add_u32 v150, v173, 4, v182
	s_mov_b32 s66, 0x0f0f0f0f
	s_mov_b32 s67, 0x0f0f0f0f
	s_mov_b32 s68, 0xf0f0f0f0
	s_mov_b32 s69, 0xf0f0f0f0
	s_add_u32 s22, s20, 0x2200
	v_add_u32_e32 v162, s22, v150
	v_lshlrev_b32_e32 v182, 5, v175
	v_lshl_add_u32 v182, v176, 3, v182
	v_add_u32_e32 v163, s22, v182
	v_mul_u32_u24_e32 v182, 0x1800, v175
	v_lshl_add_u32 v154, v176, 3, v182
	v_add_u32_e32 v158, 0x18000, v154
	v_lshlrev_b32_e32 v182, 12, v175
	v_lshlrev_b32_e32 v182, 6, v175
	v_lshl_add_u32 v153, v176, 4, v182
	v_add_u32_e32 v157, 0x400, v153
	v_lshlrev_b32_e32 v182, 11, v175
	v_lshl_add_u32 v156, v176, 3, v182
	v_add_u32_e32 v159, 0x8000, v156
	s_and_b32 s21, s89, 3
	s_lshl_b32 s21, s21, 13
	s_add_u32 s21, s21, 0x19000
	v_lshlrev_b32_e32 v182, 5, v175
	v_lshl_add_u32 v182, v176, 3, v182
	v_add_u32_e32 v155, s21, v182
	v_lshrrev_b32_e32 v182, 4, v172
	v_lshlrev_b32_e32 v182, 10, v182
	v_lshl_add_u32 v182, v175, 4, v182
	v_lshl_add_u32 v177, v173, 8, v182
	v_lshrrev_b32_e32 v182, 1, v176
	v_lshlrev_b32_e32 v182, 8, v182
	v_and_b32_e32 v183, 1, v176
	v_lshl_add_u32 v182, v183, 3, v182
	v_lshl_add_u32 v178, v175, 4, v182
	v_lshrrev_b32_e32 v182, 1, v172
	v_lshl_add_u32 v182, v173, 5, v182
	v_lshlrev_b32_e32 v179, 3, v182
	v_lshlrev_b32_e32 v183, 14, v174
	v_lshl_add_u32 v180, v182, 2, v183
	v_lshlrev_b32_e32 v181, 4, v176
	s_waitcnt vmcnt(0) lgkmcnt(0)
	s_barrier
	s_cmp_lt_u32 s89, 4
	s_cbranch_scc0 .Lssm_ctx
	s_lshr_b32 s21, s89, 1
	s_and_b32 s22, s2, 7
	s_lshl_b32 s22, s22, 6
	s_lshr_b32 s26, s2, 3
	s_lshl_b32 s26, s26, 1
	s_add_u32 s22, s22, s26
	s_add_u32 s22, s22, s21
	s_lshr_b32 s23, s22, 6
	s_and_b32 s24, s22, 63
	s_lshl_b32 s25, s23, 10
	s_add_u32 s25, s25, 0x2000
	s_and_b32 s26, s89, 1
	s_cmp_eq_u32 s26, 0
	s_cbranch_scc0 .Lssm_lat_bwd
	s_add_u32 s28, s24, 0
	s_lshl_b32 s29, s28, 13
	s_add_u32 s29, s29, 0x200000
	s_add_u32 s10, s62, s29
	s_addc_u32 s11, s63, 0
	global_load_dwordx4 v[84:87], v177, s[10:11]
	global_load_dwordx4 v[88:91], v177, s[10:11] offset:2048
	s_add_u32 s12, s10, 0x1000
	s_addc_u32 s13, s11, 0
	global_load_dwordx4 v[92:95], v177, s[12:13]
	global_load_dwordx4 v[96:99], v177, s[12:13] offset:2048
	s_lshl_b32 s29, s28, 12
	s_add_u32 s29, s29, 0x300000
	s_add_u32 s16, s62, s29
	s_addc_u32 s17, s63, 0
	global_load_dwordx2 v[20:21], v178, s[16:17]
	global_load_dwordx2 v[22:23], v178, s[16:17] offset:1024
	global_load_dwordx2 v[24:25], v178, s[16:17] offset:512
	global_load_dwordx2 v[26:27], v178, s[16:17] offset:1536
	global_load_dwordx2 v[28:29], v178, s[16:17] offset:2048
	global_load_dwordx2 v[30:31], v178, s[16:17] offset:3072
	global_load_dwordx2 v[32:33], v178, s[16:17] offset:2560
	global_load_dwordx2 v[34:35], v178, s[16:17] offset:3584
	s_lshl_b32 s29, s28, 9
	s_add_u32 s29, s29, 0x100000
	s_add_u32 s18, s62, s29
	s_addc_u32 s19, s63, 0
	global_load_dwordx2 v[116:117], v179, s[18:19]
	global_load_dwordx2 v[118:119], v179, s[18:19] offset:128
	s_lshl_b32 s30, s23, 1
	s_lshl_b32 s30, s30, 15
	s_lshl_b32 s31, s24, 8
	s_add_u32 s30, s30, s31
	v_readlane_b32 s34, v254, 10
	v_readlane_b32 s35, v254, 11
	s_nop 3
	s_add_u32 s34, s34, s30
	s_addc_u32 s35, s35, 0
	global_load_dword v120, v180, s[34:35]
	global_load_dword v121, v180, s[34:35] offset:64
	v_readlane_b32 s34, v254, 28
	v_readlane_b32 s35, v254, 29
	s_nop 3
	s_lshl_b32 s31, s24, 6
	s_add_u32 s34, s34, s31
	s_addc_u32 s35, s35, 0
	global_load_dwordx4 v[164:167], v181, s[34:35]
	s_lshl_b32 s31, s25, 5
	s_lshl_b32 s29, s24, 19
	s_add_u32 s31, s31, s29
	s_add_u32 s31, s31, 0x16800000
	s_add_u32 s4, s62, s31
	s_addc_u32 s5, s63, 0
	s_lshl_b32 s31, s22, 1
	s_lshl_b32 s31, s31, 15
	s_add_u32 s31, s31, 0x4800000
	s_add_u32 s6, s62, s31
	s_addc_u32 s7, s63, 0
	s_add_u32 s34, s4, 0
	s_addc_u32 s35, s5, 0
	global_load_dwordx4 v[80:83], v150, s[34:35]
	global_load_dwordx4 v[194:197], v150, s[34:35] offset:512
	s_mov_b64 s[10:11], s[34:35]
	s_add_u32 s10, s10, 1024
	s_addc_u32 s11, s11, 0
	global_load_dwordx4 v[144:147], v150, s[10:11]
	global_load_dwordx4 v[168:171], v150, s[10:11] offset:512
	s_add_u32 s10, s10, 1024
	s_addc_u32 s11, s11, 0
	s_add_u32 s12, s6, 0
	s_addc_u32 s13, s7, 0
	s_mov_b32 s14, 0
	s_mov_b32 s40, 0xffff0000
	s_waitcnt vmcnt(0)
	v_and_b32_e32 v182, 0xffff, v20
	v_lshrrev_b32_e32 v183, 16, v20
	v_and_b32_e32 v184, 0xffff, v21
	v_lshrrev_b32_e32 v185, 16, v21
	v_lshl_or_b32 v100, v22, 16, v182
	v_and_or_b32 v101, v22, s40, v183
	v_lshl_or_b32 v102, v23, 16, v184
	v_and_or_b32 v103, v23, s40, v185
	v_and_b32_e32 v182, 0xffff, v24
	v_lshrrev_b32_e32 v183, 16, v24
	v_and_b32_e32 v184, 0xffff, v25
	v_lshrrev_b32_e32 v185, 16, v25
	v_lshl_or_b32 v104, v26, 16, v182
	v_and_or_b32 v105, v26, s40, v183
	v_lshl_or_b32 v106, v27, 16, v184
	v_and_or_b32 v107, v27, s40, v185
	v_and_b32_e32 v182, 0xffff, v28
	v_lshrrev_b32_e32 v183, 16, v28
	v_and_b32_e32 v184, 0xffff, v29
	v_lshrrev_b32_e32 v185, 16, v29
	v_lshl_or_b32 v108, v30, 16, v182
	v_and_or_b32 v109, v30, s40, v183
	v_lshl_or_b32 v110, v31, 16, v184
	v_and_or_b32 v111, v31, s40, v185
	v_and_b32_e32 v182, 0xffff, v32
	v_lshrrev_b32_e32 v183, 16, v32
	v_and_b32_e32 v184, 0xffff, v33
	v_lshrrev_b32_e32 v185, 16, v33
	v_lshl_or_b32 v112, v34, 16, v182
	v_and_or_b32 v113, v34, s40, v183
	v_lshl_or_b32 v114, v35, 16, v184
	v_and_or_b32 v115, v35, s40, v185
	v_cmp_eq_u32_e32 vcc, 1, v174
	v_xor_b32_e32 v182, 0x80000000, v117
	v_xor_b32_e32 v183, 0x80000000, v119
	s_nop 1
	v_cndmask_b32_e32 v122, v182, v117, vcc
	v_cndmask_b32_e32 v123, v183, v119, vcc
	ds_write_b128 v162, v[80:83]
	ds_write_b128 v162, v[194:197] offset:512
	v_cndmask_b32_e64 v182, 0, v80, s[66:67]
	v_cndmask_b32_e64 v183, 0, v81, s[66:67]
	v_cndmask_b32_e64 v184, 0, v82, s[66:67]
	v_cndmask_b32_e64 v185, 0, v83, s[66:67]
	v_cndmask_b32_e64 v186, 0, v80, s[68:69]
	v_cndmask_b32_e64 v187, 0, v81, s[68:69]
	v_cndmask_b32_e64 v188, 0, v82, s[68:69]
	v_cndmask_b32_e64 v189, 0, v83, s[68:69]
	v_cndmask_b32_e64 v124, 0, v194, s[66:67]
	v_cndmask_b32_e64 v125, 0, v195, s[66:67]
	v_cndmask_b32_e64 v126, 0, v196, s[66:67]
	v_cndmask_b32_e64 v127, 0, v197, s[66:67]
	v_cndmask_b32_e64 v128, 0, v194, s[68:69]
	v_cndmask_b32_e64 v129, 0, v195, s[68:69]
	v_cndmask_b32_e64 v130, 0, v196, s[68:69]
	v_cndmask_b32_e64 v131, 0, v197, s[68:69]
	v_mfma_f32_32x32x16_bf16 v[16:31], v[182:185], v[84:87], 0
	v_mfma_f32_32x32x16_bf16 v[32:47], v[182:185], v[88:91], 0
	v_mfma_f32_32x32x16_bf16 v[16:31], v[186:189], v[92:95], v[16:31]
	v_mfma_f32_32x32x16_bf16 v[32:47], v[186:189], v[96:99], v[32:47]
	v_mfma_f32_32x32x16_bf16 v[48:63], v[124:127], v[84:87], 0
	v_mfma_f32_32x32x16_bf16 v[64:79], v[124:127], v[88:91], 0
	v_mfma_f32_32x32x16_bf16 v[48:63], v[128:131], v[92:95], v[48:63]
	v_mfma_f32_32x32x16_bf16 v[64:79], v[128:131], v[96:99], v[64:79]
	global_load_dwordx4 v[80:83], v150, s[10:11]
	global_load_dwordx4 v[194:197], v150, s[10:11] offset:512
	s_add_u32 s10, s10, 1024
	s_addc_u32 s11, s11, 0
	s_nop 7
.Lssm_tileA_d0m0:
	v_fmac_f32_e32 v16, v116, v120
	v_fmac_f32_e32 v32, v118, v121
	v_fmac_f32_dpp v16, v120, v122 quad_perm:[1,0,3,2] row_mask:0xf bank_mask:0xf
	v_fmac_f32_dpp v32, v121, v123 quad_perm:[1,0,3,2] row_mask:0xf bank_mask:0xf
	v_cvt_pk_bf16_f32 v148, v16, v32
	ds_write_b32 v151, v148
	v_fmac_f32_e32 v17, v116, v16
	v_fmac_f32_e32 v33, v118, v32
	v_fmac_f32_dpp v17, v16, v122 quad_perm:[1,0,3,2] row_mask:0xf bank_mask:0xf
	v_fmac_f32_dpp v33, v32, v123 quad_perm:[1,0,3,2] row_mask:0xf bank_mask:0xf
	v_cvt_pk_bf16_f32 v149, v17, v33
	ds_write_b32 v151, v149 offset:272
	v_fmac_f32_e32 v18, v116, v17
	v_fmac_f32_e32 v34, v118, v33
	v_fmac_f32_dpp v18, v17, v122 quad_perm:[1,0,3,2] row_mask:0xf bank_mask:0xf
	v_fmac_f32_dpp v34, v33, v123 quad_perm:[1,0,3,2] row_mask:0xf bank_mask:0xf
	v_cvt_pk_bf16_f32 v148, v18, v34
	ds_write_b32 v151, v148 offset:544
	v_fmac_f32_e32 v19, v116, v18
	v_fmac_f32_e32 v35, v118, v34
	v_fmac_f32_dpp v19, v18, v122 quad_perm:[1,0,3,2] row_mask:0xf bank_mask:0xf
	v_fmac_f32_dpp v35, v34, v123 quad_perm:[1,0,3,2] row_mask:0xf bank_mask:0xf
	v_cvt_pk_bf16_f32 v149, v19, v35
	ds_write_b32 v151, v149 offset:816
	v_fmac_f32_e32 v20, v116, v19
	v_fmac_f32_e32 v36, v118, v35
	v_fmac_f32_dpp v20, v19, v122 quad_perm:[1,0,3,2] row_mask:0xf bank_mask:0xf
	v_fmac_f32_dpp v36, v35, v123 quad_perm:[1,0,3,2] row_mask:0xf bank_mask:0xf
	v_cvt_pk_bf16_f32 v148, v20, v36
	ds_write_b32 v151, v148 offset:1088
	v_fmac_f32_e32 v21, v116, v20
	v_fmac_f32_e32 v37, v118, v36
	v_fmac_f32_dpp v21, v20, v122 quad_perm:[1,0,3,2] row_mask:0xf bank_mask:0xf
	v_fmac_f32_dpp v37, v36, v123 quad_perm:[1,0,3,2] row_mask:0xf bank_mask:0xf
	v_cvt_pk_bf16_f32 v149, v21, v37
	ds_write_b32 v151, v149 offset:1360
	v_fmac_f32_e32 v22, v116, v21
	v_fmac_f32_e32 v38, v118, v37
	v_fmac_f32_dpp v22, v21, v122 quad_perm:[1,0,3,2] row_mask:0xf bank_mask:0xf
	v_fmac_f32_dpp v38, v37, v123 quad_perm:[1,0,3,2] row_mask:0xf bank_mask:0xf
	v_cvt_pk_bf16_f32 v148, v22, v38
	ds_write_b32 v151, v148 offset:1632
	v_fmac_f32_e32 v23, v116, v22
	v_fmac_f32_e32 v39, v118, v38
	v_fmac_f32_dpp v23, v22, v122 quad_perm:[1,0,3,2] row_mask:0xf bank_mask:0xf
	v_fmac_f32_dpp v39, v38, v123 quad_perm:[1,0,3,2] row_mask:0xf bank_mask:0xf
	v_cvt_pk_bf16_f32 v149, v23, v39
	ds_write_b32 v151, v149 offset:1904
	v_fmac_f32_e32 v24, v116, v23
	v_fmac_f32_e32 v40, v118, v39
	v_fmac_f32_dpp v24, v23, v122 quad_perm:[1,0,3,2] row_mask:0xf bank_mask:0xf
	v_fmac_f32_dpp v40, v39, v123 quad_perm:[1,0,3,2] row_mask:0xf bank_mask:0xf
	v_cvt_pk_bf16_f32 v148, v24, v40
	ds_write_b32 v151, v148 offset:2176
	v_fmac_f32_e32 v25, v116, v24
	v_fmac_f32_e32 v41, v118, v40
	v_fmac_f32_dpp v25, v24, v122 quad_perm:[1,0,3,2] row_mask:0xf bank_mask:0xf
	v_fmac_f32_dpp v41, v40, v123 quad_perm:[1,0,3,2] row_mask:0xf bank_mask:0xf
	v_cvt_pk_bf16_f32 v149, v25, v41
	ds_write_b32 v151, v149 offset:2448
	v_fmac_f32_e32 v26, v116, v25
	v_fmac_f32_e32 v42, v118, v41
	v_fmac_f32_dpp v26, v25, v122 quad_perm:[1,0,3,2] row_mask:0xf bank_mask:0xf
	v_fmac_f32_dpp v42, v41, v123 quad_perm:[1,0,3,2] row_mask:0xf bank_mask:0xf
	v_cvt_pk_bf16_f32 v148, v26, v42
	ds_write_b32 v151, v148 offset:2720
	v_fmac_f32_e32 v27, v116, v26
	v_fmac_f32_e32 v43, v118, v42
	v_fmac_f32_dpp v27, v26, v122 quad_perm:[1,0,3,2] row_mask:0xf bank_mask:0xf
	v_fmac_f32_dpp v43, v42, v123 quad_perm:[1,0,3,2] row_mask:0xf bank_mask:0xf
	v_cvt_pk_bf16_f32 v149, v27, v43
	ds_write_b32 v151, v149 offset:2992
	v_fmac_f32_e32 v28, v116, v27
	v_fmac_f32_e32 v44, v118, v43
	v_fmac_f32_dpp v28, v27, v122 quad_perm:[1,0,3,2] row_mask:0xf bank_mask:0xf
	v_fmac_f32_dpp v44, v43, v123 quad_perm:[1,0,3,2] row_mask:0xf bank_mask:0xf
	v_cvt_pk_bf16_f32 v148, v28, v44
	ds_write_b32 v151, v148 offset:3264
	v_fmac_f32_e32 v29, v116, v28
	v_fmac_f32_e32 v45, v118, v44
	v_fmac_f32_dpp v29, v28, v122 quad_perm:[1,0,3,2] row_mask:0xf bank_mask:0xf
	v_fmac_f32_dpp v45, v44, v123 quad_perm:[1,0,3,2] row_mask:0xf bank_mask:0xf
	v_cvt_pk_bf16_f32 v149, v29, v45
	ds_write_b32 v151, v149 offset:3536
	v_fmac_f32_e32 v30, v116, v29
	v_fmac_f32_e32 v46, v118, v45
	v_fmac_f32_dpp v30, v29, v122 quad_perm:[1,0,3,2] row_mask:0xf bank_mask:0xf
	v_fmac_f32_dpp v46, v45, v123 quad_perm:[1,0,3,2] row_mask:0xf bank_mask:0xf
	v_cvt_pk_bf16_f32 v148, v30, v46
	ds_write_b32 v151, v148 offset:3808
	v_fmac_f32_e32 v31, v116, v30
	v_fmac_f32_e32 v47, v118, v46
	v_fmac_f32_dpp v31, v30, v122 quad_perm:[1,0,3,2] row_mask:0xf bank_mask:0xf
	v_fmac_f32_dpp v47, v46, v123 quad_perm:[1,0,3,2] row_mask:0xf bank_mask:0xf
	v_cvt_pk_bf16_f32 v149, v31, v47
	ds_write_b32 v151, v149 offset:4080
	s_waitcnt vmcnt(5)
	ds_write_b128 v162, v[144:147] offset:1024
	v_cndmask_b32_e64 v182, 0, v144, s[66:67]
	v_cndmask_b32_e64 v183, 0, v145, s[66:67]
	v_cndmask_b32_e64 v184, 0, v146, s[66:67]
	v_cndmask_b32_e64 v185, 0, v147, s[66:67]
	v_cndmask_b32_e64 v186, 0, v144, s[68:69]
	v_cndmask_b32_e64 v187, 0, v145, s[68:69]
	v_cndmask_b32_e64 v188, 0, v146, s[68:69]
	v_cndmask_b32_e64 v189, 0, v147, s[68:69]
	global_load_dwordx4 v[144:147], v150, s[10:11]
	v_fmac_f32_e32 v48, v116, v31
	v_fmac_f32_e32 v64, v118, v47
	v_fmac_f32_dpp v48, v31, v122 quad_perm:[1,0,3,2] row_mask:0xf bank_mask:0xf
	v_fmac_f32_dpp v64, v47, v123 quad_perm:[1,0,3,2] row_mask:0xf bank_mask:0xf
	v_cvt_pk_bf16_f32 v148, v48, v64
	ds_write_b32 v151, v148 offset:4352
	v_fmac_f32_e32 v49, v116, v48
	v_fmac_f32_e32 v65, v118, v64
	v_fmac_f32_dpp v49, v48, v122 quad_perm:[1,0,3,2] row_mask:0xf bank_mask:0xf
	v_fmac_f32_dpp v65, v64, v123 quad_perm:[1,0,3,2] row_mask:0xf bank_mask:0xf
	v_cvt_pk_bf16_f32 v149, v49, v65
	ds_write_b32 v151, v149 offset:4624
	v_mfma_f32_32x32x16_bf16 v[16:31], v[182:185], v[84:87], 0
	v_fmac_f32_e32 v50, v116, v49
	v_fmac_f32_e32 v66, v118, v65
	v_fmac_f32_dpp v50, v49, v122 quad_perm:[1,0,3,2] row_mask:0xf bank_mask:0xf
	v_fmac_f32_dpp v66, v65, v123 quad_perm:[1,0,3,2] row_mask:0xf bank_mask:0xf
	v_cvt_pk_bf16_f32 v148, v50, v66
	ds_write_b32 v151, v148 offset:4896
	v_fmac_f32_e32 v51, v116, v50
	v_fmac_f32_e32 v67, v118, v66
	v_fmac_f32_dpp v51, v50, v122 quad_perm:[1,0,3,2] row_mask:0xf bank_mask:0xf
	v_fmac_f32_dpp v67, v66, v123 quad_perm:[1,0,3,2] row_mask:0xf bank_mask:0xf
	v_cvt_pk_bf16_f32 v149, v51, v67
	ds_write_b32 v151, v149 offset:5168
	v_mfma_f32_32x32x16_bf16 v[32:47], v[182:185], v[88:91], 0
	v_fmac_f32_e32 v52, v116, v51
	v_fmac_f32_e32 v68, v118, v67
	v_fmac_f32_dpp v52, v51, v122 quad_perm:[1,0,3,2] row_mask:0xf bank_mask:0xf
	v_fmac_f32_dpp v68, v67, v123 quad_perm:[1,0,3,2] row_mask:0xf bank_mask:0xf
	v_cvt_pk_bf16_f32 v148, v52, v68
	ds_write_b32 v151, v148 offset:5440
	v_fmac_f32_e32 v53, v116, v52
	v_fmac_f32_e32 v69, v118, v68
	v_fmac_f32_dpp v53, v52, v122 quad_perm:[1,0,3,2] row_mask:0xf bank_mask:0xf
	v_fmac_f32_dpp v69, v68, v123 quad_perm:[1,0,3,2] row_mask:0xf bank_mask:0xf
	v_cvt_pk_bf16_f32 v149, v53, v69
	ds_write_b32 v151, v149 offset:5712
	v_mfma_f32_32x32x16_bf16 v[16:31], v[186:189], v[92:95], v[16:31]
	v_fmac_f32_e32 v54, v116, v53
	v_fmac_f32_e32 v70, v118, v69
	v_fmac_f32_dpp v54, v53, v122 quad_perm:[1,0,3,2] row_mask:0xf bank_mask:0xf
	v_fmac_f32_dpp v70, v69, v123 quad_perm:[1,0,3,2] row_mask:0xf bank_mask:0xf
	v_cvt_pk_bf16_f32 v148, v54, v70
	ds_write_b32 v151, v148 offset:5984
	v_fmac_f32_e32 v55, v116, v54
	v_fmac_f32_e32 v71, v118, v70
	v_fmac_f32_dpp v55, v54, v122 quad_perm:[1,0,3,2] row_mask:0xf bank_mask:0xf
	v_fmac_f32_dpp v71, v70, v123 quad_perm:[1,0,3,2] row_mask:0xf bank_mask:0xf
	v_cvt_pk_bf16_f32 v149, v55, v71
	ds_write_b32 v151, v149 offset:6256
	v_mfma_f32_32x32x16_bf16 v[32:47], v[186:189], v[96:99], v[32:47]
	v_fmac_f32_e32 v56, v116, v55
	v_fmac_f32_e32 v72, v118, v71
	v_fmac_f32_dpp v56, v55, v122 quad_perm:[1,0,3,2] row_mask:0xf bank_mask:0xf
	v_fmac_f32_dpp v72, v71, v123 quad_perm:[1,0,3,2] row_mask:0xf bank_mask:0xf
	v_cvt_pk_bf16_f32 v148, v56, v72
	ds_write_b32 v151, v148 offset:6528
	v_fmac_f32_e32 v57, v116, v56
	v_fmac_f32_e32 v73, v118, v72
	v_fmac_f32_dpp v57, v56, v122 quad_perm:[1,0,3,2] row_mask:0xf bank_mask:0xf
	v_fmac_f32_dpp v73, v72, v123 quad_perm:[1,0,3,2] row_mask:0xf bank_mask:0xf
	v_cvt_pk_bf16_f32 v149, v57, v73
	ds_write_b32 v151, v149 offset:6800
	v_fmac_f32_e32 v58, v116, v57
	v_fmac_f32_e32 v74, v118, v73
	v_fmac_f32_dpp v58, v57, v122 quad_perm:[1,0,3,2] row_mask:0xf bank_mask:0xf
	v_fmac_f32_dpp v74, v73, v123 quad_perm:[1,0,3,2] row_mask:0xf bank_mask:0xf
	v_cvt_pk_bf16_f32 v148, v58, v74
	ds_write_b32 v151, v148 offset:7072
	v_fmac_f32_e32 v59, v116, v58
	v_fmac_f32_e32 v75, v118, v74
	v_fmac_f32_dpp v59, v58, v122 quad_perm:[1,0,3,2] row_mask:0xf bank_mask:0xf
	v_fmac_f32_dpp v75, v74, v123 quad_perm:[1,0,3,2] row_mask:0xf bank_mask:0xf
	v_cvt_pk_bf16_f32 v149, v59, v75
	ds_write_b32 v151, v149 offset:7344
	v_fmac_f32_e32 v60, v116, v59
	v_fmac_f32_e32 v76, v118, v75
	v_fmac_f32_dpp v60, v59, v122 quad_perm:[1,0,3,2] row_mask:0xf bank_mask:0xf
	v_fmac_f32_dpp v76, v75, v123 quad_perm:[1,0,3,2] row_mask:0xf bank_mask:0xf
	v_cvt_pk_bf16_f32 v148, v60, v76
	ds_write_b32 v151, v148 offset:7616
	v_fmac_f32_e32 v61, v116, v60
	v_fmac_f32_e32 v77, v118, v76
	v_fmac_f32_dpp v61, v60, v122 quad_perm:[1,0,3,2] row_mask:0xf bank_mask:0xf
	v_fmac_f32_dpp v77, v76, v123 quad_perm:[1,0,3,2] row_mask:0xf bank_mask:0xf
	v_cvt_pk_bf16_f32 v149, v61, v77
	ds_write_b32 v151, v149 offset:7888
	v_fmac_f32_e32 v62, v116, v61
	v_fmac_f32_e32 v78, v118, v77
	v_fmac_f32_dpp v62, v61, v122 quad_perm:[1,0,3,2] row_mask:0xf bank_mask:0xf
	v_fmac_f32_dpp v78, v77, v123 quad_perm:[1,0,3,2] row_mask:0xf bank_mask:0xf
	v_cvt_pk_bf16_f32 v148, v62, v78
	ds_write_b32 v151, v148 offset:8160
	v_fmac_f32_e32 v63, v116, v62
	v_fmac_f32_e32 v79, v118, v78
	v_fmac_f32_dpp v63, v62, v122 quad_perm:[1,0,3,2] row_mask:0xf bank_mask:0xf
	v_fmac_f32_dpp v79, v78, v123 quad_perm:[1,0,3,2] row_mask:0xf bank_mask:0xf
	v_cvt_pk_bf16_f32 v149, v63, v79
	ds_write_b32 v151, v149 offset:8432
	v_mov_b32_e32 v120, v63
	v_mov_b32_e32 v121, v79
	s_waitcnt vmcnt(5)
	ds_write_b128 v162, v[168:171] offset:1536
	v_cndmask_b32_e64 v182, 0, v168, s[66:67]
	v_cndmask_b32_e64 v183, 0, v169, s[66:67]
	v_cndmask_b32_e64 v184, 0, v170, s[66:67]
	v_cndmask_b32_e64 v185, 0, v171, s[66:67]
	v_cndmask_b32_e64 v186, 0, v168, s[68:69]
	v_cndmask_b32_e64 v187, 0, v169, s[68:69]
	v_cndmask_b32_e64 v188, 0, v170, s[68:69]
	v_cndmask_b32_e64 v189, 0, v171, s[68:69]
	global_load_dwordx4 v[168:171], v150, s[10:11] offset:512
	s_add_u32 s29, s14, 4
	s_cmp_lt_u32 s29, 32
	s_cselect_b32 s29, 1024, 0
	s_add_u32 s10, s10, s29
	s_addc_u32 s11, s11, 0
	ds_read_b128 v[124:127], v152
	ds_read_b128 v[128:131], v152 offset:64
	ds_read_b128 v[132:135], v152 offset:128
	ds_read_b128 v[136:139], v152 offset:192
	v_mfma_f32_32x32x16_bf16 v[48:63], v[182:185], v[84:87], 0
	v_mfma_f32_32x32x16_bf16 v[64:79], v[182:185], v[88:91], 0
	v_mfma_f32_32x32x16_bf16 v[48:63], v[186:189], v[92:95], v[48:63]
	v_mfma_f32_32x32x16_bf16 v[64:79], v[186:189], v[96:99], v[64:79]
	s_waitcnt lgkmcnt(3)
	v_mfma_f32_16x16x32_bf16 v[140:143], v[100:103], v[124:127], 0
	s_waitcnt lgkmcnt(2)
	v_mfma_f32_16x16x32_bf16 v[140:143], v[104:107], v[128:131], v[140:143]
	s_waitcnt lgkmcnt(1)
	v_mfma_f32_16x16x32_bf16 v[140:143], v[108:111], v[132:135], v[140:143]
	s_waitcnt lgkmcnt(0)
	v_mfma_f32_16x16x32_bf16 v[140:143], v[112:115], v[136:139], v[140:143]
	s_nop 9
	global_store_dwordx4 v153, v[140:143], s[12:13]
	s_nop 1
	ds_read_b128 v[124:127], v152 offset:4352
	ds_read_b128 v[128:131], v152 offset:4416
	ds_read_b128 v[132:135], v152 offset:4480
	ds_read_b128 v[136:139], v152 offset:4544
	s_waitcnt lgkmcnt(3)
	v_mfma_f32_16x16x32_bf16 v[140:143], v[100:103], v[124:127], 0
	s_waitcnt lgkmcnt(2)
	v_mfma_f32_16x16x32_bf16 v[140:143], v[104:107], v[128:131], v[140:143]
	s_waitcnt lgkmcnt(1)
	v_mfma_f32_16x16x32_bf16 v[140:143], v[108:111], v[132:135], v[140:143]
	s_waitcnt lgkmcnt(0)
	v_mfma_f32_16x16x32_bf16 v[140:143], v[112:115], v[136:139], v[140:143]
	s_nop 9
	global_store_dwordx4 v157, v[140:143], s[12:13]
	s_nop 1
	s_add_u32 s12, s12, 2048
	s_addc_u32 s13, s13, 0
	v_fmac_f32_e32 v16, v116, v120
	v_fmac_f32_e32 v32, v118, v121
	v_fmac_f32_dpp v16, v120, v122 quad_perm:[1,0,3,2] row_mask:0xf bank_mask:0xf
	v_fmac_f32_dpp v32, v121, v123 quad_perm:[1,0,3,2] row_mask:0xf bank_mask:0xf
	v_cvt_pk_bf16_f32 v148, v16, v32
	ds_write_b32 v151, v148
	v_fmac_f32_e32 v17, v116, v16
	v_fmac_f32_e32 v33, v118, v32
	v_fmac_f32_dpp v17, v16, v122 quad_perm:[1,0,3,2] row_mask:0xf bank_mask:0xf
	v_fmac_f32_dpp v33, v32, v123 quad_perm:[1,0,3,2] row_mask:0xf bank_mask:0xf
	v_cvt_pk_bf16_f32 v149, v17, v33
	ds_write_b32 v151, v149 offset:272
	v_fmac_f32_e32 v18, v116, v17
	v_fmac_f32_e32 v34, v118, v33
	v_fmac_f32_dpp v18, v17, v122 quad_perm:[1,0,3,2] row_mask:0xf bank_mask:0xf
	v_fmac_f32_dpp v34, v33, v123 quad_perm:[1,0,3,2] row_mask:0xf bank_mask:0xf
	v_cvt_pk_bf16_f32 v148, v18, v34
	ds_write_b32 v151, v148 offset:544
	v_fmac_f32_e32 v19, v116, v18
	v_fmac_f32_e32 v35, v118, v34
	v_fmac_f32_dpp v19, v18, v122 quad_perm:[1,0,3,2] row_mask:0xf bank_mask:0xf
	v_fmac_f32_dpp v35, v34, v123 quad_perm:[1,0,3,2] row_mask:0xf bank_mask:0xf
	v_cvt_pk_bf16_f32 v149, v19, v35
	ds_write_b32 v151, v149 offset:816
	v_fmac_f32_e32 v20, v116, v19
	v_fmac_f32_e32 v36, v118, v35
	v_fmac_f32_dpp v20, v19, v122 quad_perm:[1,0,3,2] row_mask:0xf bank_mask:0xf
	v_fmac_f32_dpp v36, v35, v123 quad_perm:[1,0,3,2] row_mask:0xf bank_mask:0xf
	v_cvt_pk_bf16_f32 v148, v20, v36
	ds_write_b32 v151, v148 offset:1088
	v_fmac_f32_e32 v21, v116, v20
	v_fmac_f32_e32 v37, v118, v36
	v_fmac_f32_dpp v21, v20, v122 quad_perm:[1,0,3,2] row_mask:0xf bank_mask:0xf
	v_fmac_f32_dpp v37, v36, v123 quad_perm:[1,0,3,2] row_mask:0xf bank_mask:0xf
	v_cvt_pk_bf16_f32 v149, v21, v37
	ds_write_b32 v151, v149 offset:1360
	v_fmac_f32_e32 v22, v116, v21
	v_fmac_f32_e32 v38, v118, v37
	v_fmac_f32_dpp v22, v21, v122 quad_perm:[1,0,3,2] row_mask:0xf bank_mask:0xf
	v_fmac_f32_dpp v38, v37, v123 quad_perm:[1,0,3,2] row_mask:0xf bank_mask:0xf
	v_cvt_pk_bf16_f32 v148, v22, v38
	ds_write_b32 v151, v148 offset:1632
	v_fmac_f32_e32 v23, v116, v22
	v_fmac_f32_e32 v39, v118, v38
	v_fmac_f32_dpp v23, v22, v122 quad_perm:[1,0,3,2] row_mask:0xf bank_mask:0xf
	v_fmac_f32_dpp v39, v38, v123 quad_perm:[1,0,3,2] row_mask:0xf bank_mask:0xf
	v_cvt_pk_bf16_f32 v149, v23, v39
	ds_write_b32 v151, v149 offset:1904
	v_fmac_f32_e32 v24, v116, v23
	v_fmac_f32_e32 v40, v118, v39
	v_fmac_f32_dpp v24, v23, v122 quad_perm:[1,0,3,2] row_mask:0xf bank_mask:0xf
	v_fmac_f32_dpp v40, v39, v123 quad_perm:[1,0,3,2] row_mask:0xf bank_mask:0xf
	v_cvt_pk_bf16_f32 v148, v24, v40
	ds_write_b32 v151, v148 offset:2176
	v_fmac_f32_e32 v25, v116, v24
	v_fmac_f32_e32 v41, v118, v40
	v_fmac_f32_dpp v25, v24, v122 quad_perm:[1,0,3,2] row_mask:0xf bank_mask:0xf
	v_fmac_f32_dpp v41, v40, v123 quad_perm:[1,0,3,2] row_mask:0xf bank_mask:0xf
	v_cvt_pk_bf16_f32 v149, v25, v41
	ds_write_b32 v151, v149 offset:2448
	v_fmac_f32_e32 v26, v116, v25
	v_fmac_f32_e32 v42, v118, v41
	v_fmac_f32_dpp v26, v25, v122 quad_perm:[1,0,3,2] row_mask:0xf bank_mask:0xf
	v_fmac_f32_dpp v42, v41, v123 quad_perm:[1,0,3,2] row_mask:0xf bank_mask:0xf
	v_cvt_pk_bf16_f32 v148, v26, v42
	ds_write_b32 v151, v148 offset:2720
	v_fmac_f32_e32 v27, v116, v26
	v_fmac_f32_e32 v43, v118, v42
	v_fmac_f32_dpp v27, v26, v122 quad_perm:[1,0,3,2] row_mask:0xf bank_mask:0xf
	v_fmac_f32_dpp v43, v42, v123 quad_perm:[1,0,3,2] row_mask:0xf bank_mask:0xf
	v_cvt_pk_bf16_f32 v149, v27, v43
	ds_write_b32 v151, v149 offset:2992
	v_fmac_f32_e32 v28, v116, v27
	v_fmac_f32_e32 v44, v118, v43
	v_fmac_f32_dpp v28, v27, v122 quad_perm:[1,0,3,2] row_mask:0xf bank_mask:0xf
	v_fmac_f32_dpp v44, v43, v123 quad_perm:[1,0,3,2] row_mask:0xf bank_mask:0xf
	v_cvt_pk_bf16_f32 v148, v28, v44
	ds_write_b32 v151, v148 offset:3264
	v_fmac_f32_e32 v29, v116, v28
	v_fmac_f32_e32 v45, v118, v44
	v_fmac_f32_dpp v29, v28, v122 quad_perm:[1,0,3,2] row_mask:0xf bank_mask:0xf
	v_fmac_f32_dpp v45, v44, v123 quad_perm:[1,0,3,2] row_mask:0xf bank_mask:0xf
	v_cvt_pk_bf16_f32 v149, v29, v45
	ds_write_b32 v151, v149 offset:3536
	v_fmac_f32_e32 v30, v116, v29
	v_fmac_f32_e32 v46, v118, v45
	v_fmac_f32_dpp v30, v29, v122 quad_perm:[1,0,3,2] row_mask:0xf bank_mask:0xf
	v_fmac_f32_dpp v46, v45, v123 quad_perm:[1,0,3,2] row_mask:0xf bank_mask:0xf
	v_cvt_pk_bf16_f32 v148, v30, v46
	ds_write_b32 v151, v148 offset:3808
	v_fmac_f32_e32 v31, v116, v30
	v_fmac_f32_e32 v47, v118, v46
	v_fmac_f32_dpp v31, v30, v122 quad_perm:[1,0,3,2] row_mask:0xf bank_mask:0xf
	v_fmac_f32_dpp v47, v46, v123 quad_perm:[1,0,3,2] row_mask:0xf bank_mask:0xf
	v_cvt_pk_bf16_f32 v149, v31, v47
	ds_write_b32 v151, v149 offset:4080
	s_waitcnt vmcnt(5)
	ds_write_b128 v162, v[80:83]
	v_cndmask_b32_e64 v182, 0, v80, s[66:67]
	v_cndmask_b32_e64 v183, 0, v81, s[66:67]
	v_cndmask_b32_e64 v184, 0, v82, s[66:67]
	v_cndmask_b32_e64 v185, 0, v83, s[66:67]
	v_cndmask_b32_e64 v186, 0, v80, s[68:69]
	v_cndmask_b32_e64 v187, 0, v81, s[68:69]
	v_cndmask_b32_e64 v188, 0, v82, s[68:69]
	v_cndmask_b32_e64 v189, 0, v83, s[68:69]
	global_load_dwordx4 v[80:83], v150, s[10:11]
	v_fmac_f32_e32 v48, v116, v31
	v_fmac_f32_e32 v64, v118, v47
	v_fmac_f32_dpp v48, v31, v122 quad_perm:[1,0,3,2] row_mask:0xf bank_mask:0xf
	v_fmac_f32_dpp v64, v47, v123 quad_perm:[1,0,3,2] row_mask:0xf bank_mask:0xf
	v_cvt_pk_bf16_f32 v148, v48, v64
	ds_write_b32 v151, v148 offset:4352
	v_fmac_f32_e32 v49, v116, v48
	v_fmac_f32_e32 v65, v118, v64
	v_fmac_f32_dpp v49, v48, v122 quad_perm:[1,0,3,2] row_mask:0xf bank_mask:0xf
	v_fmac_f32_dpp v65, v64, v123 quad_perm:[1,0,3,2] row_mask:0xf bank_mask:0xf
	v_cvt_pk_bf16_f32 v149, v49, v65
	ds_write_b32 v151, v149 offset:4624
	v_mfma_f32_32x32x16_bf16 v[16:31], v[182:185], v[84:87], 0
	v_fmac_f32_e32 v50, v116, v49
	v_fmac_f32_e32 v66, v118, v65
	v_fmac_f32_dpp v50, v49, v122 quad_perm:[1,0,3,2] row_mask:0xf bank_mask:0xf
	v_fmac_f32_dpp v66, v65, v123 quad_perm:[1,0,3,2] row_mask:0xf bank_mask:0xf
	v_cvt_pk_bf16_f32 v148, v50, v66
	ds_write_b32 v151, v148 offset:4896
	v_fmac_f32_e32 v51, v116, v50
	v_fmac_f32_e32 v67, v118, v66
	v_fmac_f32_dpp v51, v50, v122 quad_perm:[1,0,3,2] row_mask:0xf bank_mask:0xf
	v_fmac_f32_dpp v67, v66, v123 quad_perm:[1,0,3,2] row_mask:0xf bank_mask:0xf
	v_cvt_pk_bf16_f32 v149, v51, v67
	ds_write_b32 v151, v149 offset:5168
	v_mfma_f32_32x32x16_bf16 v[32:47], v[182:185], v[88:91], 0
	v_fmac_f32_e32 v52, v116, v51
	v_fmac_f32_e32 v68, v118, v67
	v_fmac_f32_dpp v52, v51, v122 quad_perm:[1,0,3,2] row_mask:0xf bank_mask:0xf
	v_fmac_f32_dpp v68, v67, v123 quad_perm:[1,0,3,2] row_mask:0xf bank_mask:0xf
	v_cvt_pk_bf16_f32 v148, v52, v68
	ds_write_b32 v151, v148 offset:5440
	v_fmac_f32_e32 v53, v116, v52
	v_fmac_f32_e32 v69, v118, v68
	v_fmac_f32_dpp v53, v52, v122 quad_perm:[1,0,3,2] row_mask:0xf bank_mask:0xf
	v_fmac_f32_dpp v69, v68, v123 quad_perm:[1,0,3,2] row_mask:0xf bank_mask:0xf
	v_cvt_pk_bf16_f32 v149, v53, v69
	ds_write_b32 v151, v149 offset:5712
	v_mfma_f32_32x32x16_bf16 v[16:31], v[186:189], v[92:95], v[16:31]
	v_fmac_f32_e32 v54, v116, v53
	v_fmac_f32_e32 v70, v118, v69
	v_fmac_f32_dpp v54, v53, v122 quad_perm:[1,0,3,2] row_mask:0xf bank_mask:0xf
	v_fmac_f32_dpp v70, v69, v123 quad_perm:[1,0,3,2] row_mask:0xf bank_mask:0xf
	v_cvt_pk_bf16_f32 v148, v54, v70
	ds_write_b32 v151, v148 offset:5984
	v_fmac_f32_e32 v55, v116, v54
	v_fmac_f32_e32 v71, v118, v70
	v_fmac_f32_dpp v55, v54, v122 quad_perm:[1,0,3,2] row_mask:0xf bank_mask:0xf
	v_fmac_f32_dpp v71, v70, v123 quad_perm:[1,0,3,2] row_mask:0xf bank_mask:0xf
	v_cvt_pk_bf16_f32 v149, v55, v71
	ds_write_b32 v151, v149 offset:6256
	v_mfma_f32_32x32x16_bf16 v[32:47], v[186:189], v[96:99], v[32:47]
	v_fmac_f32_e32 v56, v116, v55
	v_fmac_f32_e32 v72, v118, v71
	v_fmac_f32_dpp v56, v55, v122 quad_perm:[1,0,3,2] row_mask:0xf bank_mask:0xf
	v_fmac_f32_dpp v72, v71, v123 quad_perm:[1,0,3,2] row_mask:0xf bank_mask:0xf
	v_cvt_pk_bf16_f32 v148, v56, v72
	ds_write_b32 v151, v148 offset:6528
	v_fmac_f32_e32 v57, v116, v56
	v_fmac_f32_e32 v73, v118, v72
	v_fmac_f32_dpp v57, v56, v122 quad_perm:[1,0,3,2] row_mask:0xf bank_mask:0xf
	v_fmac_f32_dpp v73, v72, v123 quad_perm:[1,0,3,2] row_mask:0xf bank_mask:0xf
	v_cvt_pk_bf16_f32 v149, v57, v73
	ds_write_b32 v151, v149 offset:6800
	v_fmac_f32_e32 v58, v116, v57
	v_fmac_f32_e32 v74, v118, v73
	v_fmac_f32_dpp v58, v57, v122 quad_perm:[1,0,3,2] row_mask:0xf bank_mask:0xf
	v_fmac_f32_dpp v74, v73, v123 quad_perm:[1,0,3,2] row_mask:0xf bank_mask:0xf
	v_cvt_pk_bf16_f32 v148, v58, v74
	ds_write_b32 v151, v148 offset:7072
	v_fmac_f32_e32 v59, v116, v58
	v_fmac_f32_e32 v75, v118, v74
	v_fmac_f32_dpp v59, v58, v122 quad_perm:[1,0,3,2] row_mask:0xf bank_mask:0xf
	v_fmac_f32_dpp v75, v74, v123 quad_perm:[1,0,3,2] row_mask:0xf bank_mask:0xf
	v_cvt_pk_bf16_f32 v149, v59, v75
	ds_write_b32 v151, v149 offset:7344
	v_fmac_f32_e32 v60, v116, v59
	v_fmac_f32_e32 v76, v118, v75
	v_fmac_f32_dpp v60, v59, v122 quad_perm:[1,0,3,2] row_mask:0xf bank_mask:0xf
	v_fmac_f32_dpp v76, v75, v123 quad_perm:[1,0,3,2] row_mask:0xf bank_mask:0xf
	v_cvt_pk_bf16_f32 v148, v60, v76
	ds_write_b32 v151, v148 offset:7616
	v_fmac_f32_e32 v61, v116, v60
	v_fmac_f32_e32 v77, v118, v76
	v_fmac_f32_dpp v61, v60, v122 quad_perm:[1,0,3,2] row_mask:0xf bank_mask:0xf
	v_fmac_f32_dpp v77, v76, v123 quad_perm:[1,0,3,2] row_mask:0xf bank_mask:0xf
	v_cvt_pk_bf16_f32 v149, v61, v77
	ds_write_b32 v151, v149 offset:7888
	v_fmac_f32_e32 v62, v116, v61
	v_fmac_f32_e32 v78, v118, v77
	v_fmac_f32_dpp v62, v61, v122 quad_perm:[1,0,3,2] row_mask:0xf bank_mask:0xf
	v_fmac_f32_dpp v78, v77, v123 quad_perm:[1,0,3,2] row_mask:0xf bank_mask:0xf
	v_cvt_pk_bf16_f32 v148, v62, v78
	ds_write_b32 v151, v148 offset:8160
	v_fmac_f32_e32 v63, v116, v62
	v_fmac_f32_e32 v79, v118, v78
	v_fmac_f32_dpp v63, v62, v122 quad_perm:[1,0,3,2] row_mask:0xf bank_mask:0xf
	v_fmac_f32_dpp v79, v78, v123 quad_perm:[1,0,3,2] row_mask:0xf bank_mask:0xf
	v_cvt_pk_bf16_f32 v149, v63, v79
	ds_write_b32 v151, v149 offset:8432
	v_mov_b32_e32 v120, v63
	v_mov_b32_e32 v121, v79
	s_waitcnt vmcnt(5)
	ds_write_b128 v162, v[194:197] offset:512
	v_cndmask_b32_e64 v182, 0, v194, s[66:67]
	v_cndmask_b32_e64 v183, 0, v195, s[66:67]
	v_cndmask_b32_e64 v184, 0, v196, s[66:67]
	v_cndmask_b32_e64 v185, 0, v197, s[66:67]
	v_cndmask_b32_e64 v186, 0, v194, s[68:69]
	v_cndmask_b32_e64 v187, 0, v195, s[68:69]
	v_cndmask_b32_e64 v188, 0, v196, s[68:69]
	v_cndmask_b32_e64 v189, 0, v197, s[68:69]
	global_load_dwordx4 v[194:197], v150, s[10:11] offset:512
	s_add_u32 s29, s14, 5
	s_cmp_lt_u32 s29, 32
	s_cselect_b32 s29, 1024, 0
	s_add_u32 s10, s10, s29
	s_addc_u32 s11, s11, 0
	ds_read_b128 v[124:127], v152
	ds_read_b128 v[128:131], v152 offset:64
	ds_read_b128 v[132:135], v152 offset:128
	ds_read_b128 v[136:139], v152 offset:192
	v_mfma_f32_32x32x16_bf16 v[48:63], v[182:185], v[84:87], 0
	v_mfma_f32_32x32x16_bf16 v[64:79], v[182:185], v[88:91], 0
	v_mfma_f32_32x32x16_bf16 v[48:63], v[186:189], v[92:95], v[48:63]
	v_mfma_f32_32x32x16_bf16 v[64:79], v[186:189], v[96:99], v[64:79]
	s_waitcnt lgkmcnt(3)
	v_mfma_f32_16x16x32_bf16 v[140:143], v[100:103], v[124:127], 0
	s_waitcnt lgkmcnt(2)
	v_mfma_f32_16x16x32_bf16 v[140:143], v[104:107], v[128:131], v[140:143]
	s_waitcnt lgkmcnt(1)
	v_mfma_f32_16x16x32_bf16 v[140:143], v[108:111], v[132:135], v[140:143]
	s_waitcnt lgkmcnt(0)
	v_mfma_f32_16x16x32_bf16 v[140:143], v[112:115], v[136:139], v[140:143]
	s_nop 9
	global_store_dwordx4 v153, v[140:143], s[12:13]
	s_nop 1
	ds_read_b128 v[124:127], v152 offset:4352
	ds_read_b128 v[128:131], v152 offset:4416
	ds_read_b128 v[132:135], v152 offset:4480
	ds_read_b128 v[136:139], v152 offset:4544
	s_waitcnt lgkmcnt(3)
	v_mfma_f32_16x16x32_bf16 v[140:143], v[100:103], v[124:127], 0
	s_waitcnt lgkmcnt(2)
	v_mfma_f32_16x16x32_bf16 v[140:143], v[104:107], v[128:131], v[140:143]
	s_waitcnt lgkmcnt(1)
	v_mfma_f32_16x16x32_bf16 v[140:143], v[108:111], v[132:135], v[140:143]
	s_waitcnt lgkmcnt(0)
	v_mfma_f32_16x16x32_bf16 v[140:143], v[112:115], v[136:139], v[140:143]
	s_nop 9
	global_store_dwordx4 v157, v[140:143], s[12:13]
	s_nop 1
	s_add_u32 s12, s12, 2048
	s_addc_u32 s13, s13, 0
	s_add_u32 s14, s14, 2
	s_cmp_lt_u32 s14, 16
	s_cbranch_scc1 .Lssm_tileA_d0m0
	s_waitcnt vmcnt(0) lgkmcnt(0)
	s_lshr_b32 s21, s89, 1
	s_lshl_b32 s21, s21, 2
	s_add_u32 s37, s21, 0x21000
	v_mov_b32_e32 v182, s37
	v_mov_b32_e32 v183, 1
	v_cmp_eq_u32_e32 vcc, 0, v191
	s_and_saveexec_b64 s[0:1], vcc
	ds_add_u32 v182, v183
	s_mov_b64 exec, s[0:1]
	s_waitcnt lgkmcnt(0)
	s_mov_b32 s38, 0

.Lssm_spin_done_d0m0:
	s_mov_b64 s[42:43], s[6:7]
	s_add_u32 s42, s42, 32768
	s_addc_u32 s43, s43, 0
	s_lshl_b32 s31, s25, 11
	s_lshl_b32 s29, s24, 5
	s_add_u32 s31, s31, s29
	s_add_u32 s31, s31, 344981504
	s_add_u32 s12, s62, s31
	s_addc_u32 s13, s63, 0
	global_load_dwordx4 v[6:9], v153, s[42:43]
	global_load_dwordx4 v[10:13], v157, s[42:43]
	s_add_u32 s42, s42, 2048
	s_addc_u32 s43, s43, 0
	s_waitcnt vmcnt(0)
.Lssm_tileB_d0m0:
	global_load_dwordx4 v[172:175], v153, s[42:43]
	global_load_dwordx4 v[176:179], v157, s[42:43]
	s_add_u32 s42, s42, 2048
	s_addc_u32 s43, s43, 0
	v_fmac_f32_e32 v16, v116, v120
	v_fmac_f32_e32 v32, v118, v121
	v_fmac_f32_dpp v16, v120, v122 quad_perm:[1,0,3,2] row_mask:0xf bank_mask:0xf
	v_fmac_f32_dpp v32, v121, v123 quad_perm:[1,0,3,2] row_mask:0xf bank_mask:0xf
	v_cvt_pk_bf16_f32 v148, v16, v32
	ds_write_b32 v151, v148
	v_fmac_f32_e32 v17, v116, v16
	v_fmac_f32_e32 v33, v118, v32
	v_fmac_f32_dpp v17, v16, v122 quad_perm:[1,0,3,2] row_mask:0xf bank_mask:0xf
	v_fmac_f32_dpp v33, v32, v123 quad_perm:[1,0,3,2] row_mask:0xf bank_mask:0xf
	v_cvt_pk_bf16_f32 v149, v17, v33
	ds_write_b32 v151, v149 offset:272
	v_fmac_f32_e32 v18, v116, v17
	v_fmac_f32_e32 v34, v118, v33
	v_fmac_f32_dpp v18, v17, v122 quad_perm:[1,0,3,2] row_mask:0xf bank_mask:0xf
	v_fmac_f32_dpp v34, v33, v123 quad_perm:[1,0,3,2] row_mask:0xf bank_mask:0xf
	v_cvt_pk_bf16_f32 v148, v18, v34
	ds_write_b32 v151, v148 offset:544
	v_fmac_f32_e32 v19, v116, v18
	v_fmac_f32_e32 v35, v118, v34
	v_fmac_f32_dpp v19, v18, v122 quad_perm:[1,0,3,2] row_mask:0xf bank_mask:0xf
	v_fmac_f32_dpp v35, v34, v123 quad_perm:[1,0,3,2] row_mask:0xf bank_mask:0xf
	v_cvt_pk_bf16_f32 v149, v19, v35
	ds_write_b32 v151, v149 offset:816
	v_fmac_f32_e32 v20, v116, v19
	v_fmac_f32_e32 v36, v118, v35
	v_fmac_f32_dpp v20, v19, v122 quad_perm:[1,0,3,2] row_mask:0xf bank_mask:0xf
	v_fmac_f32_dpp v36, v35, v123 quad_perm:[1,0,3,2] row_mask:0xf bank_mask:0xf
	v_cvt_pk_bf16_f32 v148, v20, v36
	ds_write_b32 v151, v148 offset:1088
	v_fmac_f32_e32 v21, v116, v20
	v_fmac_f32_e32 v37, v118, v36
	v_fmac_f32_dpp v21, v20, v122 quad_perm:[1,0,3,2] row_mask:0xf bank_mask:0xf
	v_fmac_f32_dpp v37, v36, v123 quad_perm:[1,0,3,2] row_mask:0xf bank_mask:0xf
	v_cvt_pk_bf16_f32 v149, v21, v37
	ds_write_b32 v151, v149 offset:1360
	v_fmac_f32_e32 v22, v116, v21
	v_fmac_f32_e32 v38, v118, v37
	v_fmac_f32_dpp v22, v21, v122 quad_perm:[1,0,3,2] row_mask:0xf bank_mask:0xf
	v_fmac_f32_dpp v38, v37, v123 quad_perm:[1,0,3,2] row_mask:0xf bank_mask:0xf
	v_cvt_pk_bf16_f32 v148, v22, v38
	ds_write_b32 v151, v148 offset:1632
	v_fmac_f32_e32 v23, v116, v22
	v_fmac_f32_e32 v39, v118, v38
	v_fmac_f32_dpp v23, v22, v122 quad_perm:[1,0,3,2] row_mask:0xf bank_mask:0xf
	v_fmac_f32_dpp v39, v38, v123 quad_perm:[1,0,3,2] row_mask:0xf bank_mask:0xf
	v_cvt_pk_bf16_f32 v149, v23, v39
	ds_write_b32 v151, v149 offset:1904
	v_fmac_f32_e32 v24, v116, v23
	v_fmac_f32_e32 v40, v118, v39
	v_fmac_f32_dpp v24, v23, v122 quad_perm:[1,0,3,2] row_mask:0xf bank_mask:0xf
	v_fmac_f32_dpp v40, v39, v123 quad_perm:[1,0,3,2] row_mask:0xf bank_mask:0xf
	v_cvt_pk_bf16_f32 v148, v24, v40
	ds_write_b32 v151, v148 offset:2176
	v_fmac_f32_e32 v25, v116, v24
	v_fmac_f32_e32 v41, v118, v40
	v_fmac_f32_dpp v25, v24, v122 quad_perm:[1,0,3,2] row_mask:0xf bank_mask:0xf
	v_fmac_f32_dpp v41, v40, v123 quad_perm:[1,0,3,2] row_mask:0xf bank_mask:0xf
	v_cvt_pk_bf16_f32 v149, v25, v41
	ds_write_b32 v151, v149 offset:2448
	v_fmac_f32_e32 v26, v116, v25
	v_fmac_f32_e32 v42, v118, v41
	v_fmac_f32_dpp v26, v25, v122 quad_perm:[1,0,3,2] row_mask:0xf bank_mask:0xf
	v_fmac_f32_dpp v42, v41, v123 quad_perm:[1,0,3,2] row_mask:0xf bank_mask:0xf
	v_cvt_pk_bf16_f32 v148, v26, v42
	ds_write_b32 v151, v148 offset:2720
	v_fmac_f32_e32 v27, v116, v26
	v_fmac_f32_e32 v43, v118, v42
	v_fmac_f32_dpp v27, v26, v122 quad_perm:[1,0,3,2] row_mask:0xf bank_mask:0xf
	v_fmac_f32_dpp v43, v42, v123 quad_perm:[1,0,3,2] row_mask:0xf bank_mask:0xf
	v_cvt_pk_bf16_f32 v149, v27, v43
	ds_write_b32 v151, v149 offset:2992
	v_fmac_f32_e32 v28, v116, v27
	v_fmac_f32_e32 v44, v118, v43
	v_fmac_f32_dpp v28, v27, v122 quad_perm:[1,0,3,2] row_mask:0xf bank_mask:0xf
	v_fmac_f32_dpp v44, v43, v123 quad_perm:[1,0,3,2] row_mask:0xf bank_mask:0xf
	v_cvt_pk_bf16_f32 v148, v28, v44
	ds_write_b32 v151, v148 offset:3264
	v_fmac_f32_e32 v29, v116, v28
	v_fmac_f32_e32 v45, v118, v44
	v_fmac_f32_dpp v29, v28, v122 quad_perm:[1,0,3,2] row_mask:0xf bank_mask:0xf
	v_fmac_f32_dpp v45, v44, v123 quad_perm:[1,0,3,2] row_mask:0xf bank_mask:0xf
	v_cvt_pk_bf16_f32 v149, v29, v45
	ds_write_b32 v151, v149 offset:3536
	v_fmac_f32_e32 v30, v116, v29
	v_fmac_f32_e32 v46, v118, v45
	v_fmac_f32_dpp v30, v29, v122 quad_perm:[1,0,3,2] row_mask:0xf bank_mask:0xf
	v_fmac_f32_dpp v46, v45, v123 quad_perm:[1,0,3,2] row_mask:0xf bank_mask:0xf
	v_cvt_pk_bf16_f32 v148, v30, v46
	ds_write_b32 v151, v148 offset:3808
	v_fmac_f32_e32 v31, v116, v30
	v_fmac_f32_e32 v47, v118, v46
	v_fmac_f32_dpp v31, v30, v122 quad_perm:[1,0,3,2] row_mask:0xf bank_mask:0xf
	v_fmac_f32_dpp v47, v46, v123 quad_perm:[1,0,3,2] row_mask:0xf bank_mask:0xf
	v_cvt_pk_bf16_f32 v149, v31, v47
	ds_write_b32 v151, v149 offset:4080
	s_waitcnt vmcnt(11)
	ds_write_b128 v162, v[144:147] offset:1024
	v_cndmask_b32_e64 v182, 0, v144, s[66:67]
	v_cndmask_b32_e64 v183, 0, v145, s[66:67]
	v_cndmask_b32_e64 v184, 0, v146, s[66:67]
	v_cndmask_b32_e64 v185, 0, v147, s[66:67]
	v_cndmask_b32_e64 v186, 0, v144, s[68:69]
	v_cndmask_b32_e64 v187, 0, v145, s[68:69]
	v_cndmask_b32_e64 v188, 0, v146, s[68:69]
	v_cndmask_b32_e64 v189, 0, v147, s[68:69]
	global_load_dwordx4 v[144:147], v150, s[10:11]
	v_fmac_f32_e32 v48, v116, v31
	v_fmac_f32_e32 v64, v118, v47
	v_fmac_f32_dpp v48, v31, v122 quad_perm:[1,0,3,2] row_mask:0xf bank_mask:0xf
	v_fmac_f32_dpp v64, v47, v123 quad_perm:[1,0,3,2] row_mask:0xf bank_mask:0xf
	v_cvt_pk_bf16_f32 v148, v48, v64
	ds_write_b32 v151, v148 offset:4352
	v_fmac_f32_e32 v49, v116, v48
	v_fmac_f32_e32 v65, v118, v64
	v_fmac_f32_dpp v49, v48, v122 quad_perm:[1,0,3,2] row_mask:0xf bank_mask:0xf
	v_fmac_f32_dpp v65, v64, v123 quad_perm:[1,0,3,2] row_mask:0xf bank_mask:0xf
	v_cvt_pk_bf16_f32 v149, v49, v65
	ds_write_b32 v151, v149 offset:4624
	v_mfma_f32_32x32x16_bf16 v[16:31], v[182:185], v[84:87], 0
	v_fmac_f32_e32 v50, v116, v49
	v_fmac_f32_e32 v66, v118, v65
	v_fmac_f32_dpp v50, v49, v122 quad_perm:[1,0,3,2] row_mask:0xf bank_mask:0xf
	v_fmac_f32_dpp v66, v65, v123 quad_perm:[1,0,3,2] row_mask:0xf bank_mask:0xf
	v_cvt_pk_bf16_f32 v148, v50, v66
	ds_write_b32 v151, v148 offset:4896
	v_fmac_f32_e32 v51, v116, v50
	v_fmac_f32_e32 v67, v118, v66
	v_fmac_f32_dpp v51, v50, v122 quad_perm:[1,0,3,2] row_mask:0xf bank_mask:0xf
	v_fmac_f32_dpp v67, v66, v123 quad_perm:[1,0,3,2] row_mask:0xf bank_mask:0xf
	v_cvt_pk_bf16_f32 v149, v51, v67
	ds_write_b32 v151, v149 offset:5168
	v_mfma_f32_32x32x16_bf16 v[32:47], v[182:185], v[88:91], 0
	v_fmac_f32_e32 v52, v116, v51
	v_fmac_f32_e32 v68, v118, v67
	v_fmac_f32_dpp v52, v51, v122 quad_perm:[1,0,3,2] row_mask:0xf bank_mask:0xf
	v_fmac_f32_dpp v68, v67, v123 quad_perm:[1,0,3,2] row_mask:0xf bank_mask:0xf
	v_cvt_pk_bf16_f32 v148, v52, v68
	ds_write_b32 v151, v148 offset:5440
	v_fmac_f32_e32 v53, v116, v52
	v_fmac_f32_e32 v69, v118, v68
	v_fmac_f32_dpp v53, v52, v122 quad_perm:[1,0,3,2] row_mask:0xf bank_mask:0xf
	v_fmac_f32_dpp v69, v68, v123 quad_perm:[1,0,3,2] row_mask:0xf bank_mask:0xf
	v_cvt_pk_bf16_f32 v149, v53, v69
	ds_write_b32 v151, v149 offset:5712
	v_mfma_f32_32x32x16_bf16 v[16:31], v[186:189], v[92:95], v[16:31]
	v_fmac_f32_e32 v54, v116, v53
	v_fmac_f32_e32 v70, v118, v69
	v_fmac_f32_dpp v54, v53, v122 quad_perm:[1,0,3,2] row_mask:0xf bank_mask:0xf
	v_fmac_f32_dpp v70, v69, v123 quad_perm:[1,0,3,2] row_mask:0xf bank_mask:0xf
	v_cvt_pk_bf16_f32 v148, v54, v70
	ds_write_b32 v151, v148 offset:5984
	v_fmac_f32_e32 v55, v116, v54
	v_fmac_f32_e32 v71, v118, v70
	v_fmac_f32_dpp v55, v54, v122 quad_perm:[1,0,3,2] row_mask:0xf bank_mask:0xf
	v_fmac_f32_dpp v71, v70, v123 quad_perm:[1,0,3,2] row_mask:0xf bank_mask:0xf
	v_cvt_pk_bf16_f32 v149, v55, v71
	ds_write_b32 v151, v149 offset:6256
	v_mfma_f32_32x32x16_bf16 v[32:47], v[186:189], v[96:99], v[32:47]
	v_fmac_f32_e32 v56, v116, v55
	v_fmac_f32_e32 v72, v118, v71
	v_fmac_f32_dpp v56, v55, v122 quad_perm:[1,0,3,2] row_mask:0xf bank_mask:0xf
	v_fmac_f32_dpp v72, v71, v123 quad_perm:[1,0,3,2] row_mask:0xf bank_mask:0xf
	v_cvt_pk_bf16_f32 v148, v56, v72
	ds_write_b32 v151, v148 offset:6528
	v_fmac_f32_e32 v57, v116, v56
	v_fmac_f32_e32 v73, v118, v72
	v_fmac_f32_dpp v57, v56, v122 quad_perm:[1,0,3,2] row_mask:0xf bank_mask:0xf
	v_fmac_f32_dpp v73, v72, v123 quad_perm:[1,0,3,2] row_mask:0xf bank_mask:0xf
	v_cvt_pk_bf16_f32 v149, v57, v73
	ds_write_b32 v151, v149 offset:6800
	v_fmac_f32_e32 v58, v116, v57
	v_fmac_f32_e32 v74, v118, v73
	v_fmac_f32_dpp v58, v57, v122 quad_perm:[1,0,3,2] row_mask:0xf bank_mask:0xf
	v_fmac_f32_dpp v74, v73, v123 quad_perm:[1,0,3,2] row_mask:0xf bank_mask:0xf
	v_cvt_pk_bf16_f32 v148, v58, v74
	ds_write_b32 v151, v148 offset:7072
	v_fmac_f32_e32 v59, v116, v58
	v_fmac_f32_e32 v75, v118, v74
	v_fmac_f32_dpp v59, v58, v122 quad_perm:[1,0,3,2] row_mask:0xf bank_mask:0xf
	v_fmac_f32_dpp v75, v74, v123 quad_perm:[1,0,3,2] row_mask:0xf bank_mask:0xf
	v_cvt_pk_bf16_f32 v149, v59, v75
	ds_write_b32 v151, v149 offset:7344
	v_fmac_f32_e32 v60, v116, v59
	v_fmac_f32_e32 v76, v118, v75
	v_fmac_f32_dpp v60, v59, v122 quad_perm:[1,0,3,2] row_mask:0xf bank_mask:0xf
	v_fmac_f32_dpp v76, v75, v123 quad_perm:[1,0,3,2] row_mask:0xf bank_mask:0xf
	v_cvt_pk_bf16_f32 v148, v60, v76
	ds_write_b32 v151, v148 offset:7616
	v_fmac_f32_e32 v61, v116, v60
	v_fmac_f32_e32 v77, v118, v76
	v_fmac_f32_dpp v61, v60, v122 quad_perm:[1,0,3,2] row_mask:0xf bank_mask:0xf
	v_fmac_f32_dpp v77, v76, v123 quad_perm:[1,0,3,2] row_mask:0xf bank_mask:0xf
	v_cvt_pk_bf16_f32 v149, v61, v77
	ds_write_b32 v151, v149 offset:7888
	v_fmac_f32_e32 v62, v116, v61
	v_fmac_f32_e32 v78, v118, v77
	v_fmac_f32_dpp v62, v61, v122 quad_perm:[1,0,3,2] row_mask:0xf bank_mask:0xf
	v_fmac_f32_dpp v78, v77, v123 quad_perm:[1,0,3,2] row_mask:0xf bank_mask:0xf
	v_cvt_pk_bf16_f32 v148, v62, v78
	ds_write_b32 v151, v148 offset:8160
	v_fmac_f32_e32 v63, v116, v62
	v_fmac_f32_e32 v79, v118, v78
	v_fmac_f32_dpp v63, v62, v122 quad_perm:[1,0,3,2] row_mask:0xf bank_mask:0xf
	v_fmac_f32_dpp v79, v78, v123 quad_perm:[1,0,3,2] row_mask:0xf bank_mask:0xf
	v_cvt_pk_bf16_f32 v149, v63, v79
	ds_write_b32 v151, v149 offset:8432
	v_mov_b32_e32 v120, v63
	v_mov_b32_e32 v121, v79
	s_waitcnt vmcnt(11)
	ds_write_b128 v162, v[168:171] offset:1536
	v_cndmask_b32_e64 v182, 0, v168, s[66:67]
	v_cndmask_b32_e64 v183, 0, v169, s[66:67]
	v_cndmask_b32_e64 v184, 0, v170, s[66:67]
	v_cndmask_b32_e64 v185, 0, v171, s[66:67]
	v_cndmask_b32_e64 v186, 0, v168, s[68:69]
	v_cndmask_b32_e64 v187, 0, v169, s[68:69]
	v_cndmask_b32_e64 v188, 0, v170, s[68:69]
	v_cndmask_b32_e64 v189, 0, v171, s[68:69]
	global_load_dwordx4 v[168:171], v150, s[10:11] offset:512
	s_add_u32 s29, s14, 4
	s_cmp_lt_u32 s29, 32
	s_cselect_b32 s29, 1024, 0
	s_add_u32 s10, s10, s29
	s_addc_u32 s11, s11, 0
	ds_read_b128 v[124:127], v152
	ds_read_b128 v[128:131], v152 offset:64
	ds_read_b128 v[132:135], v152 offset:128
	ds_read_b128 v[136:139], v152 offset:192
	ds_read_b64 v[160:161], v163
	v_mfma_f32_32x32x16_bf16 v[48:63], v[182:185], v[84:87], 0
	v_mfma_f32_32x32x16_bf16 v[64:79], v[182:185], v[88:91], 0
	v_mfma_f32_32x32x16_bf16 v[48:63], v[186:189], v[92:95], v[48:63]
	v_mfma_f32_32x32x16_bf16 v[64:79], v[186:189], v[96:99], v[64:79]
	s_waitcnt lgkmcnt(4)
	v_mfma_f32_16x16x32_bf16 v[140:143], v[100:103], v[124:127], 0
	s_waitcnt lgkmcnt(3)
	v_mfma_f32_16x16x32_bf16 v[140:143], v[104:107], v[128:131], v[140:143]
	s_waitcnt lgkmcnt(2)
	v_mfma_f32_16x16x32_bf16 v[140:143], v[108:111], v[132:135], v[140:143]
	s_waitcnt lgkmcnt(1)
	v_mfma_f32_16x16x32_bf16 v[140:143], v[112:115], v[136:139], v[140:143]
	s_nop 9
	s_waitcnt vmcnt(9) lgkmcnt(0)
	v_add_f32_e32 v182, v6, v140
	v_add_f32_e32 v183, v7, v141
	v_add_f32_e32 v184, v8, v142
	v_add_f32_e32 v185, v9, v143
	v_lshlrev_b32_e32 v186, 16, v160
	v_and_b32_e32 v187, 0xffff0000, v160
	v_lshlrev_b32_e32 v188, 16, v161
	v_and_b32_e32 v189, 0xffff0000, v161
	v_fmac_f32_e32 v182, v164, v186
	v_fmac_f32_e32 v183, v165, v187
	v_fmac_f32_e32 v184, v166, v188
	v_fmac_f32_e32 v185, v167, v189
	v_mul_f32_e32 v186, 0x3d372713, v182
	v_mul_f32_e32 v187, 0x3d372713, v183
	v_mul_f32_e32 v188, 0x3d372713, v184
	v_mul_f32_e32 v189, 0x3d372713, v185
	v_mul_f32_e32 v186, v182, v186
	v_mul_f32_e32 v187, v183, v187
	v_mul_f32_e32 v188, v184, v188
	v_mul_f32_e32 v189, v185, v189
	v_fma_f32 v186, v182, v186, v182
	v_fma_f32 v187, v183, v187, v183
	v_fma_f32 v188, v184, v188, v184
	v_fma_f32 v189, v185, v189, v185
	v_mul_f32_e32 v186, 0xbfcc422a, v186
	v_mul_f32_e32 v187, 0xbfcc422a, v187
	v_mul_f32_e32 v188, 0xbfcc422a, v188
	v_mul_f32_e32 v189, 0xbfcc422a, v189
	v_mul_f32_e32 v186, 0x3fb8aa3b, v186
	v_mul_f32_e32 v187, 0x3fb8aa3b, v187
	v_mul_f32_e32 v188, 0x3fb8aa3b, v188
	v_mul_f32_e32 v189, 0x3fb8aa3b, v189
	v_exp_f32_e32 v186, v186
	v_exp_f32_e32 v187, v187
	v_exp_f32_e32 v188, v188
	v_exp_f32_e32 v189, v189
	v_add_f32_e32 v186, 1.0, v186
	v_add_f32_e32 v187, 1.0, v187
	v_add_f32_e32 v188, 1.0, v188
	v_add_f32_e32 v189, 1.0, v189
	v_rcp_f32_e32 v186, v186
	v_rcp_f32_e32 v187, v187
	v_rcp_f32_e32 v188, v188
	v_rcp_f32_e32 v189, v189
	v_mul_f32_e32 v182, v182, v186
	v_mul_f32_e32 v183, v183, v187
	v_mul_f32_e32 v184, v184, v188
	v_mul_f32_e32 v185, v185, v189
	v_cvt_pk_bf16_f32 v148, v182, v183
	v_cvt_pk_bf16_f32 v149, v184, v185
	global_store_dwordx2 v156, v[148:149], s[12:13]
	ds_read_b128 v[124:127], v152 offset:4352
	ds_read_b128 v[128:131], v152 offset:4416
	ds_read_b128 v[132:135], v152 offset:4480
	ds_read_b128 v[136:139], v152 offset:4544
	ds_read_b64 v[160:161], v163 offset:512
	s_waitcnt lgkmcnt(4)
	v_mfma_f32_16x16x32_bf16 v[140:143], v[100:103], v[124:127], 0
	s_waitcnt lgkmcnt(3)
	v_mfma_f32_16x16x32_bf16 v[140:143], v[104:107], v[128:131], v[140:143]
	s_waitcnt lgkmcnt(2)
	v_mfma_f32_16x16x32_bf16 v[140:143], v[108:111], v[132:135], v[140:143]
	s_waitcnt lgkmcnt(1)
	v_mfma_f32_16x16x32_bf16 v[140:143], v[112:115], v[136:139], v[140:143]
	s_nop 9
	s_waitcnt vmcnt(9) lgkmcnt(0)
	v_add_f32_e32 v182, v10, v140
	v_add_f32_e32 v183, v11, v141
	v_add_f32_e32 v184, v12, v142
	v_add_f32_e32 v185, v13, v143
	v_lshlrev_b32_e32 v186, 16, v160
	v_and_b32_e32 v187, 0xffff0000, v160
	v_lshlrev_b32_e32 v188, 16, v161
	v_and_b32_e32 v189, 0xffff0000, v161
	v_fmac_f32_e32 v182, v164, v186
	v_fmac_f32_e32 v183, v165, v187
	v_fmac_f32_e32 v184, v166, v188
	v_fmac_f32_e32 v185, v167, v189
	v_mul_f32_e32 v186, 0x3d372713, v182
	v_mul_f32_e32 v187, 0x3d372713, v183
	v_mul_f32_e32 v188, 0x3d372713, v184
	v_mul_f32_e32 v189, 0x3d372713, v185
	v_mul_f32_e32 v186, v182, v186
	v_mul_f32_e32 v187, v183, v187
	v_mul_f32_e32 v188, v184, v188
	v_mul_f32_e32 v189, v185, v189
	v_fma_f32 v186, v182, v186, v182
	v_fma_f32 v187, v183, v187, v183
	v_fma_f32 v188, v184, v188, v184
	v_fma_f32 v189, v185, v189, v185
	v_mul_f32_e32 v186, 0xbfcc422a, v186
	v_mul_f32_e32 v187, 0xbfcc422a, v187
	v_mul_f32_e32 v188, 0xbfcc422a, v188
	v_mul_f32_e32 v189, 0xbfcc422a, v189
	v_mul_f32_e32 v186, 0x3fb8aa3b, v186
	v_mul_f32_e32 v187, 0x3fb8aa3b, v187
	v_mul_f32_e32 v188, 0x3fb8aa3b, v188
	v_mul_f32_e32 v189, 0x3fb8aa3b, v189
	v_exp_f32_e32 v186, v186
	v_exp_f32_e32 v187, v187
	v_exp_f32_e32 v188, v188
	v_exp_f32_e32 v189, v189
	v_add_f32_e32 v186, 1.0, v186
	v_add_f32_e32 v187, 1.0, v187
	v_add_f32_e32 v188, 1.0, v188
	v_add_f32_e32 v189, 1.0, v189
	v_rcp_f32_e32 v186, v186
	v_rcp_f32_e32 v187, v187
	v_rcp_f32_e32 v188, v188
	v_rcp_f32_e32 v189, v189
	v_mul_f32_e32 v182, v182, v186
	v_mul_f32_e32 v183, v183, v187
	v_mul_f32_e32 v184, v184, v188
	v_mul_f32_e32 v185, v185, v189
	v_cvt_pk_bf16_f32 v148, v182, v183
	v_cvt_pk_bf16_f32 v149, v184, v185
	global_store_dwordx2 v159, v[148:149], s[12:13]
	s_add_u32 s12, s12, 65536
	s_addc_u32 s13, s13, 0
	global_load_dwordx4 v[6:9], v153, s[42:43]
	global_load_dwordx4 v[10:13], v157, s[42:43]
	s_add_u32 s42, s42, 2048
	s_addc_u32 s43, s43, 0
	v_fmac_f32_e32 v16, v116, v120
	v_fmac_f32_e32 v32, v118, v121
	v_fmac_f32_dpp v16, v120, v122 quad_perm:[1,0,3,2] row_mask:0xf bank_mask:0xf
	v_fmac_f32_dpp v32, v121, v123 quad_perm:[1,0,3,2] row_mask:0xf bank_mask:0xf
	v_cvt_pk_bf16_f32 v148, v16, v32
	ds_write_b32 v151, v148
	v_fmac_f32_e32 v17, v116, v16
	v_fmac_f32_e32 v33, v118, v32
	v_fmac_f32_dpp v17, v16, v122 quad_perm:[1,0,3,2] row_mask:0xf bank_mask:0xf
	v_fmac_f32_dpp v33, v32, v123 quad_perm:[1,0,3,2] row_mask:0xf bank_mask:0xf
	v_cvt_pk_bf16_f32 v149, v17, v33
	ds_write_b32 v151, v149 offset:272
	v_fmac_f32_e32 v18, v116, v17
	v_fmac_f32_e32 v34, v118, v33
	v_fmac_f32_dpp v18, v17, v122 quad_perm:[1,0,3,2] row_mask:0xf bank_mask:0xf
	v_fmac_f32_dpp v34, v33, v123 quad_perm:[1,0,3,2] row_mask:0xf bank_mask:0xf
	v_cvt_pk_bf16_f32 v148, v18, v34
	ds_write_b32 v151, v148 offset:544
	v_fmac_f32_e32 v19, v116, v18
	v_fmac_f32_e32 v35, v118, v34
	v_fmac_f32_dpp v19, v18, v122 quad_perm:[1,0,3,2] row_mask:0xf bank_mask:0xf
	v_fmac_f32_dpp v35, v34, v123 quad_perm:[1,0,3,2] row_mask:0xf bank_mask:0xf
	v_cvt_pk_bf16_f32 v149, v19, v35
	ds_write_b32 v151, v149 offset:816
	v_fmac_f32_e32 v20, v116, v19
	v_fmac_f32_e32 v36, v118, v35
	v_fmac_f32_dpp v20, v19, v122 quad_perm:[1,0,3,2] row_mask:0xf bank_mask:0xf
	v_fmac_f32_dpp v36, v35, v123 quad_perm:[1,0,3,2] row_mask:0xf bank_mask:0xf
	v_cvt_pk_bf16_f32 v148, v20, v36
	ds_write_b32 v151, v148 offset:1088
	v_fmac_f32_e32 v21, v116, v20
	v_fmac_f32_e32 v37, v118, v36
	v_fmac_f32_dpp v21, v20, v122 quad_perm:[1,0,3,2] row_mask:0xf bank_mask:0xf
	v_fmac_f32_dpp v37, v36, v123 quad_perm:[1,0,3,2] row_mask:0xf bank_mask:0xf
	v_cvt_pk_bf16_f32 v149, v21, v37
	ds_write_b32 v151, v149 offset:1360
	v_fmac_f32_e32 v22, v116, v21
	v_fmac_f32_e32 v38, v118, v37
	v_fmac_f32_dpp v22, v21, v122 quad_perm:[1,0,3,2] row_mask:0xf bank_mask:0xf
	v_fmac_f32_dpp v38, v37, v123 quad_perm:[1,0,3,2] row_mask:0xf bank_mask:0xf
	v_cvt_pk_bf16_f32 v148, v22, v38
	ds_write_b32 v151, v148 offset:1632
	v_fmac_f32_e32 v23, v116, v22
	v_fmac_f32_e32 v39, v118, v38
	v_fmac_f32_dpp v23, v22, v122 quad_perm:[1,0,3,2] row_mask:0xf bank_mask:0xf
	v_fmac_f32_dpp v39, v38, v123 quad_perm:[1,0,3,2] row_mask:0xf bank_mask:0xf
	v_cvt_pk_bf16_f32 v149, v23, v39
	ds_write_b32 v151, v149 offset:1904
	v_fmac_f32_e32 v24, v116, v23
	v_fmac_f32_e32 v40, v118, v39
	v_fmac_f32_dpp v24, v23, v122 quad_perm:[1,0,3,2] row_mask:0xf bank_mask:0xf
	v_fmac_f32_dpp v40, v39, v123 quad_perm:[1,0,3,2] row_mask:0xf bank_mask:0xf
	v_cvt_pk_bf16_f32 v148, v24, v40
	ds_write_b32 v151, v148 offset:2176
	v_fmac_f32_e32 v25, v116, v24
	v_fmac_f32_e32 v41, v118, v40
	v_fmac_f32_dpp v25, v24, v122 quad_perm:[1,0,3,2] row_mask:0xf bank_mask:0xf
	v_fmac_f32_dpp v41, v40, v123 quad_perm:[1,0,3,2] row_mask:0xf bank_mask:0xf
	v_cvt_pk_bf16_f32 v149, v25, v41
	ds_write_b32 v151, v149 offset:2448
	v_fmac_f32_e32 v26, v116, v25
	v_fmac_f32_e32 v42, v118, v41
	v_fmac_f32_dpp v26, v25, v122 quad_perm:[1,0,3,2] row_mask:0xf bank_mask:0xf
	v_fmac_f32_dpp v42, v41, v123 quad_perm:[1,0,3,2] row_mask:0xf bank_mask:0xf
	v_cvt_pk_bf16_f32 v148, v26, v42
	ds_write_b32 v151, v148 offset:2720
	v_fmac_f32_e32 v27, v116, v26
	v_fmac_f32_e32 v43, v118, v42
	v_fmac_f32_dpp v27, v26, v122 quad_perm:[1,0,3,2] row_mask:0xf bank_mask:0xf
	v_fmac_f32_dpp v43, v42, v123 quad_perm:[1,0,3,2] row_mask:0xf bank_mask:0xf
	v_cvt_pk_bf16_f32 v149, v27, v43
	ds_write_b32 v151, v149 offset:2992
	v_fmac_f32_e32 v28, v116, v27
	v_fmac_f32_e32 v44, v118, v43
	v_fmac_f32_dpp v28, v27, v122 quad_perm:[1,0,3,2] row_mask:0xf bank_mask:0xf
	v_fmac_f32_dpp v44, v43, v123 quad_perm:[1,0,3,2] row_mask:0xf bank_mask:0xf
	v_cvt_pk_bf16_f32 v148, v28, v44
	ds_write_b32 v151, v148 offset:3264
	v_fmac_f32_e32 v29, v116, v28
	v_fmac_f32_e32 v45, v118, v44
	v_fmac_f32_dpp v29, v28, v122 quad_perm:[1,0,3,2] row_mask:0xf bank_mask:0xf
	v_fmac_f32_dpp v45, v44, v123 quad_perm:[1,0,3,2] row_mask:0xf bank_mask:0xf
	v_cvt_pk_bf16_f32 v149, v29, v45
	ds_write_b32 v151, v149 offset:3536
	v_fmac_f32_e32 v30, v116, v29
	v_fmac_f32_e32 v46, v118, v45
	v_fmac_f32_dpp v30, v29, v122 quad_perm:[1,0,3,2] row_mask:0xf bank_mask:0xf
	v_fmac_f32_dpp v46, v45, v123 quad_perm:[1,0,3,2] row_mask:0xf bank_mask:0xf
	v_cvt_pk_bf16_f32 v148, v30, v46
	ds_write_b32 v151, v148 offset:3808
	v_fmac_f32_e32 v31, v116, v30
	v_fmac_f32_e32 v47, v118, v46
	v_fmac_f32_dpp v31, v30, v122 quad_perm:[1,0,3,2] row_mask:0xf bank_mask:0xf
	v_fmac_f32_dpp v47, v46, v123 quad_perm:[1,0,3,2] row_mask:0xf bank_mask:0xf
	v_cvt_pk_bf16_f32 v149, v31, v47
	ds_write_b32 v151, v149 offset:4080
	s_waitcnt vmcnt(11)
	ds_write_b128 v162, v[80:83]
	v_cndmask_b32_e64 v182, 0, v80, s[66:67]
	v_cndmask_b32_e64 v183, 0, v81, s[66:67]
	v_cndmask_b32_e64 v184, 0, v82, s[66:67]
	v_cndmask_b32_e64 v185, 0, v83, s[66:67]
	v_cndmask_b32_e64 v186, 0, v80, s[68:69]
	v_cndmask_b32_e64 v187, 0, v81, s[68:69]
	v_cndmask_b32_e64 v188, 0, v82, s[68:69]
	v_cndmask_b32_e64 v189, 0, v83, s[68:69]
	global_load_dwordx4 v[80:83], v150, s[10:11]
	v_fmac_f32_e32 v48, v116, v31
	v_fmac_f32_e32 v64, v118, v47
	v_fmac_f32_dpp v48, v31, v122 quad_perm:[1,0,3,2] row_mask:0xf bank_mask:0xf
	v_fmac_f32_dpp v64, v47, v123 quad_perm:[1,0,3,2] row_mask:0xf bank_mask:0xf
	v_cvt_pk_bf16_f32 v148, v48, v64
	ds_write_b32 v151, v148 offset:4352
	v_fmac_f32_e32 v49, v116, v48
	v_fmac_f32_e32 v65, v118, v64
	v_fmac_f32_dpp v49, v48, v122 quad_perm:[1,0,3,2] row_mask:0xf bank_mask:0xf
	v_fmac_f32_dpp v65, v64, v123 quad_perm:[1,0,3,2] row_mask:0xf bank_mask:0xf
	v_cvt_pk_bf16_f32 v149, v49, v65
	ds_write_b32 v151, v149 offset:4624
	v_mfma_f32_32x32x16_bf16 v[16:31], v[182:185], v[84:87], 0
	v_fmac_f32_e32 v50, v116, v49
	v_fmac_f32_e32 v66, v118, v65
	v_fmac_f32_dpp v50, v49, v122 quad_perm:[1,0,3,2] row_mask:0xf bank_mask:0xf
	v_fmac_f32_dpp v66, v65, v123 quad_perm:[1,0,3,2] row_mask:0xf bank_mask:0xf
	v_cvt_pk_bf16_f32 v148, v50, v66
	ds_write_b32 v151, v148 offset:4896
	v_fmac_f32_e32 v51, v116, v50
	v_fmac_f32_e32 v67, v118, v66
	v_fmac_f32_dpp v51, v50, v122 quad_perm:[1,0,3,2] row_mask:0xf bank_mask:0xf
	v_fmac_f32_dpp v67, v66, v123 quad_perm:[1,0,3,2] row_mask:0xf bank_mask:0xf
	v_cvt_pk_bf16_f32 v149, v51, v67
	ds_write_b32 v151, v149 offset:5168
	v_mfma_f32_32x32x16_bf16 v[32:47], v[182:185], v[88:91], 0
	v_fmac_f32_e32 v52, v116, v51
	v_fmac_f32_e32 v68, v118, v67
	v_fmac_f32_dpp v52, v51, v122 quad_perm:[1,0,3,2] row_mask:0xf bank_mask:0xf
	v_fmac_f32_dpp v68, v67, v123 quad_perm:[1,0,3,2] row_mask:0xf bank_mask:0xf
	v_cvt_pk_bf16_f32 v148, v52, v68
	ds_write_b32 v151, v148 offset:5440
	v_fmac_f32_e32 v53, v116, v52
	v_fmac_f32_e32 v69, v118, v68
	v_fmac_f32_dpp v53, v52, v122 quad_perm:[1,0,3,2] row_mask:0xf bank_mask:0xf
	v_fmac_f32_dpp v69, v68, v123 quad_perm:[1,0,3,2] row_mask:0xf bank_mask:0xf
	v_cvt_pk_bf16_f32 v149, v53, v69
	ds_write_b32 v151, v149 offset:5712
	v_mfma_f32_32x32x16_bf16 v[16:31], v[186:189], v[92:95], v[16:31]
	v_fmac_f32_e32 v54, v116, v53
	v_fmac_f32_e32 v70, v118, v69
	v_fmac_f32_dpp v54, v53, v122 quad_perm:[1,0,3,2] row_mask:0xf bank_mask:0xf
	v_fmac_f32_dpp v70, v69, v123 quad_perm:[1,0,3,2] row_mask:0xf bank_mask:0xf
	v_cvt_pk_bf16_f32 v148, v54, v70
	ds_write_b32 v151, v148 offset:5984
	v_fmac_f32_e32 v55, v116, v54
	v_fmac_f32_e32 v71, v118, v70
	v_fmac_f32_dpp v55, v54, v122 quad_perm:[1,0,3,2] row_mask:0xf bank_mask:0xf
	v_fmac_f32_dpp v71, v70, v123 quad_perm:[1,0,3,2] row_mask:0xf bank_mask:0xf
	v_cvt_pk_bf16_f32 v149, v55, v71
	ds_write_b32 v151, v149 offset:6256
	v_mfma_f32_32x32x16_bf16 v[32:47], v[186:189], v[96:99], v[32:47]
	v_fmac_f32_e32 v56, v116, v55
	v_fmac_f32_e32 v72, v118, v71
	v_fmac_f32_dpp v56, v55, v122 quad_perm:[1,0,3,2] row_mask:0xf bank_mask:0xf
	v_fmac_f32_dpp v72, v71, v123 quad_perm:[1,0,3,2] row_mask:0xf bank_mask:0xf
	v_cvt_pk_bf16_f32 v148, v56, v72
	ds_write_b32 v151, v148 offset:6528
	v_fmac_f32_e32 v57, v116, v56
	v_fmac_f32_e32 v73, v118, v72
	v_fmac_f32_dpp v57, v56, v122 quad_perm:[1,0,3,2] row_mask:0xf bank_mask:0xf
	v_fmac_f32_dpp v73, v72, v123 quad_perm:[1,0,3,2] row_mask:0xf bank_mask:0xf
	v_cvt_pk_bf16_f32 v149, v57, v73
	ds_write_b32 v151, v149 offset:6800
	v_fmac_f32_e32 v58, v116, v57
	v_fmac_f32_e32 v74, v118, v73
	v_fmac_f32_dpp v58, v57, v122 quad_perm:[1,0,3,2] row_mask:0xf bank_mask:0xf
	v_fmac_f32_dpp v74, v73, v123 quad_perm:[1,0,3,2] row_mask:0xf bank_mask:0xf
	v_cvt_pk_bf16_f32 v148, v58, v74
	ds_write_b32 v151, v148 offset:7072
	v_fmac_f32_e32 v59, v116, v58
	v_fmac_f32_e32 v75, v118, v74
	v_fmac_f32_dpp v59, v58, v122 quad_perm:[1,0,3,2] row_mask:0xf bank_mask:0xf
	v_fmac_f32_dpp v75, v74, v123 quad_perm:[1,0,3,2] row_mask:0xf bank_mask:0xf
	v_cvt_pk_bf16_f32 v149, v59, v75
	ds_write_b32 v151, v149 offset:7344
	v_fmac_f32_e32 v60, v116, v59
	v_fmac_f32_e32 v76, v118, v75
	v_fmac_f32_dpp v60, v59, v122 quad_perm:[1,0,3,2] row_mask:0xf bank_mask:0xf
	v_fmac_f32_dpp v76, v75, v123 quad_perm:[1,0,3,2] row_mask:0xf bank_mask:0xf
	v_cvt_pk_bf16_f32 v148, v60, v76
	ds_write_b32 v151, v148 offset:7616
	v_fmac_f32_e32 v61, v116, v60
	v_fmac_f32_e32 v77, v118, v76
	v_fmac_f32_dpp v61, v60, v122 quad_perm:[1,0,3,2] row_mask:0xf bank_mask:0xf
	v_fmac_f32_dpp v77, v76, v123 quad_perm:[1,0,3,2] row_mask:0xf bank_mask:0xf
	v_cvt_pk_bf16_f32 v149, v61, v77
	ds_write_b32 v151, v149 offset:7888
	v_fmac_f32_e32 v62, v116, v61
	v_fmac_f32_e32 v78, v118, v77
	v_fmac_f32_dpp v62, v61, v122 quad_perm:[1,0,3,2] row_mask:0xf bank_mask:0xf
	v_fmac_f32_dpp v78, v77, v123 quad_perm:[1,0,3,2] row_mask:0xf bank_mask:0xf
	v_cvt_pk_bf16_f32 v148, v62, v78
	ds_write_b32 v151, v148 offset:8160
	v_fmac_f32_e32 v63, v116, v62
	v_fmac_f32_e32 v79, v118, v78
	v_fmac_f32_dpp v63, v62, v122 quad_perm:[1,0,3,2] row_mask:0xf bank_mask:0xf
	v_fmac_f32_dpp v79, v78, v123 quad_perm:[1,0,3,2] row_mask:0xf bank_mask:0xf
	v_cvt_pk_bf16_f32 v149, v63, v79
	ds_write_b32 v151, v149 offset:8432
	v_mov_b32_e32 v120, v63
	v_mov_b32_e32 v121, v79
	s_waitcnt vmcnt(11)
	ds_write_b128 v162, v[194:197] offset:512
	v_cndmask_b32_e64 v182, 0, v194, s[66:67]
	v_cndmask_b32_e64 v183, 0, v195, s[66:67]
	v_cndmask_b32_e64 v184, 0, v196, s[66:67]
	v_cndmask_b32_e64 v185, 0, v197, s[66:67]
	v_cndmask_b32_e64 v186, 0, v194, s[68:69]
	v_cndmask_b32_e64 v187, 0, v195, s[68:69]
	v_cndmask_b32_e64 v188, 0, v196, s[68:69]
	v_cndmask_b32_e64 v189, 0, v197, s[68:69]
	global_load_dwordx4 v[194:197], v150, s[10:11] offset:512
	s_add_u32 s29, s14, 5
	s_cmp_lt_u32 s29, 32
	s_cselect_b32 s29, 1024, 0
	s_add_u32 s10, s10, s29
	s_addc_u32 s11, s11, 0
	ds_read_b128 v[124:127], v152
	ds_read_b128 v[128:131], v152 offset:64
	ds_read_b128 v[132:135], v152 offset:128
	ds_read_b128 v[136:139], v152 offset:192
	ds_read_b64 v[160:161], v163 offset:1024
	v_mfma_f32_32x32x16_bf16 v[48:63], v[182:185], v[84:87], 0
	v_mfma_f32_32x32x16_bf16 v[64:79], v[182:185], v[88:91], 0
	v_mfma_f32_32x32x16_bf16 v[48:63], v[186:189], v[92:95], v[48:63]
	v_mfma_f32_32x32x16_bf16 v[64:79], v[186:189], v[96:99], v[64:79]
	s_waitcnt lgkmcnt(4)
	v_mfma_f32_16x16x32_bf16 v[140:143], v[100:103], v[124:127], 0
	s_waitcnt lgkmcnt(3)
	v_mfma_f32_16x16x32_bf16 v[140:143], v[104:107], v[128:131], v[140:143]
	s_waitcnt lgkmcnt(2)
	v_mfma_f32_16x16x32_bf16 v[140:143], v[108:111], v[132:135], v[140:143]
	s_waitcnt lgkmcnt(1)
	v_mfma_f32_16x16x32_bf16 v[140:143], v[112:115], v[136:139], v[140:143]
	s_nop 9
	s_waitcnt vmcnt(9) lgkmcnt(0)
	v_add_f32_e32 v182, v172, v140
	v_add_f32_e32 v183, v173, v141
	v_add_f32_e32 v184, v174, v142
	v_add_f32_e32 v185, v175, v143
	v_lshlrev_b32_e32 v186, 16, v160
	v_and_b32_e32 v187, 0xffff0000, v160
	v_lshlrev_b32_e32 v188, 16, v161
	v_and_b32_e32 v189, 0xffff0000, v161
	v_fmac_f32_e32 v182, v164, v186
	v_fmac_f32_e32 v183, v165, v187
	v_fmac_f32_e32 v184, v166, v188
	v_fmac_f32_e32 v185, v167, v189
	v_mul_f32_e32 v186, 0x3d372713, v182
	v_mul_f32_e32 v187, 0x3d372713, v183
	v_mul_f32_e32 v188, 0x3d372713, v184
	v_mul_f32_e32 v189, 0x3d372713, v185
	v_mul_f32_e32 v186, v182, v186
	v_mul_f32_e32 v187, v183, v187
	v_mul_f32_e32 v188, v184, v188
	v_mul_f32_e32 v189, v185, v189
	v_fma_f32 v186, v182, v186, v182
	v_fma_f32 v187, v183, v187, v183
	v_fma_f32 v188, v184, v188, v184
	v_fma_f32 v189, v185, v189, v185
	v_mul_f32_e32 v186, 0xbfcc422a, v186
	v_mul_f32_e32 v187, 0xbfcc422a, v187
	v_mul_f32_e32 v188, 0xbfcc422a, v188
	v_mul_f32_e32 v189, 0xbfcc422a, v189
	v_mul_f32_e32 v186, 0x3fb8aa3b, v186
	v_mul_f32_e32 v187, 0x3fb8aa3b, v187
	v_mul_f32_e32 v188, 0x3fb8aa3b, v188
	v_mul_f32_e32 v189, 0x3fb8aa3b, v189
	v_exp_f32_e32 v186, v186
	v_exp_f32_e32 v187, v187
	v_exp_f32_e32 v188, v188
	v_exp_f32_e32 v189, v189
	v_add_f32_e32 v186, 1.0, v186
	v_add_f32_e32 v187, 1.0, v187
	v_add_f32_e32 v188, 1.0, v188
	v_add_f32_e32 v189, 1.0, v189
	v_rcp_f32_e32 v186, v186
	v_rcp_f32_e32 v187, v187
	v_rcp_f32_e32 v188, v188
	v_rcp_f32_e32 v189, v189
	v_mul_f32_e32 v182, v182, v186
	v_mul_f32_e32 v183, v183, v187
	v_mul_f32_e32 v184, v184, v188
	v_mul_f32_e32 v185, v185, v189
	v_cvt_pk_bf16_f32 v148, v182, v183
	v_cvt_pk_bf16_f32 v149, v184, v185
	global_store_dwordx2 v156, v[148:149], s[12:13]
	ds_read_b128 v[124:127], v152 offset:4352
	ds_read_b128 v[128:131], v152 offset:4416
	ds_read_b128 v[132:135], v152 offset:4480
	ds_read_b128 v[136:139], v152 offset:4544
	ds_read_b64 v[160:161], v163 offset:1536
	s_waitcnt lgkmcnt(4)
	v_mfma_f32_16x16x32_bf16 v[140:143], v[100:103], v[124:127], 0
	s_waitcnt lgkmcnt(3)
	v_mfma_f32_16x16x32_bf16 v[140:143], v[104:107], v[128:131], v[140:143]
	s_waitcnt lgkmcnt(2)
	v_mfma_f32_16x16x32_bf16 v[140:143], v[108:111], v[132:135], v[140:143]
	s_waitcnt lgkmcnt(1)
	v_mfma_f32_16x16x32_bf16 v[140:143], v[112:115], v[136:139], v[140:143]
	s_nop 9
	s_waitcnt vmcnt(9) lgkmcnt(0)
	v_add_f32_e32 v182, v176, v140
	v_add_f32_e32 v183, v177, v141
	v_add_f32_e32 v184, v178, v142
	v_add_f32_e32 v185, v179, v143
	v_lshlrev_b32_e32 v186, 16, v160
	v_and_b32_e32 v187, 0xffff0000, v160
	v_lshlrev_b32_e32 v188, 16, v161
	v_and_b32_e32 v189, 0xffff0000, v161
	v_fmac_f32_e32 v182, v164, v186
	v_fmac_f32_e32 v183, v165, v187
	v_fmac_f32_e32 v184, v166, v188
	v_fmac_f32_e32 v185, v167, v189
	v_mul_f32_e32 v186, 0x3d372713, v182
	v_mul_f32_e32 v187, 0x3d372713, v183
	v_mul_f32_e32 v188, 0x3d372713, v184
	v_mul_f32_e32 v189, 0x3d372713, v185
	v_mul_f32_e32 v186, v182, v186
	v_mul_f32_e32 v187, v183, v187
	v_mul_f32_e32 v188, v184, v188
	v_mul_f32_e32 v189, v185, v189
	v_fma_f32 v186, v182, v186, v182
	v_fma_f32 v187, v183, v187, v183
	v_fma_f32 v188, v184, v188, v184
	v_fma_f32 v189, v185, v189, v185
	v_mul_f32_e32 v186, 0xbfcc422a, v186
	v_mul_f32_e32 v187, 0xbfcc422a, v187
	v_mul_f32_e32 v188, 0xbfcc422a, v188
	v_mul_f32_e32 v189, 0xbfcc422a, v189
	v_mul_f32_e32 v186, 0x3fb8aa3b, v186
	v_mul_f32_e32 v187, 0x3fb8aa3b, v187
	v_mul_f32_e32 v188, 0x3fb8aa3b, v188
	v_mul_f32_e32 v189, 0x3fb8aa3b, v189
	v_exp_f32_e32 v186, v186
	v_exp_f32_e32 v187, v187
	v_exp_f32_e32 v188, v188
	v_exp_f32_e32 v189, v189
	v_add_f32_e32 v186, 1.0, v186
	v_add_f32_e32 v187, 1.0, v187
	v_add_f32_e32 v188, 1.0, v188
	v_add_f32_e32 v189, 1.0, v189
	v_rcp_f32_e32 v186, v186
	v_rcp_f32_e32 v187, v187
	v_rcp_f32_e32 v188, v188
	v_rcp_f32_e32 v189, v189
	v_mul_f32_e32 v182, v182, v186
	v_mul_f32_e32 v183, v183, v187
	v_mul_f32_e32 v184, v184, v188
	v_mul_f32_e32 v185, v185, v189
	v_cvt_pk_bf16_f32 v148, v182, v183
	v_cvt_pk_bf16_f32 v149, v184, v185
	global_store_dwordx2 v159, v[148:149], s[12:13]
	s_add_u32 s12, s12, 65536
	s_addc_u32 s13, s13, 0
	s_add_u32 s14, s14, 2
	s_cmp_lt_u32 s14, 32
	s_cbranch_scc1 .Lssm_tileB_d0m0
	s_waitcnt vmcnt(0) lgkmcnt(0)
	s_branch .Lssm_lat_join
.Lssm_lat_bwd:
	s_add_u32 s28, s24, 64
	s_lshl_b32 s29, s28, 13
	s_add_u32 s29, s29, 0x200000
	s_add_u32 s10, s62, s29
	s_addc_u32 s11, s63, 0
	global_load_dwordx4 v[84:87], v177, s[10:11]
	global_load_dwordx4 v[88:91], v177, s[10:11] offset:2048
	s_add_u32 s12, s10, 0x1000
	s_addc_u32 s13, s11, 0
	global_load_dwordx4 v[92:95], v177, s[12:13]
	global_load_dwordx4 v[96:99], v177, s[12:13] offset:2048
	s_lshl_b32 s29, s28, 12
	s_add_u32 s29, s29, 0x300000
	s_add_u32 s16, s62, s29
	s_addc_u32 s17, s63, 0
	global_load_dwordx2 v[20:21], v178, s[16:17]
	global_load_dwordx2 v[22:23], v178, s[16:17] offset:1024
	global_load_dwordx2 v[24:25], v178, s[16:17] offset:512
	global_load_dwordx2 v[26:27], v178, s[16:17] offset:1536
	global_load_dwordx2 v[28:29], v178, s[16:17] offset:2048
	global_load_dwordx2 v[30:31], v178, s[16:17] offset:3072
	global_load_dwordx2 v[32:33], v178, s[16:17] offset:2560
	global_load_dwordx2 v[34:35], v178, s[16:17] offset:3584
	s_lshl_b32 s29, s28, 9
	s_add_u32 s29, s29, 0x100000
	s_add_u32 s18, s62, s29
	s_addc_u32 s19, s63, 0
	global_load_dwordx2 v[116:117], v179, s[18:19]
	global_load_dwordx2 v[118:119], v179, s[18:19] offset:128
	s_lshl_b32 s30, s23, 1
	s_add_u32 s30, s30, 1
	s_lshl_b32 s30, s30, 15
	s_lshl_b32 s31, s24, 8
	s_add_u32 s30, s30, s31
	v_readlane_b32 s34, v254, 10
	v_readlane_b32 s35, v254, 11
	s_nop 3
	s_add_u32 s34, s34, s30
	s_addc_u32 s35, s35, 0
	global_load_dword v120, v180, s[34:35]
	global_load_dword v121, v180, s[34:35] offset:64
	v_readlane_b32 s34, v254, 28
	v_readlane_b32 s35, v254, 29
	s_nop 3
	s_lshl_b32 s31, s24, 6
	s_add_u32 s34, s34, s31
	s_addc_u32 s35, s35, 0
	global_load_dwordx4 v[164:167], v181, s[34:35]
	s_lshl_b32 s31, s25, 5
	s_lshl_b32 s29, s24, 19
	s_add_u32 s31, s31, s29
	s_add_u32 s31, s31, 0x16800000
	s_add_u32 s4, s62, s31
	s_addc_u32 s5, s63, 0
	s_lshl_b32 s31, s22, 1
	s_add_u32 s31, s31, 1
	s_lshl_b32 s31, s31, 15
	s_add_u32 s31, s31, 0x4800000
	s_add_u32 s6, s62, s31
	s_addc_u32 s7, s63, 0
	s_add_u32 s34, s4, 31744
	s_addc_u32 s35, s5, 0
	global_load_dwordx4 v[80:83], v150, s[34:35] offset:512
	global_load_dwordx4 v[194:197], v150, s[34:35]
	s_mov_b64 s[10:11], s[34:35]
	s_sub_u32 s10, s10, 1024
	s_subb_u32 s11, s11, 0
	global_load_dwordx4 v[144:147], v150, s[10:11] offset:512
	global_load_dwordx4 v[168:171], v150, s[10:11]
	s_sub_u32 s10, s10, 1024
	s_subb_u32 s11, s11, 0
	s_add_u32 s12, s6, 30720
	s_addc_u32 s13, s7, 0
	s_mov_b32 s14, 0
	s_mov_b32 s40, 0xffff0000
	s_waitcnt vmcnt(0)
	v_and_b32_e32 v182, 0xffff, v20
	v_lshrrev_b32_e32 v183, 16, v20
	v_and_b32_e32 v184, 0xffff, v21
	v_lshrrev_b32_e32 v185, 16, v21
	v_lshl_or_b32 v100, v22, 16, v182
	v_and_or_b32 v101, v22, s40, v183
	v_lshl_or_b32 v102, v23, 16, v184
	v_and_or_b32 v103, v23, s40, v185
	v_and_b32_e32 v182, 0xffff, v24
	v_lshrrev_b32_e32 v183, 16, v24
	v_and_b32_e32 v184, 0xffff, v25
	v_lshrrev_b32_e32 v185, 16, v25
	v_lshl_or_b32 v104, v26, 16, v182
	v_and_or_b32 v105, v26, s40, v183
	v_lshl_or_b32 v106, v27, 16, v184
	v_and_or_b32 v107, v27, s40, v185
	v_and_b32_e32 v182, 0xffff, v28
	v_lshrrev_b32_e32 v183, 16, v28
	v_and_b32_e32 v184, 0xffff, v29
	v_lshrrev_b32_e32 v185, 16, v29
	v_lshl_or_b32 v108, v30, 16, v182
	v_and_or_b32 v109, v30, s40, v183
	v_lshl_or_b32 v110, v31, 16, v184
	v_and_or_b32 v111, v31, s40, v185
	v_and_b32_e32 v182, 0xffff, v32
	v_lshrrev_b32_e32 v183, 16, v32
	v_and_b32_e32 v184, 0xffff, v33
	v_lshrrev_b32_e32 v185, 16, v33
	v_lshl_or_b32 v112, v34, 16, v182
	v_and_or_b32 v113, v34, s40, v183
	v_lshl_or_b32 v114, v35, 16, v184
	v_and_or_b32 v115, v35, s40, v185
	v_cmp_eq_u32_e32 vcc, 1, v174
	v_xor_b32_e32 v182, 0x80000000, v117
	v_xor_b32_e32 v183, 0x80000000, v119
	s_nop 1
	v_cndmask_b32_e32 v122, v182, v117, vcc
	v_cndmask_b32_e32 v123, v183, v119, vcc
	ds_write_b128 v162, v[80:83] offset:512
	ds_write_b128 v162, v[194:197]
	v_cndmask_b32_e64 v182, 0, v80, s[66:67]
	v_cndmask_b32_e64 v183, 0, v81, s[66:67]
	v_cndmask_b32_e64 v184, 0, v82, s[66:67]
	v_cndmask_b32_e64 v185, 0, v83, s[66:67]
	v_cndmask_b32_e64 v186, 0, v80, s[68:69]
	v_cndmask_b32_e64 v187, 0, v81, s[68:69]
	v_cndmask_b32_e64 v188, 0, v82, s[68:69]
	v_cndmask_b32_e64 v189, 0, v83, s[68:69]
	v_cndmask_b32_e64 v124, 0, v194, s[66:67]
	v_cndmask_b32_e64 v125, 0, v195, s[66:67]
	v_cndmask_b32_e64 v126, 0, v196, s[66:67]
	v_cndmask_b32_e64 v127, 0, v197, s[66:67]
	v_cndmask_b32_e64 v128, 0, v194, s[68:69]
	v_cndmask_b32_e64 v129, 0, v195, s[68:69]
	v_cndmask_b32_e64 v130, 0, v196, s[68:69]
	v_cndmask_b32_e64 v131, 0, v197, s[68:69]
	v_mfma_f32_32x32x16_bf16 v[48:63], v[182:185], v[84:87], 0
	v_mfma_f32_32x32x16_bf16 v[64:79], v[182:185], v[88:91], 0
	v_mfma_f32_32x32x16_bf16 v[48:63], v[186:189], v[92:95], v[48:63]
	v_mfma_f32_32x32x16_bf16 v[64:79], v[186:189], v[96:99], v[64:79]
	v_mfma_f32_32x32x16_bf16 v[16:31], v[124:127], v[84:87], 0
	v_mfma_f32_32x32x16_bf16 v[32:47], v[124:127], v[88:91], 0
	v_mfma_f32_32x32x16_bf16 v[16:31], v[128:131], v[92:95], v[16:31]
	v_mfma_f32_32x32x16_bf16 v[32:47], v[128:131], v[96:99], v[32:47]
	global_load_dwordx4 v[80:83], v150, s[10:11] offset:512
	global_load_dwordx4 v[194:197], v150, s[10:11]
	s_sub_u32 s10, s10, 1024
	s_subb_u32 s11, s11, 0
	s_nop 7
.Lssm_tileA_d1m0:
	v_fmac_f32_e32 v63, v116, v120
	v_fmac_f32_e32 v79, v118, v121
	v_fmac_f32_dpp v63, v120, v122 quad_perm:[1,0,3,2] row_mask:0xf bank_mask:0xf
	v_fmac_f32_dpp v79, v121, v123 quad_perm:[1,0,3,2] row_mask:0xf bank_mask:0xf
	v_cvt_pk_bf16_f32 v148, v63, v79
	ds_write_b32 v151, v148 offset:8432
	v_fmac_f32_e32 v62, v116, v63
	v_fmac_f32_e32 v78, v118, v79
	v_fmac_f32_dpp v62, v63, v122 quad_perm:[1,0,3,2] row_mask:0xf bank_mask:0xf
	v_fmac_f32_dpp v78, v79, v123 quad_perm:[1,0,3,2] row_mask:0xf bank_mask:0xf
	v_cvt_pk_bf16_f32 v149, v62, v78
	ds_write_b32 v151, v149 offset:8160
	v_fmac_f32_e32 v61, v116, v62
	v_fmac_f32_e32 v77, v118, v78
	v_fmac_f32_dpp v61, v62, v122 quad_perm:[1,0,3,2] row_mask:0xf bank_mask:0xf
	v_fmac_f32_dpp v77, v78, v123 quad_perm:[1,0,3,2] row_mask:0xf bank_mask:0xf
	v_cvt_pk_bf16_f32 v148, v61, v77
	ds_write_b32 v151, v148 offset:7888
	v_fmac_f32_e32 v60, v116, v61
	v_fmac_f32_e32 v76, v118, v77
	v_fmac_f32_dpp v60, v61, v122 quad_perm:[1,0,3,2] row_mask:0xf bank_mask:0xf
	v_fmac_f32_dpp v76, v77, v123 quad_perm:[1,0,3,2] row_mask:0xf bank_mask:0xf
	v_cvt_pk_bf16_f32 v149, v60, v76
	ds_write_b32 v151, v149 offset:7616
	v_fmac_f32_e32 v59, v116, v60
	v_fmac_f32_e32 v75, v118, v76
	v_fmac_f32_dpp v59, v60, v122 quad_perm:[1,0,3,2] row_mask:0xf bank_mask:0xf
	v_fmac_f32_dpp v75, v76, v123 quad_perm:[1,0,3,2] row_mask:0xf bank_mask:0xf
	v_cvt_pk_bf16_f32 v148, v59, v75
	ds_write_b32 v151, v148 offset:7344
	v_fmac_f32_e32 v58, v116, v59
	v_fmac_f32_e32 v74, v118, v75
	v_fmac_f32_dpp v58, v59, v122 quad_perm:[1,0,3,2] row_mask:0xf bank_mask:0xf
	v_fmac_f32_dpp v74, v75, v123 quad_perm:[1,0,3,2] row_mask:0xf bank_mask:0xf
	v_cvt_pk_bf16_f32 v149, v58, v74
	ds_write_b32 v151, v149 offset:7072
	v_fmac_f32_e32 v57, v116, v58
	v_fmac_f32_e32 v73, v118, v74
	v_fmac_f32_dpp v57, v58, v122 quad_perm:[1,0,3,2] row_mask:0xf bank_mask:0xf
	v_fmac_f32_dpp v73, v74, v123 quad_perm:[1,0,3,2] row_mask:0xf bank_mask:0xf
	v_cvt_pk_bf16_f32 v148, v57, v73
	ds_write_b32 v151, v148 offset:6800
	v_fmac_f32_e32 v56, v116, v57
	v_fmac_f32_e32 v72, v118, v73
	v_fmac_f32_dpp v56, v57, v122 quad_perm:[1,0,3,2] row_mask:0xf bank_mask:0xf
	v_fmac_f32_dpp v72, v73, v123 quad_perm:[1,0,3,2] row_mask:0xf bank_mask:0xf
	v_cvt_pk_bf16_f32 v149, v56, v72
	ds_write_b32 v151, v149 offset:6528
	v_fmac_f32_e32 v55, v116, v56
	v_fmac_f32_e32 v71, v118, v72
	v_fmac_f32_dpp v55, v56, v122 quad_perm:[1,0,3,2] row_mask:0xf bank_mask:0xf
	v_fmac_f32_dpp v71, v72, v123 quad_perm:[1,0,3,2] row_mask:0xf bank_mask:0xf
	v_cvt_pk_bf16_f32 v148, v55, v71
	ds_write_b32 v151, v148 offset:6256
	v_fmac_f32_e32 v54, v116, v55
	v_fmac_f32_e32 v70, v118, v71
	v_fmac_f32_dpp v54, v55, v122 quad_perm:[1,0,3,2] row_mask:0xf bank_mask:0xf
	v_fmac_f32_dpp v70, v71, v123 quad_perm:[1,0,3,2] row_mask:0xf bank_mask:0xf
	v_cvt_pk_bf16_f32 v149, v54, v70
	ds_write_b32 v151, v149 offset:5984
	v_fmac_f32_e32 v53, v116, v54
	v_fmac_f32_e32 v69, v118, v70
	v_fmac_f32_dpp v53, v54, v122 quad_perm:[1,0,3,2] row_mask:0xf bank_mask:0xf
	v_fmac_f32_dpp v69, v70, v123 quad_perm:[1,0,3,2] row_mask:0xf bank_mask:0xf
	v_cvt_pk_bf16_f32 v148, v53, v69
	ds_write_b32 v151, v148 offset:5712
	v_fmac_f32_e32 v52, v116, v53
	v_fmac_f32_e32 v68, v118, v69
	v_fmac_f32_dpp v52, v53, v122 quad_perm:[1,0,3,2] row_mask:0xf bank_mask:0xf
	v_fmac_f32_dpp v68, v69, v123 quad_perm:[1,0,3,2] row_mask:0xf bank_mask:0xf
	v_cvt_pk_bf16_f32 v149, v52, v68
	ds_write_b32 v151, v149 offset:5440
	v_fmac_f32_e32 v51, v116, v52
	v_fmac_f32_e32 v67, v118, v68
	v_fmac_f32_dpp v51, v52, v122 quad_perm:[1,0,3,2] row_mask:0xf bank_mask:0xf
	v_fmac_f32_dpp v67, v68, v123 quad_perm:[1,0,3,2] row_mask:0xf bank_mask:0xf
	v_cvt_pk_bf16_f32 v148, v51, v67
	ds_write_b32 v151, v148 offset:5168
	v_fmac_f32_e32 v50, v116, v51
	v_fmac_f32_e32 v66, v118, v67
	v_fmac_f32_dpp v50, v51, v122 quad_perm:[1,0,3,2] row_mask:0xf bank_mask:0xf
	v_fmac_f32_dpp v66, v67, v123 quad_perm:[1,0,3,2] row_mask:0xf bank_mask:0xf
	v_cvt_pk_bf16_f32 v149, v50, v66
	ds_write_b32 v151, v149 offset:4896
	v_fmac_f32_e32 v49, v116, v50
	v_fmac_f32_e32 v65, v118, v66
	v_fmac_f32_dpp v49, v50, v122 quad_perm:[1,0,3,2] row_mask:0xf bank_mask:0xf
	v_fmac_f32_dpp v65, v66, v123 quad_perm:[1,0,3,2] row_mask:0xf bank_mask:0xf
	v_cvt_pk_bf16_f32 v148, v49, v65
	ds_write_b32 v151, v148 offset:4624
	v_fmac_f32_e32 v48, v116, v49
	v_fmac_f32_e32 v64, v118, v65
	v_fmac_f32_dpp v48, v49, v122 quad_perm:[1,0,3,2] row_mask:0xf bank_mask:0xf
	v_fmac_f32_dpp v64, v65, v123 quad_perm:[1,0,3,2] row_mask:0xf bank_mask:0xf
	v_cvt_pk_bf16_f32 v149, v48, v64
	ds_write_b32 v151, v149 offset:4352
	s_waitcnt vmcnt(5)
	ds_write_b128 v162, v[144:147] offset:1536
	v_cndmask_b32_e64 v182, 0, v144, s[66:67]
	v_cndmask_b32_e64 v183, 0, v145, s[66:67]
	v_cndmask_b32_e64 v184, 0, v146, s[66:67]
	v_cndmask_b32_e64 v185, 0, v147, s[66:67]
	v_cndmask_b32_e64 v186, 0, v144, s[68:69]
	v_cndmask_b32_e64 v187, 0, v145, s[68:69]
	v_cndmask_b32_e64 v188, 0, v146, s[68:69]
	v_cndmask_b32_e64 v189, 0, v147, s[68:69]
	global_load_dwordx4 v[144:147], v150, s[10:11] offset:512
	v_fmac_f32_e32 v31, v116, v48
	v_fmac_f32_e32 v47, v118, v64
	v_fmac_f32_dpp v31, v48, v122 quad_perm:[1,0,3,2] row_mask:0xf bank_mask:0xf
	v_fmac_f32_dpp v47, v64, v123 quad_perm:[1,0,3,2] row_mask:0xf bank_mask:0xf
	v_cvt_pk_bf16_f32 v148, v31, v47
	ds_write_b32 v151, v148 offset:4080
	v_fmac_f32_e32 v30, v116, v31
	v_fmac_f32_e32 v46, v118, v47
	v_fmac_f32_dpp v30, v31, v122 quad_perm:[1,0,3,2] row_mask:0xf bank_mask:0xf
	v_fmac_f32_dpp v46, v47, v123 quad_perm:[1,0,3,2] row_mask:0xf bank_mask:0xf
	v_cvt_pk_bf16_f32 v149, v30, v46
	ds_write_b32 v151, v149 offset:3808
	v_mfma_f32_32x32x16_bf16 v[48:63], v[182:185], v[84:87], 0
	v_fmac_f32_e32 v29, v116, v30
	v_fmac_f32_e32 v45, v118, v46
	v_fmac_f32_dpp v29, v30, v122 quad_perm:[1,0,3,2] row_mask:0xf bank_mask:0xf
	v_fmac_f32_dpp v45, v46, v123 quad_perm:[1,0,3,2] row_mask:0xf bank_mask:0xf
	v_cvt_pk_bf16_f32 v148, v29, v45
	ds_write_b32 v151, v148 offset:3536
	v_fmac_f32_e32 v28, v116, v29
	v_fmac_f32_e32 v44, v118, v45
	v_fmac_f32_dpp v28, v29, v122 quad_perm:[1,0,3,2] row_mask:0xf bank_mask:0xf
	v_fmac_f32_dpp v44, v45, v123 quad_perm:[1,0,3,2] row_mask:0xf bank_mask:0xf
	v_cvt_pk_bf16_f32 v149, v28, v44
	ds_write_b32 v151, v149 offset:3264
	v_mfma_f32_32x32x16_bf16 v[64:79], v[182:185], v[88:91], 0
	v_fmac_f32_e32 v27, v116, v28
	v_fmac_f32_e32 v43, v118, v44
	v_fmac_f32_dpp v27, v28, v122 quad_perm:[1,0,3,2] row_mask:0xf bank_mask:0xf
	v_fmac_f32_dpp v43, v44, v123 quad_perm:[1,0,3,2] row_mask:0xf bank_mask:0xf
	v_cvt_pk_bf16_f32 v148, v27, v43
	ds_write_b32 v151, v148 offset:2992
	v_fmac_f32_e32 v26, v116, v27
	v_fmac_f32_e32 v42, v118, v43
	v_fmac_f32_dpp v26, v27, v122 quad_perm:[1,0,3,2] row_mask:0xf bank_mask:0xf
	v_fmac_f32_dpp v42, v43, v123 quad_perm:[1,0,3,2] row_mask:0xf bank_mask:0xf
	v_cvt_pk_bf16_f32 v149, v26, v42
	ds_write_b32 v151, v149 offset:2720
	v_mfma_f32_32x32x16_bf16 v[48:63], v[186:189], v[92:95], v[48:63]
	v_fmac_f32_e32 v25, v116, v26
	v_fmac_f32_e32 v41, v118, v42
	v_fmac_f32_dpp v25, v26, v122 quad_perm:[1,0,3,2] row_mask:0xf bank_mask:0xf
	v_fmac_f32_dpp v41, v42, v123 quad_perm:[1,0,3,2] row_mask:0xf bank_mask:0xf
	v_cvt_pk_bf16_f32 v148, v25, v41
	ds_write_b32 v151, v148 offset:2448
	v_fmac_f32_e32 v24, v116, v25
	v_fmac_f32_e32 v40, v118, v41
	v_fmac_f32_dpp v24, v25, v122 quad_perm:[1,0,3,2] row_mask:0xf bank_mask:0xf
	v_fmac_f32_dpp v40, v41, v123 quad_perm:[1,0,3,2] row_mask:0xf bank_mask:0xf
	v_cvt_pk_bf16_f32 v149, v24, v40
	ds_write_b32 v151, v149 offset:2176
	v_mfma_f32_32x32x16_bf16 v[64:79], v[186:189], v[96:99], v[64:79]
	v_fmac_f32_e32 v23, v116, v24
	v_fmac_f32_e32 v39, v118, v40
	v_fmac_f32_dpp v23, v24, v122 quad_perm:[1,0,3,2] row_mask:0xf bank_mask:0xf
	v_fmac_f32_dpp v39, v40, v123 quad_perm:[1,0,3,2] row_mask:0xf bank_mask:0xf
	v_cvt_pk_bf16_f32 v148, v23, v39
	ds_write_b32 v151, v148 offset:1904
	v_fmac_f32_e32 v22, v116, v23
	v_fmac_f32_e32 v38, v118, v39
	v_fmac_f32_dpp v22, v23, v122 quad_perm:[1,0,3,2] row_mask:0xf bank_mask:0xf
	v_fmac_f32_dpp v38, v39, v123 quad_perm:[1,0,3,2] row_mask:0xf bank_mask:0xf
	v_cvt_pk_bf16_f32 v149, v22, v38
	ds_write_b32 v151, v149 offset:1632
	v_fmac_f32_e32 v21, v116, v22
	v_fmac_f32_e32 v37, v118, v38
	v_fmac_f32_dpp v21, v22, v122 quad_perm:[1,0,3,2] row_mask:0xf bank_mask:0xf
	v_fmac_f32_dpp v37, v38, v123 quad_perm:[1,0,3,2] row_mask:0xf bank_mask:0xf
	v_cvt_pk_bf16_f32 v148, v21, v37
	ds_write_b32 v151, v148 offset:1360
	v_fmac_f32_e32 v20, v116, v21
	v_fmac_f32_e32 v36, v118, v37
	v_fmac_f32_dpp v20, v21, v122 quad_perm:[1,0,3,2] row_mask:0xf bank_mask:0xf
	v_fmac_f32_dpp v36, v37, v123 quad_perm:[1,0,3,2] row_mask:0xf bank_mask:0xf
	v_cvt_pk_bf16_f32 v149, v20, v36
	ds_write_b32 v151, v149 offset:1088
	v_fmac_f32_e32 v19, v116, v20
	v_fmac_f32_e32 v35, v118, v36
	v_fmac_f32_dpp v19, v20, v122 quad_perm:[1,0,3,2] row_mask:0xf bank_mask:0xf
	v_fmac_f32_dpp v35, v36, v123 quad_perm:[1,0,3,2] row_mask:0xf bank_mask:0xf
	v_cvt_pk_bf16_f32 v148, v19, v35
	ds_write_b32 v151, v148 offset:816
	v_fmac_f32_e32 v18, v116, v19
	v_fmac_f32_e32 v34, v118, v35
	v_fmac_f32_dpp v18, v19, v122 quad_perm:[1,0,3,2] row_mask:0xf bank_mask:0xf
	v_fmac_f32_dpp v34, v35, v123 quad_perm:[1,0,3,2] row_mask:0xf bank_mask:0xf
	v_cvt_pk_bf16_f32 v149, v18, v34
	ds_write_b32 v151, v149 offset:544
	v_fmac_f32_e32 v17, v116, v18
	v_fmac_f32_e32 v33, v118, v34
	v_fmac_f32_dpp v17, v18, v122 quad_perm:[1,0,3,2] row_mask:0xf bank_mask:0xf
	v_fmac_f32_dpp v33, v34, v123 quad_perm:[1,0,3,2] row_mask:0xf bank_mask:0xf
	v_cvt_pk_bf16_f32 v148, v17, v33
	ds_write_b32 v151, v148 offset:272
	v_fmac_f32_e32 v16, v116, v17
	v_fmac_f32_e32 v32, v118, v33
	v_fmac_f32_dpp v16, v17, v122 quad_perm:[1,0,3,2] row_mask:0xf bank_mask:0xf
	v_fmac_f32_dpp v32, v33, v123 quad_perm:[1,0,3,2] row_mask:0xf bank_mask:0xf
	v_cvt_pk_bf16_f32 v149, v16, v32
	ds_write_b32 v151, v149
	v_mov_b32_e32 v120, v16
	v_mov_b32_e32 v121, v32
	s_waitcnt vmcnt(5)
	ds_write_b128 v162, v[168:171] offset:1024
	v_cndmask_b32_e64 v182, 0, v168, s[66:67]
	v_cndmask_b32_e64 v183, 0, v169, s[66:67]
	v_cndmask_b32_e64 v184, 0, v170, s[66:67]
	v_cndmask_b32_e64 v185, 0, v171, s[66:67]
	v_cndmask_b32_e64 v186, 0, v168, s[68:69]
	v_cndmask_b32_e64 v187, 0, v169, s[68:69]
	v_cndmask_b32_e64 v188, 0, v170, s[68:69]
	v_cndmask_b32_e64 v189, 0, v171, s[68:69]
	global_load_dwordx4 v[168:171], v150, s[10:11]
	s_add_u32 s29, s14, 4
	s_cmp_lt_u32 s29, 32
	s_cselect_b32 s29, 1024, 0
	s_sub_u32 s10, s10, s29
	s_subb_u32 s11, s11, 0
	ds_read_b128 v[124:127], v152
	ds_read_b128 v[128:131], v152 offset:64
	ds_read_b128 v[132:135], v152 offset:128
	ds_read_b128 v[136:139], v152 offset:192
	v_mfma_f32_32x32x16_bf16 v[16:31], v[182:185], v[84:87], 0
	v_mfma_f32_32x32x16_bf16 v[32:47], v[182:185], v[88:91], 0
	v_mfma_f32_32x32x16_bf16 v[16:31], v[186:189], v[92:95], v[16:31]
	v_mfma_f32_32x32x16_bf16 v[32:47], v[186:189], v[96:99], v[32:47]
	s_waitcnt lgkmcnt(3)
	v_mfma_f32_16x16x32_bf16 v[140:143], v[100:103], v[124:127], 0
	s_waitcnt lgkmcnt(2)
	v_mfma_f32_16x16x32_bf16 v[140:143], v[104:107], v[128:131], v[140:143]
	s_waitcnt lgkmcnt(1)
	v_mfma_f32_16x16x32_bf16 v[140:143], v[108:111], v[132:135], v[140:143]
	s_waitcnt lgkmcnt(0)
	v_mfma_f32_16x16x32_bf16 v[140:143], v[112:115], v[136:139], v[140:143]
	s_nop 9
	global_store_dwordx4 v153, v[140:143], s[12:13]
	s_nop 1
	ds_read_b128 v[124:127], v152 offset:4352
	ds_read_b128 v[128:131], v152 offset:4416
	ds_read_b128 v[132:135], v152 offset:4480
	ds_read_b128 v[136:139], v152 offset:4544
	s_waitcnt lgkmcnt(3)
	v_mfma_f32_16x16x32_bf16 v[140:143], v[100:103], v[124:127], 0
	s_waitcnt lgkmcnt(2)
	v_mfma_f32_16x16x32_bf16 v[140:143], v[104:107], v[128:131], v[140:143]
	s_waitcnt lgkmcnt(1)
	v_mfma_f32_16x16x32_bf16 v[140:143], v[108:111], v[132:135], v[140:143]
	s_waitcnt lgkmcnt(0)
	v_mfma_f32_16x16x32_bf16 v[140:143], v[112:115], v[136:139], v[140:143]
	s_nop 9
	global_store_dwordx4 v157, v[140:143], s[12:13]
	s_nop 1
	s_sub_u32 s12, s12, 2048
	s_subb_u32 s13, s13, 0
	v_fmac_f32_e32 v63, v116, v120
	v_fmac_f32_e32 v79, v118, v121
	v_fmac_f32_dpp v63, v120, v122 quad_perm:[1,0,3,2] row_mask:0xf bank_mask:0xf
	v_fmac_f32_dpp v79, v121, v123 quad_perm:[1,0,3,2] row_mask:0xf bank_mask:0xf
	v_cvt_pk_bf16_f32 v148, v63, v79
	ds_write_b32 v151, v148 offset:8432
	v_fmac_f32_e32 v62, v116, v63
	v_fmac_f32_e32 v78, v118, v79
	v_fmac_f32_dpp v62, v63, v122 quad_perm:[1,0,3,2] row_mask:0xf bank_mask:0xf
	v_fmac_f32_dpp v78, v79, v123 quad_perm:[1,0,3,2] row_mask:0xf bank_mask:0xf
	v_cvt_pk_bf16_f32 v149, v62, v78
	ds_write_b32 v151, v149 offset:8160
	v_fmac_f32_e32 v61, v116, v62
	v_fmac_f32_e32 v77, v118, v78
	v_fmac_f32_dpp v61, v62, v122 quad_perm:[1,0,3,2] row_mask:0xf bank_mask:0xf
	v_fmac_f32_dpp v77, v78, v123 quad_perm:[1,0,3,2] row_mask:0xf bank_mask:0xf
	v_cvt_pk_bf16_f32 v148, v61, v77
	ds_write_b32 v151, v148 offset:7888
	v_fmac_f32_e32 v60, v116, v61
	v_fmac_f32_e32 v76, v118, v77
	v_fmac_f32_dpp v60, v61, v122 quad_perm:[1,0,3,2] row_mask:0xf bank_mask:0xf
	v_fmac_f32_dpp v76, v77, v123 quad_perm:[1,0,3,2] row_mask:0xf bank_mask:0xf
	v_cvt_pk_bf16_f32 v149, v60, v76
	ds_write_b32 v151, v149 offset:7616
	v_fmac_f32_e32 v59, v116, v60
	v_fmac_f32_e32 v75, v118, v76
	v_fmac_f32_dpp v59, v60, v122 quad_perm:[1,0,3,2] row_mask:0xf bank_mask:0xf
	v_fmac_f32_dpp v75, v76, v123 quad_perm:[1,0,3,2] row_mask:0xf bank_mask:0xf
	v_cvt_pk_bf16_f32 v148, v59, v75
	ds_write_b32 v151, v148 offset:7344
	v_fmac_f32_e32 v58, v116, v59
	v_fmac_f32_e32 v74, v118, v75
	v_fmac_f32_dpp v58, v59, v122 quad_perm:[1,0,3,2] row_mask:0xf bank_mask:0xf
	v_fmac_f32_dpp v74, v75, v123 quad_perm:[1,0,3,2] row_mask:0xf bank_mask:0xf
	v_cvt_pk_bf16_f32 v149, v58, v74
	ds_write_b32 v151, v149 offset:7072
	v_fmac_f32_e32 v57, v116, v58
	v_fmac_f32_e32 v73, v118, v74
	v_fmac_f32_dpp v57, v58, v122 quad_perm:[1,0,3,2] row_mask:0xf bank_mask:0xf
	v_fmac_f32_dpp v73, v74, v123 quad_perm:[1,0,3,2] row_mask:0xf bank_mask:0xf
	v_cvt_pk_bf16_f32 v148, v57, v73
	ds_write_b32 v151, v148 offset:6800
	v_fmac_f32_e32 v56, v116, v57
	v_fmac_f32_e32 v72, v118, v73
	v_fmac_f32_dpp v56, v57, v122 quad_perm:[1,0,3,2] row_mask:0xf bank_mask:0xf
	v_fmac_f32_dpp v72, v73, v123 quad_perm:[1,0,3,2] row_mask:0xf bank_mask:0xf
	v_cvt_pk_bf16_f32 v149, v56, v72
	ds_write_b32 v151, v149 offset:6528
	v_fmac_f32_e32 v55, v116, v56
	v_fmac_f32_e32 v71, v118, v72
	v_fmac_f32_dpp v55, v56, v122 quad_perm:[1,0,3,2] row_mask:0xf bank_mask:0xf
	v_fmac_f32_dpp v71, v72, v123 quad_perm:[1,0,3,2] row_mask:0xf bank_mask:0xf
	v_cvt_pk_bf16_f32 v148, v55, v71
	ds_write_b32 v151, v148 offset:6256
	v_fmac_f32_e32 v54, v116, v55
	v_fmac_f32_e32 v70, v118, v71
	v_fmac_f32_dpp v54, v55, v122 quad_perm:[1,0,3,2] row_mask:0xf bank_mask:0xf
	v_fmac_f32_dpp v70, v71, v123 quad_perm:[1,0,3,2] row_mask:0xf bank_mask:0xf
	v_cvt_pk_bf16_f32 v149, v54, v70
	ds_write_b32 v151, v149 offset:5984
	v_fmac_f32_e32 v53, v116, v54
	v_fmac_f32_e32 v69, v118, v70
	v_fmac_f32_dpp v53, v54, v122 quad_perm:[1,0,3,2] row_mask:0xf bank_mask:0xf
	v_fmac_f32_dpp v69, v70, v123 quad_perm:[1,0,3,2] row_mask:0xf bank_mask:0xf
	v_cvt_pk_bf16_f32 v148, v53, v69
	ds_write_b32 v151, v148 offset:5712
	v_fmac_f32_e32 v52, v116, v53
	v_fmac_f32_e32 v68, v118, v69
	v_fmac_f32_dpp v52, v53, v122 quad_perm:[1,0,3,2] row_mask:0xf bank_mask:0xf
	v_fmac_f32_dpp v68, v69, v123 quad_perm:[1,0,3,2] row_mask:0xf bank_mask:0xf
	v_cvt_pk_bf16_f32 v149, v52, v68
	ds_write_b32 v151, v149 offset:5440
	v_fmac_f32_e32 v51, v116, v52
	v_fmac_f32_e32 v67, v118, v68
	v_fmac_f32_dpp v51, v52, v122 quad_perm:[1,0,3,2] row_mask:0xf bank_mask:0xf
	v_fmac_f32_dpp v67, v68, v123 quad_perm:[1,0,3,2] row_mask:0xf bank_mask:0xf
	v_cvt_pk_bf16_f32 v148, v51, v67
	ds_write_b32 v151, v148 offset:5168
	v_fmac_f32_e32 v50, v116, v51
	v_fmac_f32_e32 v66, v118, v67
	v_fmac_f32_dpp v50, v51, v122 quad_perm:[1,0,3,2] row_mask:0xf bank_mask:0xf
	v_fmac_f32_dpp v66, v67, v123 quad_perm:[1,0,3,2] row_mask:0xf bank_mask:0xf
	v_cvt_pk_bf16_f32 v149, v50, v66
	ds_write_b32 v151, v149 offset:4896
	v_fmac_f32_e32 v49, v116, v50
	v_fmac_f32_e32 v65, v118, v66
	v_fmac_f32_dpp v49, v50, v122 quad_perm:[1,0,3,2] row_mask:0xf bank_mask:0xf
	v_fmac_f32_dpp v65, v66, v123 quad_perm:[1,0,3,2] row_mask:0xf bank_mask:0xf
	v_cvt_pk_bf16_f32 v148, v49, v65
	ds_write_b32 v151, v148 offset:4624
	v_fmac_f32_e32 v48, v116, v49
	v_fmac_f32_e32 v64, v118, v65
	v_fmac_f32_dpp v48, v49, v122 quad_perm:[1,0,3,2] row_mask:0xf bank_mask:0xf
	v_fmac_f32_dpp v64, v65, v123 quad_perm:[1,0,3,2] row_mask:0xf bank_mask:0xf
	v_cvt_pk_bf16_f32 v149, v48, v64
	ds_write_b32 v151, v149 offset:4352
	s_waitcnt vmcnt(5)
	ds_write_b128 v162, v[80:83] offset:512
	v_cndmask_b32_e64 v182, 0, v80, s[66:67]
	v_cndmask_b32_e64 v183, 0, v81, s[66:67]
	v_cndmask_b32_e64 v184, 0, v82, s[66:67]
	v_cndmask_b32_e64 v185, 0, v83, s[66:67]
	v_cndmask_b32_e64 v186, 0, v80, s[68:69]
	v_cndmask_b32_e64 v187, 0, v81, s[68:69]
	v_cndmask_b32_e64 v188, 0, v82, s[68:69]
	v_cndmask_b32_e64 v189, 0, v83, s[68:69]
	global_load_dwordx4 v[80:83], v150, s[10:11] offset:512
	v_fmac_f32_e32 v31, v116, v48
	v_fmac_f32_e32 v47, v118, v64
	v_fmac_f32_dpp v31, v48, v122 quad_perm:[1,0,3,2] row_mask:0xf bank_mask:0xf
	v_fmac_f32_dpp v47, v64, v123 quad_perm:[1,0,3,2] row_mask:0xf bank_mask:0xf
	v_cvt_pk_bf16_f32 v148, v31, v47
	ds_write_b32 v151, v148 offset:4080
	v_fmac_f32_e32 v30, v116, v31
	v_fmac_f32_e32 v46, v118, v47
	v_fmac_f32_dpp v30, v31, v122 quad_perm:[1,0,3,2] row_mask:0xf bank_mask:0xf
	v_fmac_f32_dpp v46, v47, v123 quad_perm:[1,0,3,2] row_mask:0xf bank_mask:0xf
	v_cvt_pk_bf16_f32 v149, v30, v46
	ds_write_b32 v151, v149 offset:3808
	v_mfma_f32_32x32x16_bf16 v[48:63], v[182:185], v[84:87], 0
	v_fmac_f32_e32 v29, v116, v30
	v_fmac_f32_e32 v45, v118, v46
	v_fmac_f32_dpp v29, v30, v122 quad_perm:[1,0,3,2] row_mask:0xf bank_mask:0xf
	v_fmac_f32_dpp v45, v46, v123 quad_perm:[1,0,3,2] row_mask:0xf bank_mask:0xf
	v_cvt_pk_bf16_f32 v148, v29, v45
	ds_write_b32 v151, v148 offset:3536
	v_fmac_f32_e32 v28, v116, v29
	v_fmac_f32_e32 v44, v118, v45
	v_fmac_f32_dpp v28, v29, v122 quad_perm:[1,0,3,2] row_mask:0xf bank_mask:0xf
	v_fmac_f32_dpp v44, v45, v123 quad_perm:[1,0,3,2] row_mask:0xf bank_mask:0xf
	v_cvt_pk_bf16_f32 v149, v28, v44
	ds_write_b32 v151, v149 offset:3264
	v_mfma_f32_32x32x16_bf16 v[64:79], v[182:185], v[88:91], 0
	v_fmac_f32_e32 v27, v116, v28
	v_fmac_f32_e32 v43, v118, v44
	v_fmac_f32_dpp v27, v28, v122 quad_perm:[1,0,3,2] row_mask:0xf bank_mask:0xf
	v_fmac_f32_dpp v43, v44, v123 quad_perm:[1,0,3,2] row_mask:0xf bank_mask:0xf
	v_cvt_pk_bf16_f32 v148, v27, v43
	ds_write_b32 v151, v148 offset:2992
	v_fmac_f32_e32 v26, v116, v27
	v_fmac_f32_e32 v42, v118, v43
	v_fmac_f32_dpp v26, v27, v122 quad_perm:[1,0,3,2] row_mask:0xf bank_mask:0xf
	v_fmac_f32_dpp v42, v43, v123 quad_perm:[1,0,3,2] row_mask:0xf bank_mask:0xf
	v_cvt_pk_bf16_f32 v149, v26, v42
	ds_write_b32 v151, v149 offset:2720
	v_mfma_f32_32x32x16_bf16 v[48:63], v[186:189], v[92:95], v[48:63]
	v_fmac_f32_e32 v25, v116, v26
	v_fmac_f32_e32 v41, v118, v42
	v_fmac_f32_dpp v25, v26, v122 quad_perm:[1,0,3,2] row_mask:0xf bank_mask:0xf
	v_fmac_f32_dpp v41, v42, v123 quad_perm:[1,0,3,2] row_mask:0xf bank_mask:0xf
	v_cvt_pk_bf16_f32 v148, v25, v41
	ds_write_b32 v151, v148 offset:2448
	v_fmac_f32_e32 v24, v116, v25
	v_fmac_f32_e32 v40, v118, v41
	v_fmac_f32_dpp v24, v25, v122 quad_perm:[1,0,3,2] row_mask:0xf bank_mask:0xf
	v_fmac_f32_dpp v40, v41, v123 quad_perm:[1,0,3,2] row_mask:0xf bank_mask:0xf
	v_cvt_pk_bf16_f32 v149, v24, v40
	ds_write_b32 v151, v149 offset:2176
	v_mfma_f32_32x32x16_bf16 v[64:79], v[186:189], v[96:99], v[64:79]
	v_fmac_f32_e32 v23, v116, v24
	v_fmac_f32_e32 v39, v118, v40
	v_fmac_f32_dpp v23, v24, v122 quad_perm:[1,0,3,2] row_mask:0xf bank_mask:0xf
	v_fmac_f32_dpp v39, v40, v123 quad_perm:[1,0,3,2] row_mask:0xf bank_mask:0xf
	v_cvt_pk_bf16_f32 v148, v23, v39
	ds_write_b32 v151, v148 offset:1904
	v_fmac_f32_e32 v22, v116, v23
	v_fmac_f32_e32 v38, v118, v39
	v_fmac_f32_dpp v22, v23, v122 quad_perm:[1,0,3,2] row_mask:0xf bank_mask:0xf
	v_fmac_f32_dpp v38, v39, v123 quad_perm:[1,0,3,2] row_mask:0xf bank_mask:0xf
	v_cvt_pk_bf16_f32 v149, v22, v38
	ds_write_b32 v151, v149 offset:1632
	v_fmac_f32_e32 v21, v116, v22
	v_fmac_f32_e32 v37, v118, v38
	v_fmac_f32_dpp v21, v22, v122 quad_perm:[1,0,3,2] row_mask:0xf bank_mask:0xf
	v_fmac_f32_dpp v37, v38, v123 quad_perm:[1,0,3,2] row_mask:0xf bank_mask:0xf
	v_cvt_pk_bf16_f32 v148, v21, v37
	ds_write_b32 v151, v148 offset:1360
	v_fmac_f32_e32 v20, v116, v21
	v_fmac_f32_e32 v36, v118, v37
	v_fmac_f32_dpp v20, v21, v122 quad_perm:[1,0,3,2] row_mask:0xf bank_mask:0xf
	v_fmac_f32_dpp v36, v37, v123 quad_perm:[1,0,3,2] row_mask:0xf bank_mask:0xf
	v_cvt_pk_bf16_f32 v149, v20, v36
	ds_write_b32 v151, v149 offset:1088
	v_fmac_f32_e32 v19, v116, v20
	v_fmac_f32_e32 v35, v118, v36
	v_fmac_f32_dpp v19, v20, v122 quad_perm:[1,0,3,2] row_mask:0xf bank_mask:0xf
	v_fmac_f32_dpp v35, v36, v123 quad_perm:[1,0,3,2] row_mask:0xf bank_mask:0xf
	v_cvt_pk_bf16_f32 v148, v19, v35
	ds_write_b32 v151, v148 offset:816
	v_fmac_f32_e32 v18, v116, v19
	v_fmac_f32_e32 v34, v118, v35
	v_fmac_f32_dpp v18, v19, v122 quad_perm:[1,0,3,2] row_mask:0xf bank_mask:0xf
	v_fmac_f32_dpp v34, v35, v123 quad_perm:[1,0,3,2] row_mask:0xf bank_mask:0xf
	v_cvt_pk_bf16_f32 v149, v18, v34
	ds_write_b32 v151, v149 offset:544
	v_fmac_f32_e32 v17, v116, v18
	v_fmac_f32_e32 v33, v118, v34
	v_fmac_f32_dpp v17, v18, v122 quad_perm:[1,0,3,2] row_mask:0xf bank_mask:0xf
	v_fmac_f32_dpp v33, v34, v123 quad_perm:[1,0,3,2] row_mask:0xf bank_mask:0xf
	v_cvt_pk_bf16_f32 v148, v17, v33
	ds_write_b32 v151, v148 offset:272
	v_fmac_f32_e32 v16, v116, v17
	v_fmac_f32_e32 v32, v118, v33
	v_fmac_f32_dpp v16, v17, v122 quad_perm:[1,0,3,2] row_mask:0xf bank_mask:0xf
	v_fmac_f32_dpp v32, v33, v123 quad_perm:[1,0,3,2] row_mask:0xf bank_mask:0xf
	v_cvt_pk_bf16_f32 v149, v16, v32
	ds_write_b32 v151, v149
	v_mov_b32_e32 v120, v16
	v_mov_b32_e32 v121, v32
	s_waitcnt vmcnt(5)
	ds_write_b128 v162, v[194:197]
	v_cndmask_b32_e64 v182, 0, v194, s[66:67]
	v_cndmask_b32_e64 v183, 0, v195, s[66:67]
	v_cndmask_b32_e64 v184, 0, v196, s[66:67]
	v_cndmask_b32_e64 v185, 0, v197, s[66:67]
	v_cndmask_b32_e64 v186, 0, v194, s[68:69]
	v_cndmask_b32_e64 v187, 0, v195, s[68:69]
	v_cndmask_b32_e64 v188, 0, v196, s[68:69]
	v_cndmask_b32_e64 v189, 0, v197, s[68:69]
	global_load_dwordx4 v[194:197], v150, s[10:11]
	s_add_u32 s29, s14, 5
	s_cmp_lt_u32 s29, 32
	s_cselect_b32 s29, 1024, 0
	s_sub_u32 s10, s10, s29
	s_subb_u32 s11, s11, 0
	ds_read_b128 v[124:127], v152
	ds_read_b128 v[128:131], v152 offset:64
	ds_read_b128 v[132:135], v152 offset:128
	ds_read_b128 v[136:139], v152 offset:192
	v_mfma_f32_32x32x16_bf16 v[16:31], v[182:185], v[84:87], 0
	v_mfma_f32_32x32x16_bf16 v[32:47], v[182:185], v[88:91], 0
	v_mfma_f32_32x32x16_bf16 v[16:31], v[186:189], v[92:95], v[16:31]
	v_mfma_f32_32x32x16_bf16 v[32:47], v[186:189], v[96:99], v[32:47]
	s_waitcnt lgkmcnt(3)
	v_mfma_f32_16x16x32_bf16 v[140:143], v[100:103], v[124:127], 0
	s_waitcnt lgkmcnt(2)
	v_mfma_f32_16x16x32_bf16 v[140:143], v[104:107], v[128:131], v[140:143]
	s_waitcnt lgkmcnt(1)
	v_mfma_f32_16x16x32_bf16 v[140:143], v[108:111], v[132:135], v[140:143]
	s_waitcnt lgkmcnt(0)
	v_mfma_f32_16x16x32_bf16 v[140:143], v[112:115], v[136:139], v[140:143]
	s_nop 9
	global_store_dwordx4 v153, v[140:143], s[12:13]
	s_nop 1
	ds_read_b128 v[124:127], v152 offset:4352
	ds_read_b128 v[128:131], v152 offset:4416
	ds_read_b128 v[132:135], v152 offset:4480
	ds_read_b128 v[136:139], v152 offset:4544
	s_waitcnt lgkmcnt(3)
	v_mfma_f32_16x16x32_bf16 v[140:143], v[100:103], v[124:127], 0
	s_waitcnt lgkmcnt(2)
	v_mfma_f32_16x16x32_bf16 v[140:143], v[104:107], v[128:131], v[140:143]
	s_waitcnt lgkmcnt(1)
	v_mfma_f32_16x16x32_bf16 v[140:143], v[108:111], v[132:135], v[140:143]
	s_waitcnt lgkmcnt(0)
	v_mfma_f32_16x16x32_bf16 v[140:143], v[112:115], v[136:139], v[140:143]
	s_nop 9
	global_store_dwordx4 v157, v[140:143], s[12:13]
	s_nop 1
	s_sub_u32 s12, s12, 2048
	s_subb_u32 s13, s13, 0
	s_add_u32 s14, s14, 2
	s_cmp_lt_u32 s14, 16
	s_cbranch_scc1 .Lssm_tileA_d1m0
	s_waitcnt vmcnt(0) lgkmcnt(0)
	s_lshr_b32 s21, s89, 1
	s_lshl_b32 s21, s21, 2
	s_add_u32 s37, s21, 0x21000
	v_mov_b32_e32 v182, s37
	v_mov_b32_e32 v183, 1
	v_cmp_eq_u32_e32 vcc, 0, v191
	s_and_saveexec_b64 s[0:1], vcc
	ds_add_u32 v182, v183
	s_mov_b64 exec, s[0:1]
	s_waitcnt lgkmcnt(0)
	s_mov_b32 s38, 0

.Lssm_spin_done_d1m0:
	s_mov_b64 s[42:43], s[6:7]
	s_sub_u32 s42, s42, 2048
	s_subb_u32 s43, s43, 0
	s_lshl_b32 s31, s25, 11
	s_lshl_b32 s29, s24, 5
	s_add_u32 s31, s31, s29
	s_add_u32 s31, s31, 344915968
	s_add_u32 s12, s62, s31
	s_addc_u32 s13, s63, 0
	global_load_dwordx4 v[6:9], v153, s[42:43]
	global_load_dwordx4 v[10:13], v157, s[42:43]
	s_sub_u32 s42, s42, 2048
	s_subb_u32 s43, s43, 0
	s_waitcnt vmcnt(0)
.Lssm_tileB_d1m0:
	global_load_dwordx4 v[172:175], v153, s[42:43]
	global_load_dwordx4 v[176:179], v157, s[42:43]
	s_sub_u32 s42, s42, 2048
	s_subb_u32 s43, s43, 0
	v_fmac_f32_e32 v63, v116, v120
	v_fmac_f32_e32 v79, v118, v121
	v_fmac_f32_dpp v63, v120, v122 quad_perm:[1,0,3,2] row_mask:0xf bank_mask:0xf
	v_fmac_f32_dpp v79, v121, v123 quad_perm:[1,0,3,2] row_mask:0xf bank_mask:0xf
	v_cvt_pk_bf16_f32 v148, v63, v79
	ds_write_b32 v151, v148 offset:8432
	v_fmac_f32_e32 v62, v116, v63
	v_fmac_f32_e32 v78, v118, v79
	v_fmac_f32_dpp v62, v63, v122 quad_perm:[1,0,3,2] row_mask:0xf bank_mask:0xf
	v_fmac_f32_dpp v78, v79, v123 quad_perm:[1,0,3,2] row_mask:0xf bank_mask:0xf
	v_cvt_pk_bf16_f32 v149, v62, v78
	ds_write_b32 v151, v149 offset:8160
	v_fmac_f32_e32 v61, v116, v62
	v_fmac_f32_e32 v77, v118, v78
	v_fmac_f32_dpp v61, v62, v122 quad_perm:[1,0,3,2] row_mask:0xf bank_mask:0xf
	v_fmac_f32_dpp v77, v78, v123 quad_perm:[1,0,3,2] row_mask:0xf bank_mask:0xf
	v_cvt_pk_bf16_f32 v148, v61, v77
	ds_write_b32 v151, v148 offset:7888
	v_fmac_f32_e32 v60, v116, v61
	v_fmac_f32_e32 v76, v118, v77
	v_fmac_f32_dpp v60, v61, v122 quad_perm:[1,0,3,2] row_mask:0xf bank_mask:0xf
	v_fmac_f32_dpp v76, v77, v123 quad_perm:[1,0,3,2] row_mask:0xf bank_mask:0xf
	v_cvt_pk_bf16_f32 v149, v60, v76
	ds_write_b32 v151, v149 offset:7616
	v_fmac_f32_e32 v59, v116, v60
	v_fmac_f32_e32 v75, v118, v76
	v_fmac_f32_dpp v59, v60, v122 quad_perm:[1,0,3,2] row_mask:0xf bank_mask:0xf
	v_fmac_f32_dpp v75, v76, v123 quad_perm:[1,0,3,2] row_mask:0xf bank_mask:0xf
	v_cvt_pk_bf16_f32 v148, v59, v75
	ds_write_b32 v151, v148 offset:7344
	v_fmac_f32_e32 v58, v116, v59
	v_fmac_f32_e32 v74, v118, v75
	v_fmac_f32_dpp v58, v59, v122 quad_perm:[1,0,3,2] row_mask:0xf bank_mask:0xf
	v_fmac_f32_dpp v74, v75, v123 quad_perm:[1,0,3,2] row_mask:0xf bank_mask:0xf
	v_cvt_pk_bf16_f32 v149, v58, v74
	ds_write_b32 v151, v149 offset:7072
	v_fmac_f32_e32 v57, v116, v58
	v_fmac_f32_e32 v73, v118, v74
	v_fmac_f32_dpp v57, v58, v122 quad_perm:[1,0,3,2] row_mask:0xf bank_mask:0xf
	v_fmac_f32_dpp v73, v74, v123 quad_perm:[1,0,3,2] row_mask:0xf bank_mask:0xf
	v_cvt_pk_bf16_f32 v148, v57, v73
	ds_write_b32 v151, v148 offset:6800
	v_fmac_f32_e32 v56, v116, v57
	v_fmac_f32_e32 v72, v118, v73
	v_fmac_f32_dpp v56, v57, v122 quad_perm:[1,0,3,2] row_mask:0xf bank_mask:0xf
	v_fmac_f32_dpp v72, v73, v123 quad_perm:[1,0,3,2] row_mask:0xf bank_mask:0xf
	v_cvt_pk_bf16_f32 v149, v56, v72
	ds_write_b32 v151, v149 offset:6528
	v_fmac_f32_e32 v55, v116, v56
	v_fmac_f32_e32 v71, v118, v72
	v_fmac_f32_dpp v55, v56, v122 quad_perm:[1,0,3,2] row_mask:0xf bank_mask:0xf
	v_fmac_f32_dpp v71, v72, v123 quad_perm:[1,0,3,2] row_mask:0xf bank_mask:0xf
	v_cvt_pk_bf16_f32 v148, v55, v71
	ds_write_b32 v151, v148 offset:6256
	v_fmac_f32_e32 v54, v116, v55
	v_fmac_f32_e32 v70, v118, v71
	v_fmac_f32_dpp v54, v55, v122 quad_perm:[1,0,3,2] row_mask:0xf bank_mask:0xf
	v_fmac_f32_dpp v70, v71, v123 quad_perm:[1,0,3,2] row_mask:0xf bank_mask:0xf
	v_cvt_pk_bf16_f32 v149, v54, v70
	ds_write_b32 v151, v149 offset:5984
	v_fmac_f32_e32 v53, v116, v54
	v_fmac_f32_e32 v69, v118, v70
	v_fmac_f32_dpp v53, v54, v122 quad_perm:[1,0,3,2] row_mask:0xf bank_mask:0xf
	v_fmac_f32_dpp v69, v70, v123 quad_perm:[1,0,3,2] row_mask:0xf bank_mask:0xf
	v_cvt_pk_bf16_f32 v148, v53, v69
	ds_write_b32 v151, v148 offset:5712
	v_fmac_f32_e32 v52, v116, v53
	v_fmac_f32_e32 v68, v118, v69
	v_fmac_f32_dpp v52, v53, v122 quad_perm:[1,0,3,2] row_mask:0xf bank_mask:0xf
	v_fmac_f32_dpp v68, v69, v123 quad_perm:[1,0,3,2] row_mask:0xf bank_mask:0xf
	v_cvt_pk_bf16_f32 v149, v52, v68
	ds_write_b32 v151, v149 offset:5440
	v_fmac_f32_e32 v51, v116, v52
	v_fmac_f32_e32 v67, v118, v68
	v_fmac_f32_dpp v51, v52, v122 quad_perm:[1,0,3,2] row_mask:0xf bank_mask:0xf
	v_fmac_f32_dpp v67, v68, v123 quad_perm:[1,0,3,2] row_mask:0xf bank_mask:0xf
	v_cvt_pk_bf16_f32 v148, v51, v67
	ds_write_b32 v151, v148 offset:5168
	v_fmac_f32_e32 v50, v116, v51
	v_fmac_f32_e32 v66, v118, v67
	v_fmac_f32_dpp v50, v51, v122 quad_perm:[1,0,3,2] row_mask:0xf bank_mask:0xf
	v_fmac_f32_dpp v66, v67, v123 quad_perm:[1,0,3,2] row_mask:0xf bank_mask:0xf
	v_cvt_pk_bf16_f32 v149, v50, v66
	ds_write_b32 v151, v149 offset:4896
	v_fmac_f32_e32 v49, v116, v50
	v_fmac_f32_e32 v65, v118, v66
	v_fmac_f32_dpp v49, v50, v122 quad_perm:[1,0,3,2] row_mask:0xf bank_mask:0xf
	v_fmac_f32_dpp v65, v66, v123 quad_perm:[1,0,3,2] row_mask:0xf bank_mask:0xf
	v_cvt_pk_bf16_f32 v148, v49, v65
	ds_write_b32 v151, v148 offset:4624
	v_fmac_f32_e32 v48, v116, v49
	v_fmac_f32_e32 v64, v118, v65
	v_fmac_f32_dpp v48, v49, v122 quad_perm:[1,0,3,2] row_mask:0xf bank_mask:0xf
	v_fmac_f32_dpp v64, v65, v123 quad_perm:[1,0,3,2] row_mask:0xf bank_mask:0xf
	v_cvt_pk_bf16_f32 v149, v48, v64
	ds_write_b32 v151, v149 offset:4352
	s_waitcnt vmcnt(11)
	ds_write_b128 v162, v[144:147] offset:1536
	v_cndmask_b32_e64 v182, 0, v144, s[66:67]
	v_cndmask_b32_e64 v183, 0, v145, s[66:67]
	v_cndmask_b32_e64 v184, 0, v146, s[66:67]
	v_cndmask_b32_e64 v185, 0, v147, s[66:67]
	v_cndmask_b32_e64 v186, 0, v144, s[68:69]
	v_cndmask_b32_e64 v187, 0, v145, s[68:69]
	v_cndmask_b32_e64 v188, 0, v146, s[68:69]
	v_cndmask_b32_e64 v189, 0, v147, s[68:69]
	global_load_dwordx4 v[144:147], v150, s[10:11] offset:512
	v_fmac_f32_e32 v31, v116, v48
	v_fmac_f32_e32 v47, v118, v64
	v_fmac_f32_dpp v31, v48, v122 quad_perm:[1,0,3,2] row_mask:0xf bank_mask:0xf
	v_fmac_f32_dpp v47, v64, v123 quad_perm:[1,0,3,2] row_mask:0xf bank_mask:0xf
	v_cvt_pk_bf16_f32 v148, v31, v47
	ds_write_b32 v151, v148 offset:4080
	v_fmac_f32_e32 v30, v116, v31
	v_fmac_f32_e32 v46, v118, v47
	v_fmac_f32_dpp v30, v31, v122 quad_perm:[1,0,3,2] row_mask:0xf bank_mask:0xf
	v_fmac_f32_dpp v46, v47, v123 quad_perm:[1,0,3,2] row_mask:0xf bank_mask:0xf
	v_cvt_pk_bf16_f32 v149, v30, v46
	ds_write_b32 v151, v149 offset:3808
	v_mfma_f32_32x32x16_bf16 v[48:63], v[182:185], v[84:87], 0
	v_fmac_f32_e32 v29, v116, v30
	v_fmac_f32_e32 v45, v118, v46
	v_fmac_f32_dpp v29, v30, v122 quad_perm:[1,0,3,2] row_mask:0xf bank_mask:0xf
	v_fmac_f32_dpp v45, v46, v123 quad_perm:[1,0,3,2] row_mask:0xf bank_mask:0xf
	v_cvt_pk_bf16_f32 v148, v29, v45
	ds_write_b32 v151, v148 offset:3536
	v_fmac_f32_e32 v28, v116, v29
	v_fmac_f32_e32 v44, v118, v45
	v_fmac_f32_dpp v28, v29, v122 quad_perm:[1,0,3,2] row_mask:0xf bank_mask:0xf
	v_fmac_f32_dpp v44, v45, v123 quad_perm:[1,0,3,2] row_mask:0xf bank_mask:0xf
	v_cvt_pk_bf16_f32 v149, v28, v44
	ds_write_b32 v151, v149 offset:3264
	v_mfma_f32_32x32x16_bf16 v[64:79], v[182:185], v[88:91], 0
	v_fmac_f32_e32 v27, v116, v28
	v_fmac_f32_e32 v43, v118, v44
	v_fmac_f32_dpp v27, v28, v122 quad_perm:[1,0,3,2] row_mask:0xf bank_mask:0xf
	v_fmac_f32_dpp v43, v44, v123 quad_perm:[1,0,3,2] row_mask:0xf bank_mask:0xf
	v_cvt_pk_bf16_f32 v148, v27, v43
	ds_write_b32 v151, v148 offset:2992
	v_fmac_f32_e32 v26, v116, v27
	v_fmac_f32_e32 v42, v118, v43
	v_fmac_f32_dpp v26, v27, v122 quad_perm:[1,0,3,2] row_mask:0xf bank_mask:0xf
	v_fmac_f32_dpp v42, v43, v123 quad_perm:[1,0,3,2] row_mask:0xf bank_mask:0xf
	v_cvt_pk_bf16_f32 v149, v26, v42
	ds_write_b32 v151, v149 offset:2720
	v_mfma_f32_32x32x16_bf16 v[48:63], v[186:189], v[92:95], v[48:63]
	v_fmac_f32_e32 v25, v116, v26
	v_fmac_f32_e32 v41, v118, v42
	v_fmac_f32_dpp v25, v26, v122 quad_perm:[1,0,3,2] row_mask:0xf bank_mask:0xf
	v_fmac_f32_dpp v41, v42, v123 quad_perm:[1,0,3,2] row_mask:0xf bank_mask:0xf
	v_cvt_pk_bf16_f32 v148, v25, v41
	ds_write_b32 v151, v148 offset:2448
	v_fmac_f32_e32 v24, v116, v25
	v_fmac_f32_e32 v40, v118, v41
	v_fmac_f32_dpp v24, v25, v122 quad_perm:[1,0,3,2] row_mask:0xf bank_mask:0xf
	v_fmac_f32_dpp v40, v41, v123 quad_perm:[1,0,3,2] row_mask:0xf bank_mask:0xf
	v_cvt_pk_bf16_f32 v149, v24, v40
	ds_write_b32 v151, v149 offset:2176
	v_mfma_f32_32x32x16_bf16 v[64:79], v[186:189], v[96:99], v[64:79]
	v_fmac_f32_e32 v23, v116, v24
	v_fmac_f32_e32 v39, v118, v40
	v_fmac_f32_dpp v23, v24, v122 quad_perm:[1,0,3,2] row_mask:0xf bank_mask:0xf
	v_fmac_f32_dpp v39, v40, v123 quad_perm:[1,0,3,2] row_mask:0xf bank_mask:0xf
	v_cvt_pk_bf16_f32 v148, v23, v39
	ds_write_b32 v151, v148 offset:1904
	v_fmac_f32_e32 v22, v116, v23
	v_fmac_f32_e32 v38, v118, v39
	v_fmac_f32_dpp v22, v23, v122 quad_perm:[1,0,3,2] row_mask:0xf bank_mask:0xf
	v_fmac_f32_dpp v38, v39, v123 quad_perm:[1,0,3,2] row_mask:0xf bank_mask:0xf
	v_cvt_pk_bf16_f32 v149, v22, v38
	ds_write_b32 v151, v149 offset:1632
	v_fmac_f32_e32 v21, v116, v22
	v_fmac_f32_e32 v37, v118, v38
	v_fmac_f32_dpp v21, v22, v122 quad_perm:[1,0,3,2] row_mask:0xf bank_mask:0xf
	v_fmac_f32_dpp v37, v38, v123 quad_perm:[1,0,3,2] row_mask:0xf bank_mask:0xf
	v_cvt_pk_bf16_f32 v148, v21, v37
	ds_write_b32 v151, v148 offset:1360
	v_fmac_f32_e32 v20, v116, v21
	v_fmac_f32_e32 v36, v118, v37
	v_fmac_f32_dpp v20, v21, v122 quad_perm:[1,0,3,2] row_mask:0xf bank_mask:0xf
	v_fmac_f32_dpp v36, v37, v123 quad_perm:[1,0,3,2] row_mask:0xf bank_mask:0xf
	v_cvt_pk_bf16_f32 v149, v20, v36
	ds_write_b32 v151, v149 offset:1088
	v_fmac_f32_e32 v19, v116, v20
	v_fmac_f32_e32 v35, v118, v36
	v_fmac_f32_dpp v19, v20, v122 quad_perm:[1,0,3,2] row_mask:0xf bank_mask:0xf
	v_fmac_f32_dpp v35, v36, v123 quad_perm:[1,0,3,2] row_mask:0xf bank_mask:0xf
	v_cvt_pk_bf16_f32 v148, v19, v35
	ds_write_b32 v151, v148 offset:816
	v_fmac_f32_e32 v18, v116, v19
	v_fmac_f32_e32 v34, v118, v35
	v_fmac_f32_dpp v18, v19, v122 quad_perm:[1,0,3,2] row_mask:0xf bank_mask:0xf
	v_fmac_f32_dpp v34, v35, v123 quad_perm:[1,0,3,2] row_mask:0xf bank_mask:0xf
	v_cvt_pk_bf16_f32 v149, v18, v34
	ds_write_b32 v151, v149 offset:544
	v_fmac_f32_e32 v17, v116, v18
	v_fmac_f32_e32 v33, v118, v34
	v_fmac_f32_dpp v17, v18, v122 quad_perm:[1,0,3,2] row_mask:0xf bank_mask:0xf
	v_fmac_f32_dpp v33, v34, v123 quad_perm:[1,0,3,2] row_mask:0xf bank_mask:0xf
	v_cvt_pk_bf16_f32 v148, v17, v33
	ds_write_b32 v151, v148 offset:272
	v_fmac_f32_e32 v16, v116, v17
	v_fmac_f32_e32 v32, v118, v33
	v_fmac_f32_dpp v16, v17, v122 quad_perm:[1,0,3,2] row_mask:0xf bank_mask:0xf
	v_fmac_f32_dpp v32, v33, v123 quad_perm:[1,0,3,2] row_mask:0xf bank_mask:0xf
	v_cvt_pk_bf16_f32 v149, v16, v32
	ds_write_b32 v151, v149
	v_mov_b32_e32 v120, v16
	v_mov_b32_e32 v121, v32
	s_waitcnt vmcnt(11)
	ds_write_b128 v162, v[168:171] offset:1024
	v_cndmask_b32_e64 v182, 0, v168, s[66:67]
	v_cndmask_b32_e64 v183, 0, v169, s[66:67]
	v_cndmask_b32_e64 v184, 0, v170, s[66:67]
	v_cndmask_b32_e64 v185, 0, v171, s[66:67]
	v_cndmask_b32_e64 v186, 0, v168, s[68:69]
	v_cndmask_b32_e64 v187, 0, v169, s[68:69]
	v_cndmask_b32_e64 v188, 0, v170, s[68:69]
	v_cndmask_b32_e64 v189, 0, v171, s[68:69]
	global_load_dwordx4 v[168:171], v150, s[10:11]
	s_add_u32 s29, s14, 4
	s_cmp_lt_u32 s29, 32
	s_cselect_b32 s29, 1024, 0
	s_sub_u32 s10, s10, s29
	s_subb_u32 s11, s11, 0
	ds_read_b128 v[124:127], v152
	ds_read_b128 v[128:131], v152 offset:64
	ds_read_b128 v[132:135], v152 offset:128
	ds_read_b128 v[136:139], v152 offset:192
	ds_read_b64 v[160:161], v163
	v_mfma_f32_32x32x16_bf16 v[16:31], v[182:185], v[84:87], 0
	v_mfma_f32_32x32x16_bf16 v[32:47], v[182:185], v[88:91], 0
	v_mfma_f32_32x32x16_bf16 v[16:31], v[186:189], v[92:95], v[16:31]
	v_mfma_f32_32x32x16_bf16 v[32:47], v[186:189], v[96:99], v[32:47]
	s_waitcnt lgkmcnt(4)
	v_mfma_f32_16x16x32_bf16 v[140:143], v[100:103], v[124:127], 0
	s_waitcnt lgkmcnt(3)
	v_mfma_f32_16x16x32_bf16 v[140:143], v[104:107], v[128:131], v[140:143]
	s_waitcnt lgkmcnt(2)
	v_mfma_f32_16x16x32_bf16 v[140:143], v[108:111], v[132:135], v[140:143]
	s_waitcnt lgkmcnt(1)
	v_mfma_f32_16x16x32_bf16 v[140:143], v[112:115], v[136:139], v[140:143]
	s_nop 9
	s_waitcnt vmcnt(9) lgkmcnt(0)
	v_add_f32_e32 v182, v6, v140
	v_add_f32_e32 v183, v7, v141
	v_add_f32_e32 v184, v8, v142
	v_add_f32_e32 v185, v9, v143
	v_lshlrev_b32_e32 v186, 16, v160
	v_and_b32_e32 v187, 0xffff0000, v160
	v_lshlrev_b32_e32 v188, 16, v161
	v_and_b32_e32 v189, 0xffff0000, v161
	v_fmac_f32_e32 v182, v164, v186
	v_fmac_f32_e32 v183, v165, v187
	v_fmac_f32_e32 v184, v166, v188
	v_fmac_f32_e32 v185, v167, v189
	v_mul_f32_e32 v186, 0x3d372713, v182
	v_mul_f32_e32 v187, 0x3d372713, v183
	v_mul_f32_e32 v188, 0x3d372713, v184
	v_mul_f32_e32 v189, 0x3d372713, v185
	v_mul_f32_e32 v186, v182, v186
	v_mul_f32_e32 v187, v183, v187
	v_mul_f32_e32 v188, v184, v188
	v_mul_f32_e32 v189, v185, v189
	v_fma_f32 v186, v182, v186, v182
	v_fma_f32 v187, v183, v187, v183
	v_fma_f32 v188, v184, v188, v184
	v_fma_f32 v189, v185, v189, v185
	v_mul_f32_e32 v186, 0xbfcc422a, v186
	v_mul_f32_e32 v187, 0xbfcc422a, v187
	v_mul_f32_e32 v188, 0xbfcc422a, v188
	v_mul_f32_e32 v189, 0xbfcc422a, v189
	v_mul_f32_e32 v186, 0x3fb8aa3b, v186
	v_mul_f32_e32 v187, 0x3fb8aa3b, v187
	v_mul_f32_e32 v188, 0x3fb8aa3b, v188
	v_mul_f32_e32 v189, 0x3fb8aa3b, v189
	v_exp_f32_e32 v186, v186
	v_exp_f32_e32 v187, v187
	v_exp_f32_e32 v188, v188
	v_exp_f32_e32 v189, v189
	v_add_f32_e32 v186, 1.0, v186
	v_add_f32_e32 v187, 1.0, v187
	v_add_f32_e32 v188, 1.0, v188
	v_add_f32_e32 v189, 1.0, v189
	v_rcp_f32_e32 v186, v186
	v_rcp_f32_e32 v187, v187
	v_rcp_f32_e32 v188, v188
	v_rcp_f32_e32 v189, v189
	v_mul_f32_e32 v182, v182, v186
	v_mul_f32_e32 v183, v183, v187
	v_mul_f32_e32 v184, v184, v188
	v_mul_f32_e32 v185, v185, v189
	v_cvt_pk_bf16_f32 v148, v182, v183
	v_cvt_pk_bf16_f32 v149, v184, v185
	global_store_dwordx2 v156, v[148:149], s[12:13]
	ds_read_b128 v[124:127], v152 offset:4352
	ds_read_b128 v[128:131], v152 offset:4416
	ds_read_b128 v[132:135], v152 offset:4480
	ds_read_b128 v[136:139], v152 offset:4544
	ds_read_b64 v[160:161], v163 offset:512
	s_waitcnt lgkmcnt(4)
	v_mfma_f32_16x16x32_bf16 v[140:143], v[100:103], v[124:127], 0
	s_waitcnt lgkmcnt(3)
	v_mfma_f32_16x16x32_bf16 v[140:143], v[104:107], v[128:131], v[140:143]
	s_waitcnt lgkmcnt(2)
	v_mfma_f32_16x16x32_bf16 v[140:143], v[108:111], v[132:135], v[140:143]
	s_waitcnt lgkmcnt(1)
	v_mfma_f32_16x16x32_bf16 v[140:143], v[112:115], v[136:139], v[140:143]
	s_nop 9
	s_waitcnt vmcnt(9) lgkmcnt(0)
	v_add_f32_e32 v182, v10, v140
	v_add_f32_e32 v183, v11, v141
	v_add_f32_e32 v184, v12, v142
	v_add_f32_e32 v185, v13, v143
	v_lshlrev_b32_e32 v186, 16, v160
	v_and_b32_e32 v187, 0xffff0000, v160
	v_lshlrev_b32_e32 v188, 16, v161
	v_and_b32_e32 v189, 0xffff0000, v161
	v_fmac_f32_e32 v182, v164, v186
	v_fmac_f32_e32 v183, v165, v187
	v_fmac_f32_e32 v184, v166, v188
	v_fmac_f32_e32 v185, v167, v189
	v_mul_f32_e32 v186, 0x3d372713, v182
	v_mul_f32_e32 v187, 0x3d372713, v183
	v_mul_f32_e32 v188, 0x3d372713, v184
	v_mul_f32_e32 v189, 0x3d372713, v185
	v_mul_f32_e32 v186, v182, v186
	v_mul_f32_e32 v187, v183, v187
	v_mul_f32_e32 v188, v184, v188
	v_mul_f32_e32 v189, v185, v189
	v_fma_f32 v186, v182, v186, v182
	v_fma_f32 v187, v183, v187, v183
	v_fma_f32 v188, v184, v188, v184
	v_fma_f32 v189, v185, v189, v185
	v_mul_f32_e32 v186, 0xbfcc422a, v186
	v_mul_f32_e32 v187, 0xbfcc422a, v187
	v_mul_f32_e32 v188, 0xbfcc422a, v188
	v_mul_f32_e32 v189, 0xbfcc422a, v189
	v_mul_f32_e32 v186, 0x3fb8aa3b, v186
	v_mul_f32_e32 v187, 0x3fb8aa3b, v187
	v_mul_f32_e32 v188, 0x3fb8aa3b, v188
	v_mul_f32_e32 v189, 0x3fb8aa3b, v189
	v_exp_f32_e32 v186, v186
	v_exp_f32_e32 v187, v187
	v_exp_f32_e32 v188, v188
	v_exp_f32_e32 v189, v189
	v_add_f32_e32 v186, 1.0, v186
	v_add_f32_e32 v187, 1.0, v187
	v_add_f32_e32 v188, 1.0, v188
	v_add_f32_e32 v189, 1.0, v189
	v_rcp_f32_e32 v186, v186
	v_rcp_f32_e32 v187, v187
	v_rcp_f32_e32 v188, v188
	v_rcp_f32_e32 v189, v189
	v_mul_f32_e32 v182, v182, v186
	v_mul_f32_e32 v183, v183, v187
	v_mul_f32_e32 v184, v184, v188
	v_mul_f32_e32 v185, v185, v189
	v_cvt_pk_bf16_f32 v148, v182, v183
	v_cvt_pk_bf16_f32 v149, v184, v185
	global_store_dwordx2 v159, v[148:149], s[12:13]
	s_sub_u32 s12, s12, 65536
	s_subb_u32 s13, s13, 0
	global_load_dwordx4 v[6:9], v153, s[42:43]
	global_load_dwordx4 v[10:13], v157, s[42:43]
	s_sub_u32 s42, s42, 2048
	s_subb_u32 s43, s43, 0
	v_fmac_f32_e32 v63, v116, v120
	v_fmac_f32_e32 v79, v118, v121
	v_fmac_f32_dpp v63, v120, v122 quad_perm:[1,0,3,2] row_mask:0xf bank_mask:0xf
	v_fmac_f32_dpp v79, v121, v123 quad_perm:[1,0,3,2] row_mask:0xf bank_mask:0xf
	v_cvt_pk_bf16_f32 v148, v63, v79
	ds_write_b32 v151, v148 offset:8432
	v_fmac_f32_e32 v62, v116, v63
	v_fmac_f32_e32 v78, v118, v79
	v_fmac_f32_dpp v62, v63, v122 quad_perm:[1,0,3,2] row_mask:0xf bank_mask:0xf
	v_fmac_f32_dpp v78, v79, v123 quad_perm:[1,0,3,2] row_mask:0xf bank_mask:0xf
	v_cvt_pk_bf16_f32 v149, v62, v78
	ds_write_b32 v151, v149 offset:8160
	v_fmac_f32_e32 v61, v116, v62
	v_fmac_f32_e32 v77, v118, v78
	v_fmac_f32_dpp v61, v62, v122 quad_perm:[1,0,3,2] row_mask:0xf bank_mask:0xf
	v_fmac_f32_dpp v77, v78, v123 quad_perm:[1,0,3,2] row_mask:0xf bank_mask:0xf
	v_cvt_pk_bf16_f32 v148, v61, v77
	ds_write_b32 v151, v148 offset:7888
	v_fmac_f32_e32 v60, v116, v61
	v_fmac_f32_e32 v76, v118, v77
	v_fmac_f32_dpp v60, v61, v122 quad_perm:[1,0,3,2] row_mask:0xf bank_mask:0xf
	v_fmac_f32_dpp v76, v77, v123 quad_perm:[1,0,3,2] row_mask:0xf bank_mask:0xf
	v_cvt_pk_bf16_f32 v149, v60, v76
	ds_write_b32 v151, v149 offset:7616
	v_fmac_f32_e32 v59, v116, v60
	v_fmac_f32_e32 v75, v118, v76
	v_fmac_f32_dpp v59, v60, v122 quad_perm:[1,0,3,2] row_mask:0xf bank_mask:0xf
	v_fmac_f32_dpp v75, v76, v123 quad_perm:[1,0,3,2] row_mask:0xf bank_mask:0xf
	v_cvt_pk_bf16_f32 v148, v59, v75
	ds_write_b32 v151, v148 offset:7344
	v_fmac_f32_e32 v58, v116, v59
	v_fmac_f32_e32 v74, v118, v75
	v_fmac_f32_dpp v58, v59, v122 quad_perm:[1,0,3,2] row_mask:0xf bank_mask:0xf
	v_fmac_f32_dpp v74, v75, v123 quad_perm:[1,0,3,2] row_mask:0xf bank_mask:0xf
	v_cvt_pk_bf16_f32 v149, v58, v74
	ds_write_b32 v151, v149 offset:7072
	v_fmac_f32_e32 v57, v116, v58
	v_fmac_f32_e32 v73, v118, v74
	v_fmac_f32_dpp v57, v58, v122 quad_perm:[1,0,3,2] row_mask:0xf bank_mask:0xf
	v_fmac_f32_dpp v73, v74, v123 quad_perm:[1,0,3,2] row_mask:0xf bank_mask:0xf
	v_cvt_pk_bf16_f32 v148, v57, v73
	ds_write_b32 v151, v148 offset:6800
	v_fmac_f32_e32 v56, v116, v57
	v_fmac_f32_e32 v72, v118, v73
	v_fmac_f32_dpp v56, v57, v122 quad_perm:[1,0,3,2] row_mask:0xf bank_mask:0xf
	v_fmac_f32_dpp v72, v73, v123 quad_perm:[1,0,3,2] row_mask:0xf bank_mask:0xf
	v_cvt_pk_bf16_f32 v149, v56, v72
	ds_write_b32 v151, v149 offset:6528
	v_fmac_f32_e32 v55, v116, v56
	v_fmac_f32_e32 v71, v118, v72
	v_fmac_f32_dpp v55, v56, v122 quad_perm:[1,0,3,2] row_mask:0xf bank_mask:0xf
	v_fmac_f32_dpp v71, v72, v123 quad_perm:[1,0,3,2] row_mask:0xf bank_mask:0xf
	v_cvt_pk_bf16_f32 v148, v55, v71
	ds_write_b32 v151, v148 offset:6256
	v_fmac_f32_e32 v54, v116, v55
	v_fmac_f32_e32 v70, v118, v71
	v_fmac_f32_dpp v54, v55, v122 quad_perm:[1,0,3,2] row_mask:0xf bank_mask:0xf
	v_fmac_f32_dpp v70, v71, v123 quad_perm:[1,0,3,2] row_mask:0xf bank_mask:0xf
	v_cvt_pk_bf16_f32 v149, v54, v70
	ds_write_b32 v151, v149 offset:5984
	v_fmac_f32_e32 v53, v116, v54
	v_fmac_f32_e32 v69, v118, v70
	v_fmac_f32_dpp v53, v54, v122 quad_perm:[1,0,3,2] row_mask:0xf bank_mask:0xf
	v_fmac_f32_dpp v69, v70, v123 quad_perm:[1,0,3,2] row_mask:0xf bank_mask:0xf
	v_cvt_pk_bf16_f32 v148, v53, v69
	ds_write_b32 v151, v148 offset:5712
	v_fmac_f32_e32 v52, v116, v53
	v_fmac_f32_e32 v68, v118, v69
	v_fmac_f32_dpp v52, v53, v122 quad_perm:[1,0,3,2] row_mask:0xf bank_mask:0xf
	v_fmac_f32_dpp v68, v69, v123 quad_perm:[1,0,3,2] row_mask:0xf bank_mask:0xf
	v_cvt_pk_bf16_f32 v149, v52, v68
	ds_write_b32 v151, v149 offset:5440
	v_fmac_f32_e32 v51, v116, v52
	v_fmac_f32_e32 v67, v118, v68
	v_fmac_f32_dpp v51, v52, v122 quad_perm:[1,0,3,2] row_mask:0xf bank_mask:0xf
	v_fmac_f32_dpp v67, v68, v123 quad_perm:[1,0,3,2] row_mask:0xf bank_mask:0xf
	v_cvt_pk_bf16_f32 v148, v51, v67
	ds_write_b32 v151, v148 offset:5168
	v_fmac_f32_e32 v50, v116, v51
	v_fmac_f32_e32 v66, v118, v67
	v_fmac_f32_dpp v50, v51, v122 quad_perm:[1,0,3,2] row_mask:0xf bank_mask:0xf
	v_fmac_f32_dpp v66, v67, v123 quad_perm:[1,0,3,2] row_mask:0xf bank_mask:0xf
	v_cvt_pk_bf16_f32 v149, v50, v66
	ds_write_b32 v151, v149 offset:4896
	v_fmac_f32_e32 v49, v116, v50
	v_fmac_f32_e32 v65, v118, v66
	v_fmac_f32_dpp v49, v50, v122 quad_perm:[1,0,3,2] row_mask:0xf bank_mask:0xf
	v_fmac_f32_dpp v65, v66, v123 quad_perm:[1,0,3,2] row_mask:0xf bank_mask:0xf
	v_cvt_pk_bf16_f32 v148, v49, v65
	ds_write_b32 v151, v148 offset:4624
	v_fmac_f32_e32 v48, v116, v49
	v_fmac_f32_e32 v64, v118, v65
	v_fmac_f32_dpp v48, v49, v122 quad_perm:[1,0,3,2] row_mask:0xf bank_mask:0xf
	v_fmac_f32_dpp v64, v65, v123 quad_perm:[1,0,3,2] row_mask:0xf bank_mask:0xf
	v_cvt_pk_bf16_f32 v149, v48, v64
	ds_write_b32 v151, v149 offset:4352
	s_waitcnt vmcnt(11)
	ds_write_b128 v162, v[80:83] offset:512
	v_cndmask_b32_e64 v182, 0, v80, s[66:67]
	v_cndmask_b32_e64 v183, 0, v81, s[66:67]
	v_cndmask_b32_e64 v184, 0, v82, s[66:67]
	v_cndmask_b32_e64 v185, 0, v83, s[66:67]
	v_cndmask_b32_e64 v186, 0, v80, s[68:69]
	v_cndmask_b32_e64 v187, 0, v81, s[68:69]
	v_cndmask_b32_e64 v188, 0, v82, s[68:69]
	v_cndmask_b32_e64 v189, 0, v83, s[68:69]
	global_load_dwordx4 v[80:83], v150, s[10:11] offset:512
	v_fmac_f32_e32 v31, v116, v48
	v_fmac_f32_e32 v47, v118, v64
	v_fmac_f32_dpp v31, v48, v122 quad_perm:[1,0,3,2] row_mask:0xf bank_mask:0xf
	v_fmac_f32_dpp v47, v64, v123 quad_perm:[1,0,3,2] row_mask:0xf bank_mask:0xf
	v_cvt_pk_bf16_f32 v148, v31, v47
	ds_write_b32 v151, v148 offset:4080
	v_fmac_f32_e32 v30, v116, v31
	v_fmac_f32_e32 v46, v118, v47
	v_fmac_f32_dpp v30, v31, v122 quad_perm:[1,0,3,2] row_mask:0xf bank_mask:0xf
	v_fmac_f32_dpp v46, v47, v123 quad_perm:[1,0,3,2] row_mask:0xf bank_mask:0xf
	v_cvt_pk_bf16_f32 v149, v30, v46
	ds_write_b32 v151, v149 offset:3808
	v_mfma_f32_32x32x16_bf16 v[48:63], v[182:185], v[84:87], 0
	v_fmac_f32_e32 v29, v116, v30
	v_fmac_f32_e32 v45, v118, v46
	v_fmac_f32_dpp v29, v30, v122 quad_perm:[1,0,3,2] row_mask:0xf bank_mask:0xf
	v_fmac_f32_dpp v45, v46, v123 quad_perm:[1,0,3,2] row_mask:0xf bank_mask:0xf
	v_cvt_pk_bf16_f32 v148, v29, v45
	ds_write_b32 v151, v148 offset:3536
	v_fmac_f32_e32 v28, v116, v29
	v_fmac_f32_e32 v44, v118, v45
	v_fmac_f32_dpp v28, v29, v122 quad_perm:[1,0,3,2] row_mask:0xf bank_mask:0xf
	v_fmac_f32_dpp v44, v45, v123 quad_perm:[1,0,3,2] row_mask:0xf bank_mask:0xf
	v_cvt_pk_bf16_f32 v149, v28, v44
	ds_write_b32 v151, v149 offset:3264
	v_mfma_f32_32x32x16_bf16 v[64:79], v[182:185], v[88:91], 0
	v_fmac_f32_e32 v27, v116, v28
	v_fmac_f32_e32 v43, v118, v44
	v_fmac_f32_dpp v27, v28, v122 quad_perm:[1,0,3,2] row_mask:0xf bank_mask:0xf
	v_fmac_f32_dpp v43, v44, v123 quad_perm:[1,0,3,2] row_mask:0xf bank_mask:0xf
	v_cvt_pk_bf16_f32 v148, v27, v43
	ds_write_b32 v151, v148 offset:2992
	v_fmac_f32_e32 v26, v116, v27
	v_fmac_f32_e32 v42, v118, v43
	v_fmac_f32_dpp v26, v27, v122 quad_perm:[1,0,3,2] row_mask:0xf bank_mask:0xf
	v_fmac_f32_dpp v42, v43, v123 quad_perm:[1,0,3,2] row_mask:0xf bank_mask:0xf
	v_cvt_pk_bf16_f32 v149, v26, v42
	ds_write_b32 v151, v149 offset:2720
	v_mfma_f32_32x32x16_bf16 v[48:63], v[186:189], v[92:95], v[48:63]
	v_fmac_f32_e32 v25, v116, v26
	v_fmac_f32_e32 v41, v118, v42
	v_fmac_f32_dpp v25, v26, v122 quad_perm:[1,0,3,2] row_mask:0xf bank_mask:0xf
	v_fmac_f32_dpp v41, v42, v123 quad_perm:[1,0,3,2] row_mask:0xf bank_mask:0xf
	v_cvt_pk_bf16_f32 v148, v25, v41
	ds_write_b32 v151, v148 offset:2448
	v_fmac_f32_e32 v24, v116, v25
	v_fmac_f32_e32 v40, v118, v41
	v_fmac_f32_dpp v24, v25, v122 quad_perm:[1,0,3,2] row_mask:0xf bank_mask:0xf
	v_fmac_f32_dpp v40, v41, v123 quad_perm:[1,0,3,2] row_mask:0xf bank_mask:0xf
	v_cvt_pk_bf16_f32 v149, v24, v40
	ds_write_b32 v151, v149 offset:2176
	v_mfma_f32_32x32x16_bf16 v[64:79], v[186:189], v[96:99], v[64:79]
	v_fmac_f32_e32 v23, v116, v24
	v_fmac_f32_e32 v39, v118, v40
	v_fmac_f32_dpp v23, v24, v122 quad_perm:[1,0,3,2] row_mask:0xf bank_mask:0xf
	v_fmac_f32_dpp v39, v40, v123 quad_perm:[1,0,3,2] row_mask:0xf bank_mask:0xf
	v_cvt_pk_bf16_f32 v148, v23, v39
	ds_write_b32 v151, v148 offset:1904
	v_fmac_f32_e32 v22, v116, v23
	v_fmac_f32_e32 v38, v118, v39
	v_fmac_f32_dpp v22, v23, v122 quad_perm:[1,0,3,2] row_mask:0xf bank_mask:0xf
	v_fmac_f32_dpp v38, v39, v123 quad_perm:[1,0,3,2] row_mask:0xf bank_mask:0xf
	v_cvt_pk_bf16_f32 v149, v22, v38
	ds_write_b32 v151, v149 offset:1632
	v_fmac_f32_e32 v21, v116, v22
	v_fmac_f32_e32 v37, v118, v38
	v_fmac_f32_dpp v21, v22, v122 quad_perm:[1,0,3,2] row_mask:0xf bank_mask:0xf
	v_fmac_f32_dpp v37, v38, v123 quad_perm:[1,0,3,2] row_mask:0xf bank_mask:0xf
	v_cvt_pk_bf16_f32 v148, v21, v37
	ds_write_b32 v151, v148 offset:1360
	v_fmac_f32_e32 v20, v116, v21
	v_fmac_f32_e32 v36, v118, v37
	v_fmac_f32_dpp v20, v21, v122 quad_perm:[1,0,3,2] row_mask:0xf bank_mask:0xf
	v_fmac_f32_dpp v36, v37, v123 quad_perm:[1,0,3,2] row_mask:0xf bank_mask:0xf
	v_cvt_pk_bf16_f32 v149, v20, v36
	ds_write_b32 v151, v149 offset:1088
	v_fmac_f32_e32 v19, v116, v20
	v_fmac_f32_e32 v35, v118, v36
	v_fmac_f32_dpp v19, v20, v122 quad_perm:[1,0,3,2] row_mask:0xf bank_mask:0xf
	v_fmac_f32_dpp v35, v36, v123 quad_perm:[1,0,3,2] row_mask:0xf bank_mask:0xf
	v_cvt_pk_bf16_f32 v148, v19, v35
	ds_write_b32 v151, v148 offset:816
	v_fmac_f32_e32 v18, v116, v19
	v_fmac_f32_e32 v34, v118, v35
	v_fmac_f32_dpp v18, v19, v122 quad_perm:[1,0,3,2] row_mask:0xf bank_mask:0xf
	v_fmac_f32_dpp v34, v35, v123 quad_perm:[1,0,3,2] row_mask:0xf bank_mask:0xf
	v_cvt_pk_bf16_f32 v149, v18, v34
	ds_write_b32 v151, v149 offset:544
	v_fmac_f32_e32 v17, v116, v18
	v_fmac_f32_e32 v33, v118, v34
	v_fmac_f32_dpp v17, v18, v122 quad_perm:[1,0,3,2] row_mask:0xf bank_mask:0xf
	v_fmac_f32_dpp v33, v34, v123 quad_perm:[1,0,3,2] row_mask:0xf bank_mask:0xf
	v_cvt_pk_bf16_f32 v148, v17, v33
	ds_write_b32 v151, v148 offset:272
	v_fmac_f32_e32 v16, v116, v17
	v_fmac_f32_e32 v32, v118, v33
	v_fmac_f32_dpp v16, v17, v122 quad_perm:[1,0,3,2] row_mask:0xf bank_mask:0xf
	v_fmac_f32_dpp v32, v33, v123 quad_perm:[1,0,3,2] row_mask:0xf bank_mask:0xf
	v_cvt_pk_bf16_f32 v149, v16, v32
	ds_write_b32 v151, v149
	v_mov_b32_e32 v120, v16
	v_mov_b32_e32 v121, v32
	s_waitcnt vmcnt(11)
	ds_write_b128 v162, v[194:197]
	v_cndmask_b32_e64 v182, 0, v194, s[66:67]
	v_cndmask_b32_e64 v183, 0, v195, s[66:67]
	v_cndmask_b32_e64 v184, 0, v196, s[66:67]
	v_cndmask_b32_e64 v185, 0, v197, s[66:67]
	v_cndmask_b32_e64 v186, 0, v194, s[68:69]
	v_cndmask_b32_e64 v187, 0, v195, s[68:69]
	v_cndmask_b32_e64 v188, 0, v196, s[68:69]
	v_cndmask_b32_e64 v189, 0, v197, s[68:69]
	global_load_dwordx4 v[194:197], v150, s[10:11]
	s_add_u32 s29, s14, 5
	s_cmp_lt_u32 s29, 32
	s_cselect_b32 s29, 1024, 0
	s_sub_u32 s10, s10, s29
	s_subb_u32 s11, s11, 0
	ds_read_b128 v[124:127], v152
	ds_read_b128 v[128:131], v152 offset:64
	ds_read_b128 v[132:135], v152 offset:128
	ds_read_b128 v[136:139], v152 offset:192
	ds_read_b64 v[160:161], v163 offset:1024
	v_mfma_f32_32x32x16_bf16 v[16:31], v[182:185], v[84:87], 0
	v_mfma_f32_32x32x16_bf16 v[32:47], v[182:185], v[88:91], 0
	v_mfma_f32_32x32x16_bf16 v[16:31], v[186:189], v[92:95], v[16:31]
	v_mfma_f32_32x32x16_bf16 v[32:47], v[186:189], v[96:99], v[32:47]
	s_waitcnt lgkmcnt(4)
	v_mfma_f32_16x16x32_bf16 v[140:143], v[100:103], v[124:127], 0
	s_waitcnt lgkmcnt(3)
	v_mfma_f32_16x16x32_bf16 v[140:143], v[104:107], v[128:131], v[140:143]
	s_waitcnt lgkmcnt(2)
	v_mfma_f32_16x16x32_bf16 v[140:143], v[108:111], v[132:135], v[140:143]
	s_waitcnt lgkmcnt(1)
	v_mfma_f32_16x16x32_bf16 v[140:143], v[112:115], v[136:139], v[140:143]
	s_nop 9
	s_waitcnt vmcnt(9) lgkmcnt(0)
	v_add_f32_e32 v182, v172, v140
	v_add_f32_e32 v183, v173, v141
	v_add_f32_e32 v184, v174, v142
	v_add_f32_e32 v185, v175, v143
	v_lshlrev_b32_e32 v186, 16, v160
	v_and_b32_e32 v187, 0xffff0000, v160
	v_lshlrev_b32_e32 v188, 16, v161
	v_and_b32_e32 v189, 0xffff0000, v161
	v_fmac_f32_e32 v182, v164, v186
	v_fmac_f32_e32 v183, v165, v187
	v_fmac_f32_e32 v184, v166, v188
	v_fmac_f32_e32 v185, v167, v189
	v_mul_f32_e32 v186, 0x3d372713, v182
	v_mul_f32_e32 v187, 0x3d372713, v183
	v_mul_f32_e32 v188, 0x3d372713, v184
	v_mul_f32_e32 v189, 0x3d372713, v185
	v_mul_f32_e32 v186, v182, v186
	v_mul_f32_e32 v187, v183, v187
	v_mul_f32_e32 v188, v184, v188
	v_mul_f32_e32 v189, v185, v189
	v_fma_f32 v186, v182, v186, v182
	v_fma_f32 v187, v183, v187, v183
	v_fma_f32 v188, v184, v188, v184
	v_fma_f32 v189, v185, v189, v185
	v_mul_f32_e32 v186, 0xbfcc422a, v186
	v_mul_f32_e32 v187, 0xbfcc422a, v187
	v_mul_f32_e32 v188, 0xbfcc422a, v188
	v_mul_f32_e32 v189, 0xbfcc422a, v189
	v_mul_f32_e32 v186, 0x3fb8aa3b, v186
	v_mul_f32_e32 v187, 0x3fb8aa3b, v187
	v_mul_f32_e32 v188, 0x3fb8aa3b, v188
	v_mul_f32_e32 v189, 0x3fb8aa3b, v189
	v_exp_f32_e32 v186, v186
	v_exp_f32_e32 v187, v187
	v_exp_f32_e32 v188, v188
	v_exp_f32_e32 v189, v189
	v_add_f32_e32 v186, 1.0, v186
	v_add_f32_e32 v187, 1.0, v187
	v_add_f32_e32 v188, 1.0, v188
	v_add_f32_e32 v189, 1.0, v189
	v_rcp_f32_e32 v186, v186
	v_rcp_f32_e32 v187, v187
	v_rcp_f32_e32 v188, v188
	v_rcp_f32_e32 v189, v189
	v_mul_f32_e32 v182, v182, v186
	v_mul_f32_e32 v183, v183, v187
	v_mul_f32_e32 v184, v184, v188
	v_mul_f32_e32 v185, v185, v189
	v_cvt_pk_bf16_f32 v148, v182, v183
	v_cvt_pk_bf16_f32 v149, v184, v185
	global_store_dwordx2 v156, v[148:149], s[12:13]
	ds_read_b128 v[124:127], v152 offset:4352
	ds_read_b128 v[128:131], v152 offset:4416
	ds_read_b128 v[132:135], v152 offset:4480
	ds_read_b128 v[136:139], v152 offset:4544
	ds_read_b64 v[160:161], v163 offset:1536
	s_waitcnt lgkmcnt(4)
	v_mfma_f32_16x16x32_bf16 v[140:143], v[100:103], v[124:127], 0
	s_waitcnt lgkmcnt(3)
	v_mfma_f32_16x16x32_bf16 v[140:143], v[104:107], v[128:131], v[140:143]
	s_waitcnt lgkmcnt(2)
	v_mfma_f32_16x16x32_bf16 v[140:143], v[108:111], v[132:135], v[140:143]
	s_waitcnt lgkmcnt(1)
	v_mfma_f32_16x16x32_bf16 v[140:143], v[112:115], v[136:139], v[140:143]
	s_nop 9
	s_waitcnt vmcnt(9) lgkmcnt(0)
	v_add_f32_e32 v182, v176, v140
	v_add_f32_e32 v183, v177, v141
	v_add_f32_e32 v184, v178, v142
	v_add_f32_e32 v185, v179, v143
	v_lshlrev_b32_e32 v186, 16, v160
	v_and_b32_e32 v187, 0xffff0000, v160
	v_lshlrev_b32_e32 v188, 16, v161
	v_and_b32_e32 v189, 0xffff0000, v161
	v_fmac_f32_e32 v182, v164, v186
	v_fmac_f32_e32 v183, v165, v187
	v_fmac_f32_e32 v184, v166, v188
	v_fmac_f32_e32 v185, v167, v189
	v_mul_f32_e32 v186, 0x3d372713, v182
	v_mul_f32_e32 v187, 0x3d372713, v183
	v_mul_f32_e32 v188, 0x3d372713, v184
	v_mul_f32_e32 v189, 0x3d372713, v185
	v_mul_f32_e32 v186, v182, v186
	v_mul_f32_e32 v187, v183, v187
	v_mul_f32_e32 v188, v184, v188
	v_mul_f32_e32 v189, v185, v189
	v_fma_f32 v186, v182, v186, v182
	v_fma_f32 v187, v183, v187, v183
	v_fma_f32 v188, v184, v188, v184
	v_fma_f32 v189, v185, v189, v185
	v_mul_f32_e32 v186, 0xbfcc422a, v186
	v_mul_f32_e32 v187, 0xbfcc422a, v187
	v_mul_f32_e32 v188, 0xbfcc422a, v188
	v_mul_f32_e32 v189, 0xbfcc422a, v189
	v_mul_f32_e32 v186, 0x3fb8aa3b, v186
	v_mul_f32_e32 v187, 0x3fb8aa3b, v187
	v_mul_f32_e32 v188, 0x3fb8aa3b, v188
	v_mul_f32_e32 v189, 0x3fb8aa3b, v189
	v_exp_f32_e32 v186, v186
	v_exp_f32_e32 v187, v187
	v_exp_f32_e32 v188, v188
	v_exp_f32_e32 v189, v189
	v_add_f32_e32 v186, 1.0, v186
	v_add_f32_e32 v187, 1.0, v187
	v_add_f32_e32 v188, 1.0, v188
	v_add_f32_e32 v189, 1.0, v189
	v_rcp_f32_e32 v186, v186
	v_rcp_f32_e32 v187, v187
	v_rcp_f32_e32 v188, v188
	v_rcp_f32_e32 v189, v189
	v_mul_f32_e32 v182, v182, v186
	v_mul_f32_e32 v183, v183, v187
	v_mul_f32_e32 v184, v184, v188
	v_mul_f32_e32 v185, v185, v189
	v_cvt_pk_bf16_f32 v148, v182, v183
	v_cvt_pk_bf16_f32 v149, v184, v185
	global_store_dwordx2 v159, v[148:149], s[12:13]
	s_sub_u32 s12, s12, 65536
	s_subb_u32 s13, s13, 0
	s_add_u32 s14, s14, 2
	s_cmp_lt_u32 s14, 32
	s_cbranch_scc1 .Lssm_tileB_d1m0
	s_waitcnt vmcnt(0) lgkmcnt(0)

.Lssm_ctx_loop:
	s_lshl_b32 s22, s2, 3
	s_sub_u32 s21, s89, 4
	s_add_u32 s22, s22, s21
	s_lshl_b32 s21, s27, 2
	s_add_u32 s22, s22, s21
	s_lshr_b32 s23, s22, 6
	s_and_b32 s24, s22, 63
	s_lshl_b32 s25, s23, 8
	s_add_u32 s28, s24, 0
	s_lshl_b32 s29, s28, 13
	s_add_u32 s29, s29, 0x200000
	s_add_u32 s10, s62, s29
	s_addc_u32 s11, s63, 0
	global_load_dwordx4 v[84:87], v177, s[10:11]
	global_load_dwordx4 v[88:91], v177, s[10:11] offset:2048
	s_add_u32 s12, s10, 0x1000
	s_addc_u32 s13, s11, 0
	global_load_dwordx4 v[92:95], v177, s[12:13]
	global_load_dwordx4 v[96:99], v177, s[12:13] offset:2048
	s_lshl_b32 s29, s28, 12
	s_add_u32 s29, s29, 0x300000
	s_add_u32 s16, s62, s29
	s_addc_u32 s17, s63, 0
	global_load_dwordx2 v[20:21], v178, s[16:17]
	global_load_dwordx2 v[22:23], v178, s[16:17] offset:1024
	global_load_dwordx2 v[24:25], v178, s[16:17] offset:512
	global_load_dwordx2 v[26:27], v178, s[16:17] offset:1536
	global_load_dwordx2 v[28:29], v178, s[16:17] offset:2048
	global_load_dwordx2 v[30:31], v178, s[16:17] offset:3072
	global_load_dwordx2 v[32:33], v178, s[16:17] offset:2560
	global_load_dwordx2 v[34:35], v178, s[16:17] offset:3584
	s_lshl_b32 s29, s28, 9
	s_add_u32 s29, s29, 0x100000
	s_add_u32 s18, s62, s29
	s_addc_u32 s19, s63, 0
	global_load_dwordx2 v[116:117], v179, s[18:19]
	global_load_dwordx2 v[118:119], v179, s[18:19] offset:128
	s_lshl_b32 s30, s23, 1
	s_lshl_b32 s30, s30, 15
	s_lshl_b32 s31, s24, 8
	s_add_u32 s30, s30, s31
	v_mov_b32_e32 v120, 0
	v_mov_b32_e32 v121, 0
	s_lshl_b32 s31, s25, 5
	s_lshl_b32 s29, s24, 19
	s_add_u32 s31, s31, s29
	s_add_u32 s31, s31, 0x16800000
	s_add_u32 s4, s62, s31
	s_addc_u32 s5, s63, 0
	s_add_u32 s34, s4, 0
	s_addc_u32 s35, s5, 0
	global_load_dwordx4 v[80:83], v150, s[34:35]
	global_load_dwordx4 v[194:197], v150, s[34:35] offset:512
	s_mov_b64 s[10:11], s[34:35]
	s_add_u32 s10, s10, 1024
	s_addc_u32 s11, s11, 0
	global_load_dwordx4 v[144:147], v150, s[10:11]
	global_load_dwordx4 v[6:9], v150, s[10:11] offset:512
	s_add_u32 s10, s10, 1024
	s_addc_u32 s11, s11, 0
	s_mov_b32 s36, 0
	s_mov_b32 s14, 0
	s_mov_b32 s40, 0xffff0000
	s_waitcnt vmcnt(0)
	v_and_b32_e32 v182, 0xffff, v20
	v_lshrrev_b32_e32 v183, 16, v20
	v_and_b32_e32 v184, 0xffff, v21
	v_lshrrev_b32_e32 v185, 16, v21
	v_lshl_or_b32 v100, v22, 16, v182
	v_and_or_b32 v101, v22, s40, v183
	v_lshl_or_b32 v102, v23, 16, v184
	v_and_or_b32 v103, v23, s40, v185
	v_and_b32_e32 v182, 0xffff, v24
	v_lshrrev_b32_e32 v183, 16, v24
	v_and_b32_e32 v184, 0xffff, v25
	v_lshrrev_b32_e32 v185, 16, v25
	v_lshl_or_b32 v104, v26, 16, v182
	v_and_or_b32 v105, v26, s40, v183
	v_lshl_or_b32 v106, v27, 16, v184
	v_and_or_b32 v107, v27, s40, v185
	v_and_b32_e32 v182, 0xffff, v28
	v_lshrrev_b32_e32 v183, 16, v28
	v_and_b32_e32 v184, 0xffff, v29
	v_lshrrev_b32_e32 v185, 16, v29
	v_lshl_or_b32 v108, v30, 16, v182
	v_and_or_b32 v109, v30, s40, v183
	v_lshl_or_b32 v110, v31, 16, v184
	v_and_or_b32 v111, v31, s40, v185
	v_and_b32_e32 v182, 0xffff, v32
	v_lshrrev_b32_e32 v183, 16, v32
	v_and_b32_e32 v184, 0xffff, v33
	v_lshrrev_b32_e32 v185, 16, v33
	v_lshl_or_b32 v112, v34, 16, v182
	v_and_or_b32 v113, v34, s40, v183
	v_lshl_or_b32 v114, v35, 16, v184
	v_and_or_b32 v115, v35, s40, v185
	v_cmp_eq_u32_e32 vcc, 1, v174
	v_xor_b32_e32 v182, 0x80000000, v117
	v_xor_b32_e32 v183, 0x80000000, v119
	s_nop 1
	v_cndmask_b32_e32 v122, v182, v117, vcc
	v_cndmask_b32_e32 v123, v183, v119, vcc
	v_cndmask_b32_e64 v182, 0, v80, s[66:67]
	v_cndmask_b32_e64 v183, 0, v81, s[66:67]
	v_cndmask_b32_e64 v184, 0, v82, s[66:67]
	v_cndmask_b32_e64 v185, 0, v83, s[66:67]
	v_cndmask_b32_e64 v186, 0, v80, s[68:69]
	v_cndmask_b32_e64 v187, 0, v81, s[68:69]
	v_cndmask_b32_e64 v188, 0, v82, s[68:69]
	v_cndmask_b32_e64 v189, 0, v83, s[68:69]
	v_cndmask_b32_e64 v124, 0, v194, s[66:67]
	v_cndmask_b32_e64 v125, 0, v195, s[66:67]
	v_cndmask_b32_e64 v126, 0, v196, s[66:67]
	v_cndmask_b32_e64 v127, 0, v197, s[66:67]
	v_cndmask_b32_e64 v128, 0, v194, s[68:69]
	v_cndmask_b32_e64 v129, 0, v195, s[68:69]
	v_cndmask_b32_e64 v130, 0, v196, s[68:69]
	v_cndmask_b32_e64 v131, 0, v197, s[68:69]
	v_mfma_f32_32x32x16_bf16 v[16:31], v[182:185], v[84:87], 0
	v_mfma_f32_32x32x16_bf16 v[32:47], v[182:185], v[88:91], 0
	v_mfma_f32_32x32x16_bf16 v[16:31], v[186:189], v[92:95], v[16:31]
	v_mfma_f32_32x32x16_bf16 v[32:47], v[186:189], v[96:99], v[32:47]
	v_mfma_f32_32x32x16_bf16 v[48:63], v[124:127], v[84:87], 0
	v_mfma_f32_32x32x16_bf16 v[64:79], v[124:127], v[88:91], 0
	v_mfma_f32_32x32x16_bf16 v[48:63], v[128:131], v[92:95], v[48:63]
	v_mfma_f32_32x32x16_bf16 v[64:79], v[128:131], v[96:99], v[64:79]
	global_load_dwordx4 v[80:83], v150, s[10:11]
	global_load_dwordx4 v[194:197], v150, s[10:11] offset:512
	s_add_u32 s10, s10, 1024
	s_addc_u32 s11, s11, 0
	s_nop 7
.Lssm_tile_d0m1:
	v_add_u32_e32 v171, s36, v155
	v_fmac_f32_e32 v16, v116, v120
	v_fmac_f32_e32 v32, v118, v121
	v_fmac_f32_dpp v16, v120, v122 quad_perm:[1,0,3,2] row_mask:0xf bank_mask:0xf
	v_fmac_f32_dpp v32, v121, v123 quad_perm:[1,0,3,2] row_mask:0xf bank_mask:0xf
	v_cvt_pk_bf16_f32 v148, v16, v32
	ds_write_b32 v151, v148
	v_fmac_f32_e32 v17, v116, v16
	v_fmac_f32_e32 v33, v118, v32
	v_fmac_f32_dpp v17, v16, v122 quad_perm:[1,0,3,2] row_mask:0xf bank_mask:0xf
	v_fmac_f32_dpp v33, v32, v123 quad_perm:[1,0,3,2] row_mask:0xf bank_mask:0xf
	v_cvt_pk_bf16_f32 v149, v17, v33
	ds_write_b32 v151, v149 offset:272
	v_fmac_f32_e32 v18, v116, v17
	v_fmac_f32_e32 v34, v118, v33
	v_fmac_f32_dpp v18, v17, v122 quad_perm:[1,0,3,2] row_mask:0xf bank_mask:0xf
	v_fmac_f32_dpp v34, v33, v123 quad_perm:[1,0,3,2] row_mask:0xf bank_mask:0xf
	v_cvt_pk_bf16_f32 v148, v18, v34
	ds_write_b32 v151, v148 offset:544
	v_fmac_f32_e32 v19, v116, v18
	v_fmac_f32_e32 v35, v118, v34
	v_fmac_f32_dpp v19, v18, v122 quad_perm:[1,0,3,2] row_mask:0xf bank_mask:0xf
	v_fmac_f32_dpp v35, v34, v123 quad_perm:[1,0,3,2] row_mask:0xf bank_mask:0xf
	v_cvt_pk_bf16_f32 v149, v19, v35
	ds_write_b32 v151, v149 offset:816
	v_fmac_f32_e32 v20, v116, v19
	v_fmac_f32_e32 v36, v118, v35
	v_fmac_f32_dpp v20, v19, v122 quad_perm:[1,0,3,2] row_mask:0xf bank_mask:0xf
	v_fmac_f32_dpp v36, v35, v123 quad_perm:[1,0,3,2] row_mask:0xf bank_mask:0xf
	v_cvt_pk_bf16_f32 v148, v20, v36
	ds_write_b32 v151, v148 offset:1088
	v_fmac_f32_e32 v21, v116, v20
	v_fmac_f32_e32 v37, v118, v36
	v_fmac_f32_dpp v21, v20, v122 quad_perm:[1,0,3,2] row_mask:0xf bank_mask:0xf
	v_fmac_f32_dpp v37, v36, v123 quad_perm:[1,0,3,2] row_mask:0xf bank_mask:0xf
	v_cvt_pk_bf16_f32 v149, v21, v37
	ds_write_b32 v151, v149 offset:1360
	v_fmac_f32_e32 v22, v116, v21
	v_fmac_f32_e32 v38, v118, v37
	v_fmac_f32_dpp v22, v21, v122 quad_perm:[1,0,3,2] row_mask:0xf bank_mask:0xf
	v_fmac_f32_dpp v38, v37, v123 quad_perm:[1,0,3,2] row_mask:0xf bank_mask:0xf
	v_cvt_pk_bf16_f32 v148, v22, v38
	ds_write_b32 v151, v148 offset:1632
	v_fmac_f32_e32 v23, v116, v22
	v_fmac_f32_e32 v39, v118, v38
	v_fmac_f32_dpp v23, v22, v122 quad_perm:[1,0,3,2] row_mask:0xf bank_mask:0xf
	v_fmac_f32_dpp v39, v38, v123 quad_perm:[1,0,3,2] row_mask:0xf bank_mask:0xf
	v_cvt_pk_bf16_f32 v149, v23, v39
	ds_write_b32 v151, v149 offset:1904
	v_fmac_f32_e32 v24, v116, v23
	v_fmac_f32_e32 v40, v118, v39
	v_fmac_f32_dpp v24, v23, v122 quad_perm:[1,0,3,2] row_mask:0xf bank_mask:0xf
	v_fmac_f32_dpp v40, v39, v123 quad_perm:[1,0,3,2] row_mask:0xf bank_mask:0xf
	v_cvt_pk_bf16_f32 v148, v24, v40
	ds_write_b32 v151, v148 offset:2176
	v_fmac_f32_e32 v25, v116, v24
	v_fmac_f32_e32 v41, v118, v40
	v_fmac_f32_dpp v25, v24, v122 quad_perm:[1,0,3,2] row_mask:0xf bank_mask:0xf
	v_fmac_f32_dpp v41, v40, v123 quad_perm:[1,0,3,2] row_mask:0xf bank_mask:0xf
	v_cvt_pk_bf16_f32 v149, v25, v41
	ds_write_b32 v151, v149 offset:2448
	v_fmac_f32_e32 v26, v116, v25
	v_fmac_f32_e32 v42, v118, v41
	v_fmac_f32_dpp v26, v25, v122 quad_perm:[1,0,3,2] row_mask:0xf bank_mask:0xf
	v_fmac_f32_dpp v42, v41, v123 quad_perm:[1,0,3,2] row_mask:0xf bank_mask:0xf
	v_cvt_pk_bf16_f32 v148, v26, v42
	ds_write_b32 v151, v148 offset:2720
	v_fmac_f32_e32 v27, v116, v26
	v_fmac_f32_e32 v43, v118, v42
	v_fmac_f32_dpp v27, v26, v122 quad_perm:[1,0,3,2] row_mask:0xf bank_mask:0xf
	v_fmac_f32_dpp v43, v42, v123 quad_perm:[1,0,3,2] row_mask:0xf bank_mask:0xf
	v_cvt_pk_bf16_f32 v149, v27, v43
	ds_write_b32 v151, v149 offset:2992
	v_fmac_f32_e32 v28, v116, v27
	v_fmac_f32_e32 v44, v118, v43
	v_fmac_f32_dpp v28, v27, v122 quad_perm:[1,0,3,2] row_mask:0xf bank_mask:0xf
	v_fmac_f32_dpp v44, v43, v123 quad_perm:[1,0,3,2] row_mask:0xf bank_mask:0xf
	v_cvt_pk_bf16_f32 v148, v28, v44
	ds_write_b32 v151, v148 offset:3264
	v_fmac_f32_e32 v29, v116, v28
	v_fmac_f32_e32 v45, v118, v44
	v_fmac_f32_dpp v29, v28, v122 quad_perm:[1,0,3,2] row_mask:0xf bank_mask:0xf
	v_fmac_f32_dpp v45, v44, v123 quad_perm:[1,0,3,2] row_mask:0xf bank_mask:0xf
	v_cvt_pk_bf16_f32 v149, v29, v45
	ds_write_b32 v151, v149 offset:3536
	v_fmac_f32_e32 v30, v116, v29
	v_fmac_f32_e32 v46, v118, v45
	v_fmac_f32_dpp v30, v29, v122 quad_perm:[1,0,3,2] row_mask:0xf bank_mask:0xf
	v_fmac_f32_dpp v46, v45, v123 quad_perm:[1,0,3,2] row_mask:0xf bank_mask:0xf
	v_cvt_pk_bf16_f32 v148, v30, v46
	ds_write_b32 v151, v148 offset:3808
	v_fmac_f32_e32 v31, v116, v30
	v_fmac_f32_e32 v47, v118, v46
	v_fmac_f32_dpp v31, v30, v122 quad_perm:[1,0,3,2] row_mask:0xf bank_mask:0xf
	v_fmac_f32_dpp v47, v46, v123 quad_perm:[1,0,3,2] row_mask:0xf bank_mask:0xf
	v_cvt_pk_bf16_f32 v149, v31, v47
	ds_write_b32 v151, v149 offset:4080
	s_waitcnt vmcnt(3)
	v_cndmask_b32_e64 v182, 0, v144, s[66:67]
	v_cndmask_b32_e64 v183, 0, v145, s[66:67]
	v_cndmask_b32_e64 v184, 0, v146, s[66:67]
	v_cndmask_b32_e64 v185, 0, v147, s[66:67]
	v_cndmask_b32_e64 v186, 0, v144, s[68:69]
	v_cndmask_b32_e64 v187, 0, v145, s[68:69]
	v_cndmask_b32_e64 v188, 0, v146, s[68:69]
	v_cndmask_b32_e64 v189, 0, v147, s[68:69]
	global_load_dwordx4 v[144:147], v150, s[10:11]
	v_fmac_f32_e32 v48, v116, v31
	v_fmac_f32_e32 v64, v118, v47
	v_fmac_f32_dpp v48, v31, v122 quad_perm:[1,0,3,2] row_mask:0xf bank_mask:0xf
	v_fmac_f32_dpp v64, v47, v123 quad_perm:[1,0,3,2] row_mask:0xf bank_mask:0xf
	v_cvt_pk_bf16_f32 v148, v48, v64
	ds_write_b32 v151, v148 offset:4352
	v_fmac_f32_e32 v49, v116, v48
	v_fmac_f32_e32 v65, v118, v64
	v_fmac_f32_dpp v49, v48, v122 quad_perm:[1,0,3,2] row_mask:0xf bank_mask:0xf
	v_fmac_f32_dpp v65, v64, v123 quad_perm:[1,0,3,2] row_mask:0xf bank_mask:0xf
	v_cvt_pk_bf16_f32 v149, v49, v65
	ds_write_b32 v151, v149 offset:4624
	v_mfma_f32_32x32x16_bf16 v[16:31], v[182:185], v[84:87], 0
	v_fmac_f32_e32 v50, v116, v49
	v_fmac_f32_e32 v66, v118, v65
	v_fmac_f32_dpp v50, v49, v122 quad_perm:[1,0,3,2] row_mask:0xf bank_mask:0xf
	v_fmac_f32_dpp v66, v65, v123 quad_perm:[1,0,3,2] row_mask:0xf bank_mask:0xf
	v_cvt_pk_bf16_f32 v148, v50, v66
	ds_write_b32 v151, v148 offset:4896
	v_fmac_f32_e32 v51, v116, v50
	v_fmac_f32_e32 v67, v118, v66
	v_fmac_f32_dpp v51, v50, v122 quad_perm:[1,0,3,2] row_mask:0xf bank_mask:0xf
	v_fmac_f32_dpp v67, v66, v123 quad_perm:[1,0,3,2] row_mask:0xf bank_mask:0xf
	v_cvt_pk_bf16_f32 v149, v51, v67
	ds_write_b32 v151, v149 offset:5168
	v_mfma_f32_32x32x16_bf16 v[32:47], v[182:185], v[88:91], 0
	v_fmac_f32_e32 v52, v116, v51
	v_fmac_f32_e32 v68, v118, v67
	v_fmac_f32_dpp v52, v51, v122 quad_perm:[1,0,3,2] row_mask:0xf bank_mask:0xf
	v_fmac_f32_dpp v68, v67, v123 quad_perm:[1,0,3,2] row_mask:0xf bank_mask:0xf
	v_cvt_pk_bf16_f32 v148, v52, v68
	ds_write_b32 v151, v148 offset:5440
	v_fmac_f32_e32 v53, v116, v52
	v_fmac_f32_e32 v69, v118, v68
	v_fmac_f32_dpp v53, v52, v122 quad_perm:[1,0,3,2] row_mask:0xf bank_mask:0xf
	v_fmac_f32_dpp v69, v68, v123 quad_perm:[1,0,3,2] row_mask:0xf bank_mask:0xf
	v_cvt_pk_bf16_f32 v149, v53, v69
	ds_write_b32 v151, v149 offset:5712
	v_mfma_f32_32x32x16_bf16 v[16:31], v[186:189], v[92:95], v[16:31]
	v_fmac_f32_e32 v54, v116, v53
	v_fmac_f32_e32 v70, v118, v69
	v_fmac_f32_dpp v54, v53, v122 quad_perm:[1,0,3,2] row_mask:0xf bank_mask:0xf
	v_fmac_f32_dpp v70, v69, v123 quad_perm:[1,0,3,2] row_mask:0xf bank_mask:0xf
	v_cvt_pk_bf16_f32 v148, v54, v70
	ds_write_b32 v151, v148 offset:5984
	v_fmac_f32_e32 v55, v116, v54
	v_fmac_f32_e32 v71, v118, v70
	v_fmac_f32_dpp v55, v54, v122 quad_perm:[1,0,3,2] row_mask:0xf bank_mask:0xf
	v_fmac_f32_dpp v71, v70, v123 quad_perm:[1,0,3,2] row_mask:0xf bank_mask:0xf
	v_cvt_pk_bf16_f32 v149, v55, v71
	ds_write_b32 v151, v149 offset:6256
	v_mfma_f32_32x32x16_bf16 v[32:47], v[186:189], v[96:99], v[32:47]
	v_fmac_f32_e32 v56, v116, v55
	v_fmac_f32_e32 v72, v118, v71
	v_fmac_f32_dpp v56, v55, v122 quad_perm:[1,0,3,2] row_mask:0xf bank_mask:0xf
	v_fmac_f32_dpp v72, v71, v123 quad_perm:[1,0,3,2] row_mask:0xf bank_mask:0xf
	v_cvt_pk_bf16_f32 v148, v56, v72
	ds_write_b32 v151, v148 offset:6528
	v_fmac_f32_e32 v57, v116, v56
	v_fmac_f32_e32 v73, v118, v72
	v_fmac_f32_dpp v57, v56, v122 quad_perm:[1,0,3,2] row_mask:0xf bank_mask:0xf
	v_fmac_f32_dpp v73, v72, v123 quad_perm:[1,0,3,2] row_mask:0xf bank_mask:0xf
	v_cvt_pk_bf16_f32 v149, v57, v73
	ds_write_b32 v151, v149 offset:6800
	v_fmac_f32_e32 v58, v116, v57
	v_fmac_f32_e32 v74, v118, v73
	v_fmac_f32_dpp v58, v57, v122 quad_perm:[1,0,3,2] row_mask:0xf bank_mask:0xf
	v_fmac_f32_dpp v74, v73, v123 quad_perm:[1,0,3,2] row_mask:0xf bank_mask:0xf
	v_cvt_pk_bf16_f32 v148, v58, v74
	ds_write_b32 v151, v148 offset:7072
	v_fmac_f32_e32 v59, v116, v58
	v_fmac_f32_e32 v75, v118, v74
	v_fmac_f32_dpp v59, v58, v122 quad_perm:[1,0,3,2] row_mask:0xf bank_mask:0xf
	v_fmac_f32_dpp v75, v74, v123 quad_perm:[1,0,3,2] row_mask:0xf bank_mask:0xf
	v_cvt_pk_bf16_f32 v149, v59, v75
	ds_write_b32 v151, v149 offset:7344
	v_fmac_f32_e32 v60, v116, v59
	v_fmac_f32_e32 v76, v118, v75
	v_fmac_f32_dpp v60, v59, v122 quad_perm:[1,0,3,2] row_mask:0xf bank_mask:0xf
	v_fmac_f32_dpp v76, v75, v123 quad_perm:[1,0,3,2] row_mask:0xf bank_mask:0xf
	v_cvt_pk_bf16_f32 v148, v60, v76
	ds_write_b32 v151, v148 offset:7616
	v_fmac_f32_e32 v61, v116, v60
	v_fmac_f32_e32 v77, v118, v76
	v_fmac_f32_dpp v61, v60, v122 quad_perm:[1,0,3,2] row_mask:0xf bank_mask:0xf
	v_fmac_f32_dpp v77, v76, v123 quad_perm:[1,0,3,2] row_mask:0xf bank_mask:0xf
	v_cvt_pk_bf16_f32 v149, v61, v77
	ds_write_b32 v151, v149 offset:7888
	v_fmac_f32_e32 v62, v116, v61
	v_fmac_f32_e32 v78, v118, v77
	v_fmac_f32_dpp v62, v61, v122 quad_perm:[1,0,3,2] row_mask:0xf bank_mask:0xf
	v_fmac_f32_dpp v78, v77, v123 quad_perm:[1,0,3,2] row_mask:0xf bank_mask:0xf
	v_cvt_pk_bf16_f32 v148, v62, v78
	ds_write_b32 v151, v148 offset:8160
	v_fmac_f32_e32 v63, v116, v62
	v_fmac_f32_e32 v79, v118, v78
	v_fmac_f32_dpp v63, v62, v122 quad_perm:[1,0,3,2] row_mask:0xf bank_mask:0xf
	v_fmac_f32_dpp v79, v78, v123 quad_perm:[1,0,3,2] row_mask:0xf bank_mask:0xf
	v_cvt_pk_bf16_f32 v149, v63, v79
	ds_write_b32 v151, v149 offset:8432
	v_mov_b32_e32 v120, v63
	v_mov_b32_e32 v121, v79
	s_waitcnt vmcnt(3)
	v_cndmask_b32_e64 v182, 0, v6, s[66:67]
	v_cndmask_b32_e64 v183, 0, v7, s[66:67]
	v_cndmask_b32_e64 v184, 0, v8, s[66:67]
	v_cndmask_b32_e64 v185, 0, v9, s[66:67]
	v_cndmask_b32_e64 v186, 0, v6, s[68:69]
	v_cndmask_b32_e64 v187, 0, v7, s[68:69]
	v_cndmask_b32_e64 v188, 0, v8, s[68:69]
	v_cndmask_b32_e64 v189, 0, v9, s[68:69]
	global_load_dwordx4 v[6:9], v150, s[10:11] offset:512
	s_add_u32 s29, s14, 4
	s_cmp_lt_u32 s29, 8
	s_cselect_b32 s29, 1024, 0
	s_add_u32 s10, s10, s29
	s_addc_u32 s11, s11, 0
	ds_read_b128 v[124:127], v152
	ds_read_b128 v[128:131], v152 offset:64
	ds_read_b128 v[132:135], v152 offset:128
	ds_read_b128 v[136:139], v152 offset:192
	v_mfma_f32_32x32x16_bf16 v[48:63], v[182:185], v[84:87], 0
	v_mfma_f32_32x32x16_bf16 v[64:79], v[182:185], v[88:91], 0
	v_mfma_f32_32x32x16_bf16 v[48:63], v[186:189], v[92:95], v[48:63]
	v_mfma_f32_32x32x16_bf16 v[64:79], v[186:189], v[96:99], v[64:79]
	s_waitcnt lgkmcnt(3)
	v_mfma_f32_16x16x32_bf16 v[140:143], v[100:103], v[124:127], 0
	s_waitcnt lgkmcnt(2)
	v_mfma_f32_16x16x32_bf16 v[140:143], v[104:107], v[128:131], v[140:143]
	s_waitcnt lgkmcnt(1)
	v_mfma_f32_16x16x32_bf16 v[140:143], v[108:111], v[132:135], v[140:143]
	s_waitcnt lgkmcnt(0)
	v_mfma_f32_16x16x32_bf16 v[140:143], v[112:115], v[136:139], v[140:143]
	s_nop 9
	v_cvt_pk_bf16_f32 v182, v140, v141
	v_cvt_pk_bf16_f32 v183, v142, v143
	ds_write_b64 v171, v[182:183]
	ds_read_b128 v[124:127], v152 offset:4352
	ds_read_b128 v[128:131], v152 offset:4416
	ds_read_b128 v[132:135], v152 offset:4480
	ds_read_b128 v[136:139], v152 offset:4544
	s_waitcnt lgkmcnt(3)
	v_mfma_f32_16x16x32_bf16 v[140:143], v[100:103], v[124:127], 0
	s_waitcnt lgkmcnt(2)
	v_mfma_f32_16x16x32_bf16 v[140:143], v[104:107], v[128:131], v[140:143]
	s_waitcnt lgkmcnt(1)
	v_mfma_f32_16x16x32_bf16 v[140:143], v[108:111], v[132:135], v[140:143]
	s_waitcnt lgkmcnt(0)
	v_mfma_f32_16x16x32_bf16 v[140:143], v[112:115], v[136:139], v[140:143]
	s_nop 9
	v_cvt_pk_bf16_f32 v182, v140, v141
	v_cvt_pk_bf16_f32 v183, v142, v143
	ds_write_b64 v171, v[182:183] offset:512
	s_add_u32 s36, s36, 1024
	v_add_u32_e32 v171, s36, v155
	v_fmac_f32_e32 v16, v116, v120
	v_fmac_f32_e32 v32, v118, v121
	v_fmac_f32_dpp v16, v120, v122 quad_perm:[1,0,3,2] row_mask:0xf bank_mask:0xf
	v_fmac_f32_dpp v32, v121, v123 quad_perm:[1,0,3,2] row_mask:0xf bank_mask:0xf
	v_cvt_pk_bf16_f32 v148, v16, v32
	ds_write_b32 v151, v148
	v_fmac_f32_e32 v17, v116, v16
	v_fmac_f32_e32 v33, v118, v32
	v_fmac_f32_dpp v17, v16, v122 quad_perm:[1,0,3,2] row_mask:0xf bank_mask:0xf
	v_fmac_f32_dpp v33, v32, v123 quad_perm:[1,0,3,2] row_mask:0xf bank_mask:0xf
	v_cvt_pk_bf16_f32 v149, v17, v33
	ds_write_b32 v151, v149 offset:272
	v_fmac_f32_e32 v18, v116, v17
	v_fmac_f32_e32 v34, v118, v33
	v_fmac_f32_dpp v18, v17, v122 quad_perm:[1,0,3,2] row_mask:0xf bank_mask:0xf
	v_fmac_f32_dpp v34, v33, v123 quad_perm:[1,0,3,2] row_mask:0xf bank_mask:0xf
	v_cvt_pk_bf16_f32 v148, v18, v34
	ds_write_b32 v151, v148 offset:544
	v_fmac_f32_e32 v19, v116, v18
	v_fmac_f32_e32 v35, v118, v34
	v_fmac_f32_dpp v19, v18, v122 quad_perm:[1,0,3,2] row_mask:0xf bank_mask:0xf
	v_fmac_f32_dpp v35, v34, v123 quad_perm:[1,0,3,2] row_mask:0xf bank_mask:0xf
	v_cvt_pk_bf16_f32 v149, v19, v35
	ds_write_b32 v151, v149 offset:816
	v_fmac_f32_e32 v20, v116, v19
	v_fmac_f32_e32 v36, v118, v35
	v_fmac_f32_dpp v20, v19, v122 quad_perm:[1,0,3,2] row_mask:0xf bank_mask:0xf
	v_fmac_f32_dpp v36, v35, v123 quad_perm:[1,0,3,2] row_mask:0xf bank_mask:0xf
	v_cvt_pk_bf16_f32 v148, v20, v36
	ds_write_b32 v151, v148 offset:1088
	v_fmac_f32_e32 v21, v116, v20
	v_fmac_f32_e32 v37, v118, v36
	v_fmac_f32_dpp v21, v20, v122 quad_perm:[1,0,3,2] row_mask:0xf bank_mask:0xf
	v_fmac_f32_dpp v37, v36, v123 quad_perm:[1,0,3,2] row_mask:0xf bank_mask:0xf
	v_cvt_pk_bf16_f32 v149, v21, v37
	ds_write_b32 v151, v149 offset:1360
	v_fmac_f32_e32 v22, v116, v21
	v_fmac_f32_e32 v38, v118, v37
	v_fmac_f32_dpp v22, v21, v122 quad_perm:[1,0,3,2] row_mask:0xf bank_mask:0xf
	v_fmac_f32_dpp v38, v37, v123 quad_perm:[1,0,3,2] row_mask:0xf bank_mask:0xf
	v_cvt_pk_bf16_f32 v148, v22, v38
	ds_write_b32 v151, v148 offset:1632
	v_fmac_f32_e32 v23, v116, v22
	v_fmac_f32_e32 v39, v118, v38
	v_fmac_f32_dpp v23, v22, v122 quad_perm:[1,0,3,2] row_mask:0xf bank_mask:0xf
	v_fmac_f32_dpp v39, v38, v123 quad_perm:[1,0,3,2] row_mask:0xf bank_mask:0xf
	v_cvt_pk_bf16_f32 v149, v23, v39
	ds_write_b32 v151, v149 offset:1904
	v_fmac_f32_e32 v24, v116, v23
	v_fmac_f32_e32 v40, v118, v39
	v_fmac_f32_dpp v24, v23, v122 quad_perm:[1,0,3,2] row_mask:0xf bank_mask:0xf
	v_fmac_f32_dpp v40, v39, v123 quad_perm:[1,0,3,2] row_mask:0xf bank_mask:0xf
	v_cvt_pk_bf16_f32 v148, v24, v40
	ds_write_b32 v151, v148 offset:2176
	v_fmac_f32_e32 v25, v116, v24
	v_fmac_f32_e32 v41, v118, v40
	v_fmac_f32_dpp v25, v24, v122 quad_perm:[1,0,3,2] row_mask:0xf bank_mask:0xf
	v_fmac_f32_dpp v41, v40, v123 quad_perm:[1,0,3,2] row_mask:0xf bank_mask:0xf
	v_cvt_pk_bf16_f32 v149, v25, v41
	ds_write_b32 v151, v149 offset:2448
	v_fmac_f32_e32 v26, v116, v25
	v_fmac_f32_e32 v42, v118, v41
	v_fmac_f32_dpp v26, v25, v122 quad_perm:[1,0,3,2] row_mask:0xf bank_mask:0xf
	v_fmac_f32_dpp v42, v41, v123 quad_perm:[1,0,3,2] row_mask:0xf bank_mask:0xf
	v_cvt_pk_bf16_f32 v148, v26, v42
	ds_write_b32 v151, v148 offset:2720
	v_fmac_f32_e32 v27, v116, v26
	v_fmac_f32_e32 v43, v118, v42
	v_fmac_f32_dpp v27, v26, v122 quad_perm:[1,0,3,2] row_mask:0xf bank_mask:0xf
	v_fmac_f32_dpp v43, v42, v123 quad_perm:[1,0,3,2] row_mask:0xf bank_mask:0xf
	v_cvt_pk_bf16_f32 v149, v27, v43
	ds_write_b32 v151, v149 offset:2992
	v_fmac_f32_e32 v28, v116, v27
	v_fmac_f32_e32 v44, v118, v43
	v_fmac_f32_dpp v28, v27, v122 quad_perm:[1,0,3,2] row_mask:0xf bank_mask:0xf
	v_fmac_f32_dpp v44, v43, v123 quad_perm:[1,0,3,2] row_mask:0xf bank_mask:0xf
	v_cvt_pk_bf16_f32 v148, v28, v44
	ds_write_b32 v151, v148 offset:3264
	v_fmac_f32_e32 v29, v116, v28
	v_fmac_f32_e32 v45, v118, v44
	v_fmac_f32_dpp v29, v28, v122 quad_perm:[1,0,3,2] row_mask:0xf bank_mask:0xf
	v_fmac_f32_dpp v45, v44, v123 quad_perm:[1,0,3,2] row_mask:0xf bank_mask:0xf
	v_cvt_pk_bf16_f32 v149, v29, v45
	ds_write_b32 v151, v149 offset:3536
	v_fmac_f32_e32 v30, v116, v29
	v_fmac_f32_e32 v46, v118, v45
	v_fmac_f32_dpp v30, v29, v122 quad_perm:[1,0,3,2] row_mask:0xf bank_mask:0xf
	v_fmac_f32_dpp v46, v45, v123 quad_perm:[1,0,3,2] row_mask:0xf bank_mask:0xf
	v_cvt_pk_bf16_f32 v148, v30, v46
	ds_write_b32 v151, v148 offset:3808
	v_fmac_f32_e32 v31, v116, v30
	v_fmac_f32_e32 v47, v118, v46
	v_fmac_f32_dpp v31, v30, v122 quad_perm:[1,0,3,2] row_mask:0xf bank_mask:0xf
	v_fmac_f32_dpp v47, v46, v123 quad_perm:[1,0,3,2] row_mask:0xf bank_mask:0xf
	v_cvt_pk_bf16_f32 v149, v31, v47
	ds_write_b32 v151, v149 offset:4080
	s_waitcnt vmcnt(3)
	v_cndmask_b32_e64 v182, 0, v80, s[66:67]
	v_cndmask_b32_e64 v183, 0, v81, s[66:67]
	v_cndmask_b32_e64 v184, 0, v82, s[66:67]
	v_cndmask_b32_e64 v185, 0, v83, s[66:67]
	v_cndmask_b32_e64 v186, 0, v80, s[68:69]
	v_cndmask_b32_e64 v187, 0, v81, s[68:69]
	v_cndmask_b32_e64 v188, 0, v82, s[68:69]
	v_cndmask_b32_e64 v189, 0, v83, s[68:69]
	global_load_dwordx4 v[80:83], v150, s[10:11]
	v_fmac_f32_e32 v48, v116, v31
	v_fmac_f32_e32 v64, v118, v47
	v_fmac_f32_dpp v48, v31, v122 quad_perm:[1,0,3,2] row_mask:0xf bank_mask:0xf
	v_fmac_f32_dpp v64, v47, v123 quad_perm:[1,0,3,2] row_mask:0xf bank_mask:0xf
	v_cvt_pk_bf16_f32 v148, v48, v64
	ds_write_b32 v151, v148 offset:4352
	v_fmac_f32_e32 v49, v116, v48
	v_fmac_f32_e32 v65, v118, v64
	v_fmac_f32_dpp v49, v48, v122 quad_perm:[1,0,3,2] row_mask:0xf bank_mask:0xf
	v_fmac_f32_dpp v65, v64, v123 quad_perm:[1,0,3,2] row_mask:0xf bank_mask:0xf
	v_cvt_pk_bf16_f32 v149, v49, v65
	ds_write_b32 v151, v149 offset:4624
	v_mfma_f32_32x32x16_bf16 v[16:31], v[182:185], v[84:87], 0
	v_fmac_f32_e32 v50, v116, v49
	v_fmac_f32_e32 v66, v118, v65
	v_fmac_f32_dpp v50, v49, v122 quad_perm:[1,0,3,2] row_mask:0xf bank_mask:0xf
	v_fmac_f32_dpp v66, v65, v123 quad_perm:[1,0,3,2] row_mask:0xf bank_mask:0xf
	v_cvt_pk_bf16_f32 v148, v50, v66
	ds_write_b32 v151, v148 offset:4896
	v_fmac_f32_e32 v51, v116, v50
	v_fmac_f32_e32 v67, v118, v66
	v_fmac_f32_dpp v51, v50, v122 quad_perm:[1,0,3,2] row_mask:0xf bank_mask:0xf
	v_fmac_f32_dpp v67, v66, v123 quad_perm:[1,0,3,2] row_mask:0xf bank_mask:0xf
	v_cvt_pk_bf16_f32 v149, v51, v67
	ds_write_b32 v151, v149 offset:5168
	v_mfma_f32_32x32x16_bf16 v[32:47], v[182:185], v[88:91], 0
	v_fmac_f32_e32 v52, v116, v51
	v_fmac_f32_e32 v68, v118, v67
	v_fmac_f32_dpp v52, v51, v122 quad_perm:[1,0,3,2] row_mask:0xf bank_mask:0xf
	v_fmac_f32_dpp v68, v67, v123 quad_perm:[1,0,3,2] row_mask:0xf bank_mask:0xf
	v_cvt_pk_bf16_f32 v148, v52, v68
	ds_write_b32 v151, v148 offset:5440
	v_fmac_f32_e32 v53, v116, v52
	v_fmac_f32_e32 v69, v118, v68
	v_fmac_f32_dpp v53, v52, v122 quad_perm:[1,0,3,2] row_mask:0xf bank_mask:0xf
	v_fmac_f32_dpp v69, v68, v123 quad_perm:[1,0,3,2] row_mask:0xf bank_mask:0xf
	v_cvt_pk_bf16_f32 v149, v53, v69
	ds_write_b32 v151, v149 offset:5712
	v_mfma_f32_32x32x16_bf16 v[16:31], v[186:189], v[92:95], v[16:31]
	v_fmac_f32_e32 v54, v116, v53
	v_fmac_f32_e32 v70, v118, v69
	v_fmac_f32_dpp v54, v53, v122 quad_perm:[1,0,3,2] row_mask:0xf bank_mask:0xf
	v_fmac_f32_dpp v70, v69, v123 quad_perm:[1,0,3,2] row_mask:0xf bank_mask:0xf
	v_cvt_pk_bf16_f32 v148, v54, v70
	ds_write_b32 v151, v148 offset:5984
	v_fmac_f32_e32 v55, v116, v54
	v_fmac_f32_e32 v71, v118, v70
	v_fmac_f32_dpp v55, v54, v122 quad_perm:[1,0,3,2] row_mask:0xf bank_mask:0xf
	v_fmac_f32_dpp v71, v70, v123 quad_perm:[1,0,3,2] row_mask:0xf bank_mask:0xf
	v_cvt_pk_bf16_f32 v149, v55, v71
	ds_write_b32 v151, v149 offset:6256
	v_mfma_f32_32x32x16_bf16 v[32:47], v[186:189], v[96:99], v[32:47]
	v_fmac_f32_e32 v56, v116, v55
	v_fmac_f32_e32 v72, v118, v71
	v_fmac_f32_dpp v56, v55, v122 quad_perm:[1,0,3,2] row_mask:0xf bank_mask:0xf
	v_fmac_f32_dpp v72, v71, v123 quad_perm:[1,0,3,2] row_mask:0xf bank_mask:0xf
	v_cvt_pk_bf16_f32 v148, v56, v72
	ds_write_b32 v151, v148 offset:6528
	v_fmac_f32_e32 v57, v116, v56
	v_fmac_f32_e32 v73, v118, v72
	v_fmac_f32_dpp v57, v56, v122 quad_perm:[1,0,3,2] row_mask:0xf bank_mask:0xf
	v_fmac_f32_dpp v73, v72, v123 quad_perm:[1,0,3,2] row_mask:0xf bank_mask:0xf
	v_cvt_pk_bf16_f32 v149, v57, v73
	ds_write_b32 v151, v149 offset:6800
	v_fmac_f32_e32 v58, v116, v57
	v_fmac_f32_e32 v74, v118, v73
	v_fmac_f32_dpp v58, v57, v122 quad_perm:[1,0,3,2] row_mask:0xf bank_mask:0xf
	v_fmac_f32_dpp v74, v73, v123 quad_perm:[1,0,3,2] row_mask:0xf bank_mask:0xf
	v_cvt_pk_bf16_f32 v148, v58, v74
	ds_write_b32 v151, v148 offset:7072
	v_fmac_f32_e32 v59, v116, v58
	v_fmac_f32_e32 v75, v118, v74
	v_fmac_f32_dpp v59, v58, v122 quad_perm:[1,0,3,2] row_mask:0xf bank_mask:0xf
	v_fmac_f32_dpp v75, v74, v123 quad_perm:[1,0,3,2] row_mask:0xf bank_mask:0xf
	v_cvt_pk_bf16_f32 v149, v59, v75
	ds_write_b32 v151, v149 offset:7344
	v_fmac_f32_e32 v60, v116, v59
	v_fmac_f32_e32 v76, v118, v75
	v_fmac_f32_dpp v60, v59, v122 quad_perm:[1,0,3,2] row_mask:0xf bank_mask:0xf
	v_fmac_f32_dpp v76, v75, v123 quad_perm:[1,0,3,2] row_mask:0xf bank_mask:0xf
	v_cvt_pk_bf16_f32 v148, v60, v76
	ds_write_b32 v151, v148 offset:7616
	v_fmac_f32_e32 v61, v116, v60
	v_fmac_f32_e32 v77, v118, v76
	v_fmac_f32_dpp v61, v60, v122 quad_perm:[1,0,3,2] row_mask:0xf bank_mask:0xf
	v_fmac_f32_dpp v77, v76, v123 quad_perm:[1,0,3,2] row_mask:0xf bank_mask:0xf
	v_cvt_pk_bf16_f32 v149, v61, v77
	ds_write_b32 v151, v149 offset:7888
	v_fmac_f32_e32 v62, v116, v61
	v_fmac_f32_e32 v78, v118, v77
	v_fmac_f32_dpp v62, v61, v122 quad_perm:[1,0,3,2] row_mask:0xf bank_mask:0xf
	v_fmac_f32_dpp v78, v77, v123 quad_perm:[1,0,3,2] row_mask:0xf bank_mask:0xf
	v_cvt_pk_bf16_f32 v148, v62, v78
	ds_write_b32 v151, v148 offset:8160
	v_fmac_f32_e32 v63, v116, v62
	v_fmac_f32_e32 v79, v118, v78
	v_fmac_f32_dpp v63, v62, v122 quad_perm:[1,0,3,2] row_mask:0xf bank_mask:0xf
	v_fmac_f32_dpp v79, v78, v123 quad_perm:[1,0,3,2] row_mask:0xf bank_mask:0xf
	v_cvt_pk_bf16_f32 v149, v63, v79
	ds_write_b32 v151, v149 offset:8432
	v_mov_b32_e32 v120, v63
	v_mov_b32_e32 v121, v79
	s_waitcnt vmcnt(3)
	v_cndmask_b32_e64 v182, 0, v194, s[66:67]
	v_cndmask_b32_e64 v183, 0, v195, s[66:67]
	v_cndmask_b32_e64 v184, 0, v196, s[66:67]
	v_cndmask_b32_e64 v185, 0, v197, s[66:67]
	v_cndmask_b32_e64 v186, 0, v194, s[68:69]
	v_cndmask_b32_e64 v187, 0, v195, s[68:69]
	v_cndmask_b32_e64 v188, 0, v196, s[68:69]
	v_cndmask_b32_e64 v189, 0, v197, s[68:69]
	global_load_dwordx4 v[194:197], v150, s[10:11] offset:512
	s_add_u32 s29, s14, 5
	s_cmp_lt_u32 s29, 8
	s_cselect_b32 s29, 1024, 0
	s_add_u32 s10, s10, s29
	s_addc_u32 s11, s11, 0
	ds_read_b128 v[124:127], v152
	ds_read_b128 v[128:131], v152 offset:64
	ds_read_b128 v[132:135], v152 offset:128
	ds_read_b128 v[136:139], v152 offset:192
	v_mfma_f32_32x32x16_bf16 v[48:63], v[182:185], v[84:87], 0
	v_mfma_f32_32x32x16_bf16 v[64:79], v[182:185], v[88:91], 0
	v_mfma_f32_32x32x16_bf16 v[48:63], v[186:189], v[92:95], v[48:63]
	v_mfma_f32_32x32x16_bf16 v[64:79], v[186:189], v[96:99], v[64:79]
	s_waitcnt lgkmcnt(3)
	v_mfma_f32_16x16x32_bf16 v[140:143], v[100:103], v[124:127], 0
	s_waitcnt lgkmcnt(2)
	v_mfma_f32_16x16x32_bf16 v[140:143], v[104:107], v[128:131], v[140:143]
	s_waitcnt lgkmcnt(1)
	v_mfma_f32_16x16x32_bf16 v[140:143], v[108:111], v[132:135], v[140:143]
	s_waitcnt lgkmcnt(0)
	v_mfma_f32_16x16x32_bf16 v[140:143], v[112:115], v[136:139], v[140:143]
	s_nop 9
	v_cvt_pk_bf16_f32 v182, v140, v141
	v_cvt_pk_bf16_f32 v183, v142, v143
	ds_write_b64 v171, v[182:183]
	ds_read_b128 v[124:127], v152 offset:4352
	ds_read_b128 v[128:131], v152 offset:4416
	ds_read_b128 v[132:135], v152 offset:4480
	ds_read_b128 v[136:139], v152 offset:4544
	s_waitcnt lgkmcnt(3)
	v_mfma_f32_16x16x32_bf16 v[140:143], v[100:103], v[124:127], 0
	s_waitcnt lgkmcnt(2)
	v_mfma_f32_16x16x32_bf16 v[140:143], v[104:107], v[128:131], v[140:143]
	s_waitcnt lgkmcnt(1)
	v_mfma_f32_16x16x32_bf16 v[140:143], v[108:111], v[132:135], v[140:143]
	s_waitcnt lgkmcnt(0)
	v_mfma_f32_16x16x32_bf16 v[140:143], v[112:115], v[136:139], v[140:143]
	s_nop 9
	v_cvt_pk_bf16_f32 v182, v140, v141
	v_cvt_pk_bf16_f32 v183, v142, v143
	ds_write_b64 v171, v[182:183] offset:512
	s_add_u32 s36, s36, 1024
	s_add_u32 s14, s14, 2
	s_cmp_lt_u32 s14, 8
	s_cbranch_scc1 .Lssm_tile_d0m1
	s_add_u32 s30, s30, 0x8000000
	s_add_u32 s16, s60, s30
	s_addc_u32 s17, s61, 0
	global_store_dword v180, v120, s[16:17]
	global_store_dword v180, v121, s[16:17] offset:64
	s_waitcnt vmcnt(0) lgkmcnt(0)
	s_add_u32 s28, s24, 64
	s_lshl_b32 s29, s28, 13
	s_add_u32 s29, s29, 0x200000
	s_add_u32 s10, s62, s29
	s_addc_u32 s11, s63, 0
	global_load_dwordx4 v[84:87], v177, s[10:11]
	global_load_dwordx4 v[88:91], v177, s[10:11] offset:2048
	s_add_u32 s12, s10, 0x1000
	s_addc_u32 s13, s11, 0
	global_load_dwordx4 v[92:95], v177, s[12:13]
	global_load_dwordx4 v[96:99], v177, s[12:13] offset:2048
	s_lshl_b32 s29, s28, 12
	s_add_u32 s29, s29, 0x300000
	s_add_u32 s16, s62, s29
	s_addc_u32 s17, s63, 0
	global_load_dwordx2 v[20:21], v178, s[16:17]
	global_load_dwordx2 v[22:23], v178, s[16:17] offset:1024
	global_load_dwordx2 v[24:25], v178, s[16:17] offset:512
	global_load_dwordx2 v[26:27], v178, s[16:17] offset:1536
	global_load_dwordx2 v[28:29], v178, s[16:17] offset:2048
	global_load_dwordx2 v[30:31], v178, s[16:17] offset:3072
	global_load_dwordx2 v[32:33], v178, s[16:17] offset:2560
	global_load_dwordx2 v[34:35], v178, s[16:17] offset:3584
	s_lshl_b32 s29, s28, 9
	s_add_u32 s29, s29, 0x100000
	s_add_u32 s18, s62, s29
	s_addc_u32 s19, s63, 0
	global_load_dwordx2 v[116:117], v179, s[18:19]
	global_load_dwordx2 v[118:119], v179, s[18:19] offset:128
	s_lshl_b32 s30, s23, 1
	s_add_u32 s30, s30, 1
	s_lshl_b32 s30, s30, 15
	s_lshl_b32 s31, s24, 8
	s_add_u32 s30, s30, s31
	v_mov_b32_e32 v120, 0
	v_mov_b32_e32 v121, 0
	v_readlane_b32 s34, v254, 28
	v_readlane_b32 s35, v254, 29
	s_nop 3
	s_lshl_b32 s31, s24, 6
	s_add_u32 s34, s34, s31
	s_addc_u32 s35, s35, 0
	global_load_dwordx4 v[164:167], v181, s[34:35]
	s_lshl_b32 s31, s25, 5
	s_lshl_b32 s29, s24, 19
	s_add_u32 s31, s31, s29
	s_add_u32 s31, s31, 0x16800000
	s_add_u32 s4, s62, s31
	s_addc_u32 s5, s63, 0
	s_lshl_b32 s31, s25, 11
	s_lshl_b32 s29, s24, 5
	s_add_u32 s31, s31, s29
	s_add_u32 s31, s31, 0x14800000
	s_add_u32 s6, s62, s31
	s_addc_u32 s7, s63, 0
	s_add_u32 s34, s4, 7168
	s_addc_u32 s35, s5, 0
	global_load_dwordx4 v[80:83], v150, s[34:35] offset:512
	global_load_dwordx4 v[194:197], v150, s[34:35]
	s_mov_b64 s[10:11], s[34:35]
	s_sub_u32 s10, s10, 1024
	s_subb_u32 s11, s11, 0
	global_load_dwordx4 v[144:147], v150, s[10:11] offset:512
	global_load_dwordx4 v[6:9], v150, s[10:11]
	s_sub_u32 s10, s10, 1024
	s_subb_u32 s11, s11, 0
	s_add_u32 s12, s6, 458752
	s_addc_u32 s13, s7, 0
	s_mov_b32 s36, 7168
	s_mov_b32 s14, 0
	s_mov_b32 s40, 0xffff0000
	s_waitcnt vmcnt(0)
	v_and_b32_e32 v182, 0xffff, v20
	v_lshrrev_b32_e32 v183, 16, v20
	v_and_b32_e32 v184, 0xffff, v21
	v_lshrrev_b32_e32 v185, 16, v21
	v_lshl_or_b32 v100, v22, 16, v182
	v_and_or_b32 v101, v22, s40, v183
	v_lshl_or_b32 v102, v23, 16, v184
	v_and_or_b32 v103, v23, s40, v185
	v_and_b32_e32 v182, 0xffff, v24
	v_lshrrev_b32_e32 v183, 16, v24
	v_and_b32_e32 v184, 0xffff, v25
	v_lshrrev_b32_e32 v185, 16, v25
	v_lshl_or_b32 v104, v26, 16, v182
	v_and_or_b32 v105, v26, s40, v183
	v_lshl_or_b32 v106, v27, 16, v184
	v_and_or_b32 v107, v27, s40, v185
	v_and_b32_e32 v182, 0xffff, v28
	v_lshrrev_b32_e32 v183, 16, v28
	v_and_b32_e32 v184, 0xffff, v29
	v_lshrrev_b32_e32 v185, 16, v29
	v_lshl_or_b32 v108, v30, 16, v182
	v_and_or_b32 v109, v30, s40, v183
	v_lshl_or_b32 v110, v31, 16, v184
	v_and_or_b32 v111, v31, s40, v185
	v_and_b32_e32 v182, 0xffff, v32
	v_lshrrev_b32_e32 v183, 16, v32
	v_and_b32_e32 v184, 0xffff, v33
	v_lshrrev_b32_e32 v185, 16, v33
	v_lshl_or_b32 v112, v34, 16, v182
	v_and_or_b32 v113, v34, s40, v183
	v_lshl_or_b32 v114, v35, 16, v184
	v_and_or_b32 v115, v35, s40, v185
	v_cmp_eq_u32_e32 vcc, 1, v174
	v_xor_b32_e32 v182, 0x80000000, v117
	v_xor_b32_e32 v183, 0x80000000, v119
	s_nop 1
	v_cndmask_b32_e32 v122, v182, v117, vcc
	v_cndmask_b32_e32 v123, v183, v119, vcc
	ds_write_b128 v162, v[80:83] offset:512
	ds_write_b128 v162, v[194:197]
	v_cndmask_b32_e64 v182, 0, v80, s[66:67]
	v_cndmask_b32_e64 v183, 0, v81, s[66:67]
	v_cndmask_b32_e64 v184, 0, v82, s[66:67]
	v_cndmask_b32_e64 v185, 0, v83, s[66:67]
	v_cndmask_b32_e64 v186, 0, v80, s[68:69]
	v_cndmask_b32_e64 v187, 0, v81, s[68:69]
	v_cndmask_b32_e64 v188, 0, v82, s[68:69]
	v_cndmask_b32_e64 v189, 0, v83, s[68:69]
	v_cndmask_b32_e64 v124, 0, v194, s[66:67]
	v_cndmask_b32_e64 v125, 0, v195, s[66:67]
	v_cndmask_b32_e64 v126, 0, v196, s[66:67]
	v_cndmask_b32_e64 v127, 0, v197, s[66:67]
	v_cndmask_b32_e64 v128, 0, v194, s[68:69]
	v_cndmask_b32_e64 v129, 0, v195, s[68:69]
	v_cndmask_b32_e64 v130, 0, v196, s[68:69]
	v_cndmask_b32_e64 v131, 0, v197, s[68:69]
	v_mfma_f32_32x32x16_bf16 v[48:63], v[182:185], v[84:87], 0
	v_mfma_f32_32x32x16_bf16 v[64:79], v[182:185], v[88:91], 0
	v_mfma_f32_32x32x16_bf16 v[48:63], v[186:189], v[92:95], v[48:63]
	v_mfma_f32_32x32x16_bf16 v[64:79], v[186:189], v[96:99], v[64:79]
	v_mfma_f32_32x32x16_bf16 v[16:31], v[124:127], v[84:87], 0
	v_mfma_f32_32x32x16_bf16 v[32:47], v[124:127], v[88:91], 0
	v_mfma_f32_32x32x16_bf16 v[16:31], v[128:131], v[92:95], v[16:31]
	v_mfma_f32_32x32x16_bf16 v[32:47], v[128:131], v[96:99], v[32:47]
	global_load_dwordx4 v[80:83], v150, s[10:11] offset:512
	global_load_dwordx4 v[194:197], v150, s[10:11]
	s_sub_u32 s10, s10, 1024
	s_subb_u32 s11, s11, 0
	s_nop 7
.Lssm_tile_d1m2:
	v_add_u32_e32 v171, s36, v155
	v_fmac_f32_e32 v63, v116, v120
	v_fmac_f32_e32 v79, v118, v121
	v_fmac_f32_dpp v63, v120, v122 quad_perm:[1,0,3,2] row_mask:0xf bank_mask:0xf
	v_fmac_f32_dpp v79, v121, v123 quad_perm:[1,0,3,2] row_mask:0xf bank_mask:0xf
	v_cvt_pk_bf16_f32 v148, v63, v79
	ds_write_b32 v151, v148 offset:8432
	v_fmac_f32_e32 v62, v116, v63
	v_fmac_f32_e32 v78, v118, v79
	v_fmac_f32_dpp v62, v63, v122 quad_perm:[1,0,3,2] row_mask:0xf bank_mask:0xf
	v_fmac_f32_dpp v78, v79, v123 quad_perm:[1,0,3,2] row_mask:0xf bank_mask:0xf
	v_cvt_pk_bf16_f32 v149, v62, v78
	ds_write_b32 v151, v149 offset:8160
	v_fmac_f32_e32 v61, v116, v62
	v_fmac_f32_e32 v77, v118, v78
	v_fmac_f32_dpp v61, v62, v122 quad_perm:[1,0,3,2] row_mask:0xf bank_mask:0xf
	v_fmac_f32_dpp v77, v78, v123 quad_perm:[1,0,3,2] row_mask:0xf bank_mask:0xf
	v_cvt_pk_bf16_f32 v148, v61, v77
	ds_write_b32 v151, v148 offset:7888
	v_fmac_f32_e32 v60, v116, v61
	v_fmac_f32_e32 v76, v118, v77
	v_fmac_f32_dpp v60, v61, v122 quad_perm:[1,0,3,2] row_mask:0xf bank_mask:0xf
	v_fmac_f32_dpp v76, v77, v123 quad_perm:[1,0,3,2] row_mask:0xf bank_mask:0xf
	v_cvt_pk_bf16_f32 v149, v60, v76
	ds_write_b32 v151, v149 offset:7616
	v_fmac_f32_e32 v59, v116, v60
	v_fmac_f32_e32 v75, v118, v76
	v_fmac_f32_dpp v59, v60, v122 quad_perm:[1,0,3,2] row_mask:0xf bank_mask:0xf
	v_fmac_f32_dpp v75, v76, v123 quad_perm:[1,0,3,2] row_mask:0xf bank_mask:0xf
	v_cvt_pk_bf16_f32 v148, v59, v75
	ds_write_b32 v151, v148 offset:7344
	v_fmac_f32_e32 v58, v116, v59
	v_fmac_f32_e32 v74, v118, v75
	v_fmac_f32_dpp v58, v59, v122 quad_perm:[1,0,3,2] row_mask:0xf bank_mask:0xf
	v_fmac_f32_dpp v74, v75, v123 quad_perm:[1,0,3,2] row_mask:0xf bank_mask:0xf
	v_cvt_pk_bf16_f32 v149, v58, v74
	ds_write_b32 v151, v149 offset:7072
	v_fmac_f32_e32 v57, v116, v58
	v_fmac_f32_e32 v73, v118, v74
	v_fmac_f32_dpp v57, v58, v122 quad_perm:[1,0,3,2] row_mask:0xf bank_mask:0xf
	v_fmac_f32_dpp v73, v74, v123 quad_perm:[1,0,3,2] row_mask:0xf bank_mask:0xf
	v_cvt_pk_bf16_f32 v148, v57, v73
	ds_write_b32 v151, v148 offset:6800
	v_fmac_f32_e32 v56, v116, v57
	v_fmac_f32_e32 v72, v118, v73
	v_fmac_f32_dpp v56, v57, v122 quad_perm:[1,0,3,2] row_mask:0xf bank_mask:0xf
	v_fmac_f32_dpp v72, v73, v123 quad_perm:[1,0,3,2] row_mask:0xf bank_mask:0xf
	v_cvt_pk_bf16_f32 v149, v56, v72
	ds_write_b32 v151, v149 offset:6528
	v_fmac_f32_e32 v55, v116, v56
	v_fmac_f32_e32 v71, v118, v72
	v_fmac_f32_dpp v55, v56, v122 quad_perm:[1,0,3,2] row_mask:0xf bank_mask:0xf
	v_fmac_f32_dpp v71, v72, v123 quad_perm:[1,0,3,2] row_mask:0xf bank_mask:0xf
	v_cvt_pk_bf16_f32 v148, v55, v71
	ds_write_b32 v151, v148 offset:6256
	v_fmac_f32_e32 v54, v116, v55
	v_fmac_f32_e32 v70, v118, v71
	v_fmac_f32_dpp v54, v55, v122 quad_perm:[1,0,3,2] row_mask:0xf bank_mask:0xf
	v_fmac_f32_dpp v70, v71, v123 quad_perm:[1,0,3,2] row_mask:0xf bank_mask:0xf
	v_cvt_pk_bf16_f32 v149, v54, v70
	ds_write_b32 v151, v149 offset:5984
	v_fmac_f32_e32 v53, v116, v54
	v_fmac_f32_e32 v69, v118, v70
	v_fmac_f32_dpp v53, v54, v122 quad_perm:[1,0,3,2] row_mask:0xf bank_mask:0xf
	v_fmac_f32_dpp v69, v70, v123 quad_perm:[1,0,3,2] row_mask:0xf bank_mask:0xf
	v_cvt_pk_bf16_f32 v148, v53, v69
	ds_write_b32 v151, v148 offset:5712
	v_fmac_f32_e32 v52, v116, v53
	v_fmac_f32_e32 v68, v118, v69
	v_fmac_f32_dpp v52, v53, v122 quad_perm:[1,0,3,2] row_mask:0xf bank_mask:0xf
	v_fmac_f32_dpp v68, v69, v123 quad_perm:[1,0,3,2] row_mask:0xf bank_mask:0xf
	v_cvt_pk_bf16_f32 v149, v52, v68
	ds_write_b32 v151, v149 offset:5440
	v_fmac_f32_e32 v51, v116, v52
	v_fmac_f32_e32 v67, v118, v68
	v_fmac_f32_dpp v51, v52, v122 quad_perm:[1,0,3,2] row_mask:0xf bank_mask:0xf
	v_fmac_f32_dpp v67, v68, v123 quad_perm:[1,0,3,2] row_mask:0xf bank_mask:0xf
	v_cvt_pk_bf16_f32 v148, v51, v67
	ds_write_b32 v151, v148 offset:5168
	v_fmac_f32_e32 v50, v116, v51
	v_fmac_f32_e32 v66, v118, v67
	v_fmac_f32_dpp v50, v51, v122 quad_perm:[1,0,3,2] row_mask:0xf bank_mask:0xf
	v_fmac_f32_dpp v66, v67, v123 quad_perm:[1,0,3,2] row_mask:0xf bank_mask:0xf
	v_cvt_pk_bf16_f32 v149, v50, v66
	ds_write_b32 v151, v149 offset:4896
	v_fmac_f32_e32 v49, v116, v50
	v_fmac_f32_e32 v65, v118, v66
	v_fmac_f32_dpp v49, v50, v122 quad_perm:[1,0,3,2] row_mask:0xf bank_mask:0xf
	v_fmac_f32_dpp v65, v66, v123 quad_perm:[1,0,3,2] row_mask:0xf bank_mask:0xf
	v_cvt_pk_bf16_f32 v148, v49, v65
	ds_write_b32 v151, v148 offset:4624
	v_fmac_f32_e32 v48, v116, v49
	v_fmac_f32_e32 v64, v118, v65
	v_fmac_f32_dpp v48, v49, v122 quad_perm:[1,0,3,2] row_mask:0xf bank_mask:0xf
	v_fmac_f32_dpp v64, v65, v123 quad_perm:[1,0,3,2] row_mask:0xf bank_mask:0xf
	v_cvt_pk_bf16_f32 v149, v48, v64
	ds_write_b32 v151, v149 offset:4352
	s_waitcnt vmcnt(5)
	ds_write_b128 v162, v[144:147] offset:1536
	v_cndmask_b32_e64 v182, 0, v144, s[66:67]
	v_cndmask_b32_e64 v183, 0, v145, s[66:67]
	v_cndmask_b32_e64 v184, 0, v146, s[66:67]
	v_cndmask_b32_e64 v185, 0, v147, s[66:67]
	v_cndmask_b32_e64 v186, 0, v144, s[68:69]
	v_cndmask_b32_e64 v187, 0, v145, s[68:69]
	v_cndmask_b32_e64 v188, 0, v146, s[68:69]
	v_cndmask_b32_e64 v189, 0, v147, s[68:69]
	global_load_dwordx4 v[144:147], v150, s[10:11] offset:512
	v_fmac_f32_e32 v31, v116, v48
	v_fmac_f32_e32 v47, v118, v64
	v_fmac_f32_dpp v31, v48, v122 quad_perm:[1,0,3,2] row_mask:0xf bank_mask:0xf
	v_fmac_f32_dpp v47, v64, v123 quad_perm:[1,0,3,2] row_mask:0xf bank_mask:0xf
	v_cvt_pk_bf16_f32 v148, v31, v47
	ds_write_b32 v151, v148 offset:4080
	v_fmac_f32_e32 v30, v116, v31
	v_fmac_f32_e32 v46, v118, v47
	v_fmac_f32_dpp v30, v31, v122 quad_perm:[1,0,3,2] row_mask:0xf bank_mask:0xf
	v_fmac_f32_dpp v46, v47, v123 quad_perm:[1,0,3,2] row_mask:0xf bank_mask:0xf
	v_cvt_pk_bf16_f32 v149, v30, v46
	ds_write_b32 v151, v149 offset:3808
	v_mfma_f32_32x32x16_bf16 v[48:63], v[182:185], v[84:87], 0
	v_fmac_f32_e32 v29, v116, v30
	v_fmac_f32_e32 v45, v118, v46
	v_fmac_f32_dpp v29, v30, v122 quad_perm:[1,0,3,2] row_mask:0xf bank_mask:0xf
	v_fmac_f32_dpp v45, v46, v123 quad_perm:[1,0,3,2] row_mask:0xf bank_mask:0xf
	v_cvt_pk_bf16_f32 v148, v29, v45
	ds_write_b32 v151, v148 offset:3536
	v_fmac_f32_e32 v28, v116, v29
	v_fmac_f32_e32 v44, v118, v45
	v_fmac_f32_dpp v28, v29, v122 quad_perm:[1,0,3,2] row_mask:0xf bank_mask:0xf
	v_fmac_f32_dpp v44, v45, v123 quad_perm:[1,0,3,2] row_mask:0xf bank_mask:0xf
	v_cvt_pk_bf16_f32 v149, v28, v44
	ds_write_b32 v151, v149 offset:3264
	v_mfma_f32_32x32x16_bf16 v[64:79], v[182:185], v[88:91], 0
	v_fmac_f32_e32 v27, v116, v28
	v_fmac_f32_e32 v43, v118, v44
	v_fmac_f32_dpp v27, v28, v122 quad_perm:[1,0,3,2] row_mask:0xf bank_mask:0xf
	v_fmac_f32_dpp v43, v44, v123 quad_perm:[1,0,3,2] row_mask:0xf bank_mask:0xf
	v_cvt_pk_bf16_f32 v148, v27, v43
	ds_write_b32 v151, v148 offset:2992
	v_fmac_f32_e32 v26, v116, v27
	v_fmac_f32_e32 v42, v118, v43
	v_fmac_f32_dpp v26, v27, v122 quad_perm:[1,0,3,2] row_mask:0xf bank_mask:0xf
	v_fmac_f32_dpp v42, v43, v123 quad_perm:[1,0,3,2] row_mask:0xf bank_mask:0xf
	v_cvt_pk_bf16_f32 v149, v26, v42
	ds_write_b32 v151, v149 offset:2720
	v_mfma_f32_32x32x16_bf16 v[48:63], v[186:189], v[92:95], v[48:63]
	v_fmac_f32_e32 v25, v116, v26
	v_fmac_f32_e32 v41, v118, v42
	v_fmac_f32_dpp v25, v26, v122 quad_perm:[1,0,3,2] row_mask:0xf bank_mask:0xf
	v_fmac_f32_dpp v41, v42, v123 quad_perm:[1,0,3,2] row_mask:0xf bank_mask:0xf
	v_cvt_pk_bf16_f32 v148, v25, v41
	ds_write_b32 v151, v148 offset:2448
	v_fmac_f32_e32 v24, v116, v25
	v_fmac_f32_e32 v40, v118, v41
	v_fmac_f32_dpp v24, v25, v122 quad_perm:[1,0,3,2] row_mask:0xf bank_mask:0xf
	v_fmac_f32_dpp v40, v41, v123 quad_perm:[1,0,3,2] row_mask:0xf bank_mask:0xf
	v_cvt_pk_bf16_f32 v149, v24, v40
	ds_write_b32 v151, v149 offset:2176
	v_mfma_f32_32x32x16_bf16 v[64:79], v[186:189], v[96:99], v[64:79]
	v_fmac_f32_e32 v23, v116, v24
	v_fmac_f32_e32 v39, v118, v40
	v_fmac_f32_dpp v23, v24, v122 quad_perm:[1,0,3,2] row_mask:0xf bank_mask:0xf
	v_fmac_f32_dpp v39, v40, v123 quad_perm:[1,0,3,2] row_mask:0xf bank_mask:0xf
	v_cvt_pk_bf16_f32 v148, v23, v39
	ds_write_b32 v151, v148 offset:1904
	v_fmac_f32_e32 v22, v116, v23
	v_fmac_f32_e32 v38, v118, v39
	v_fmac_f32_dpp v22, v23, v122 quad_perm:[1,0,3,2] row_mask:0xf bank_mask:0xf
	v_fmac_f32_dpp v38, v39, v123 quad_perm:[1,0,3,2] row_mask:0xf bank_mask:0xf
	v_cvt_pk_bf16_f32 v149, v22, v38
	ds_write_b32 v151, v149 offset:1632
	v_fmac_f32_e32 v21, v116, v22
	v_fmac_f32_e32 v37, v118, v38
	v_fmac_f32_dpp v21, v22, v122 quad_perm:[1,0,3,2] row_mask:0xf bank_mask:0xf
	v_fmac_f32_dpp v37, v38, v123 quad_perm:[1,0,3,2] row_mask:0xf bank_mask:0xf
	v_cvt_pk_bf16_f32 v148, v21, v37
	ds_write_b32 v151, v148 offset:1360
	v_fmac_f32_e32 v20, v116, v21
	v_fmac_f32_e32 v36, v118, v37
	v_fmac_f32_dpp v20, v21, v122 quad_perm:[1,0,3,2] row_mask:0xf bank_mask:0xf
	v_fmac_f32_dpp v36, v37, v123 quad_perm:[1,0,3,2] row_mask:0xf bank_mask:0xf
	v_cvt_pk_bf16_f32 v149, v20, v36
	ds_write_b32 v151, v149 offset:1088
	v_fmac_f32_e32 v19, v116, v20
	v_fmac_f32_e32 v35, v118, v36
	v_fmac_f32_dpp v19, v20, v122 quad_perm:[1,0,3,2] row_mask:0xf bank_mask:0xf
	v_fmac_f32_dpp v35, v36, v123 quad_perm:[1,0,3,2] row_mask:0xf bank_mask:0xf
	v_cvt_pk_bf16_f32 v148, v19, v35
	ds_write_b32 v151, v148 offset:816
	v_fmac_f32_e32 v18, v116, v19
	v_fmac_f32_e32 v34, v118, v35
	v_fmac_f32_dpp v18, v19, v122 quad_perm:[1,0,3,2] row_mask:0xf bank_mask:0xf
	v_fmac_f32_dpp v34, v35, v123 quad_perm:[1,0,3,2] row_mask:0xf bank_mask:0xf
	v_cvt_pk_bf16_f32 v149, v18, v34
	ds_write_b32 v151, v149 offset:544
	v_fmac_f32_e32 v17, v116, v18
	v_fmac_f32_e32 v33, v118, v34
	v_fmac_f32_dpp v17, v18, v122 quad_perm:[1,0,3,2] row_mask:0xf bank_mask:0xf
	v_fmac_f32_dpp v33, v34, v123 quad_perm:[1,0,3,2] row_mask:0xf bank_mask:0xf
	v_cvt_pk_bf16_f32 v148, v17, v33
	ds_write_b32 v151, v148 offset:272
	v_fmac_f32_e32 v16, v116, v17
	v_fmac_f32_e32 v32, v118, v33
	v_fmac_f32_dpp v16, v17, v122 quad_perm:[1,0,3,2] row_mask:0xf bank_mask:0xf
	v_fmac_f32_dpp v32, v33, v123 quad_perm:[1,0,3,2] row_mask:0xf bank_mask:0xf
	v_cvt_pk_bf16_f32 v149, v16, v32
	ds_write_b32 v151, v149
	v_mov_b32_e32 v120, v16
	v_mov_b32_e32 v121, v32
	s_waitcnt vmcnt(5)
	ds_write_b128 v162, v[6:9] offset:1024
	v_cndmask_b32_e64 v182, 0, v6, s[66:67]
	v_cndmask_b32_e64 v183, 0, v7, s[66:67]
	v_cndmask_b32_e64 v184, 0, v8, s[66:67]
	v_cndmask_b32_e64 v185, 0, v9, s[66:67]
	v_cndmask_b32_e64 v186, 0, v6, s[68:69]
	v_cndmask_b32_e64 v187, 0, v7, s[68:69]
	v_cndmask_b32_e64 v188, 0, v8, s[68:69]
	v_cndmask_b32_e64 v189, 0, v9, s[68:69]
	global_load_dwordx4 v[6:9], v150, s[10:11]
	s_add_u32 s29, s14, 4
	s_cmp_lt_u32 s29, 8
	s_cselect_b32 s29, 1024, 0
	s_sub_u32 s10, s10, s29
	s_subb_u32 s11, s11, 0
	ds_read_b128 v[124:127], v152
	ds_read_b128 v[128:131], v152 offset:64
	ds_read_b128 v[132:135], v152 offset:128
	ds_read_b128 v[136:139], v152 offset:192
	ds_read_b64 v[168:169], v171
	ds_read_b64 v[160:161], v163
	v_mfma_f32_32x32x16_bf16 v[16:31], v[182:185], v[84:87], 0
	v_mfma_f32_32x32x16_bf16 v[32:47], v[182:185], v[88:91], 0
	v_mfma_f32_32x32x16_bf16 v[16:31], v[186:189], v[92:95], v[16:31]
	v_mfma_f32_32x32x16_bf16 v[32:47], v[186:189], v[96:99], v[32:47]
	s_waitcnt lgkmcnt(5)
	v_mfma_f32_16x16x32_bf16 v[140:143], v[100:103], v[124:127], 0
	s_waitcnt lgkmcnt(4)
	v_mfma_f32_16x16x32_bf16 v[140:143], v[104:107], v[128:131], v[140:143]
	s_waitcnt lgkmcnt(3)
	v_mfma_f32_16x16x32_bf16 v[140:143], v[108:111], v[132:135], v[140:143]
	s_waitcnt lgkmcnt(2)
	v_mfma_f32_16x16x32_bf16 v[140:143], v[112:115], v[136:139], v[140:143]
	s_nop 9
	s_waitcnt lgkmcnt(0)
	v_lshlrev_b32_e32 v182, 16, v168
	v_and_b32_e32 v183, 0xffff0000, v168
	v_lshlrev_b32_e32 v184, 16, v169
	v_and_b32_e32 v185, 0xffff0000, v169
	v_add_f32_e32 v182, v182, v140
	v_add_f32_e32 v183, v183, v141
	v_add_f32_e32 v184, v184, v142
	v_add_f32_e32 v185, v185, v143
	v_lshlrev_b32_e32 v186, 16, v160
	v_and_b32_e32 v187, 0xffff0000, v160
	v_lshlrev_b32_e32 v188, 16, v161
	v_and_b32_e32 v189, 0xffff0000, v161
	v_fmac_f32_e32 v182, v164, v186
	v_fmac_f32_e32 v183, v165, v187
	v_fmac_f32_e32 v184, v166, v188
	v_fmac_f32_e32 v185, v167, v189
	v_mul_f32_e32 v186, 0x3d372713, v182
	v_mul_f32_e32 v187, 0x3d372713, v183
	v_mul_f32_e32 v188, 0x3d372713, v184
	v_mul_f32_e32 v189, 0x3d372713, v185
	v_mul_f32_e32 v186, v182, v186
	v_mul_f32_e32 v187, v183, v187
	v_mul_f32_e32 v188, v184, v188
	v_mul_f32_e32 v189, v185, v189
	v_fma_f32 v186, v182, v186, v182
	v_fma_f32 v187, v183, v187, v183
	v_fma_f32 v188, v184, v188, v184
	v_fma_f32 v189, v185, v189, v185
	v_mul_f32_e32 v186, 0xbfcc422a, v186
	v_mul_f32_e32 v187, 0xbfcc422a, v187
	v_mul_f32_e32 v188, 0xbfcc422a, v188
	v_mul_f32_e32 v189, 0xbfcc422a, v189
	v_mul_f32_e32 v186, 0x3fb8aa3b, v186
	v_mul_f32_e32 v187, 0x3fb8aa3b, v187
	v_mul_f32_e32 v188, 0x3fb8aa3b, v188
	v_mul_f32_e32 v189, 0x3fb8aa3b, v189
	v_exp_f32_e32 v186, v186
	v_exp_f32_e32 v187, v187
	v_exp_f32_e32 v188, v188
	v_exp_f32_e32 v189, v189
	v_add_f32_e32 v186, 1.0, v186
	v_add_f32_e32 v187, 1.0, v187
	v_add_f32_e32 v188, 1.0, v188
	v_add_f32_e32 v189, 1.0, v189
	v_rcp_f32_e32 v186, v186
	v_rcp_f32_e32 v187, v187
	v_rcp_f32_e32 v188, v188
	v_rcp_f32_e32 v189, v189
	v_mul_f32_e32 v182, v182, v186
	v_mul_f32_e32 v183, v183, v187
	v_mul_f32_e32 v184, v184, v188
	v_mul_f32_e32 v185, v185, v189
	v_cvt_pk_bf16_f32 v148, v182, v183
	v_cvt_pk_bf16_f32 v149, v184, v185
	global_store_dwordx2 v156, v[148:149], s[12:13]
	ds_read_b128 v[124:127], v152 offset:4352
	ds_read_b128 v[128:131], v152 offset:4416
	ds_read_b128 v[132:135], v152 offset:4480
	ds_read_b128 v[136:139], v152 offset:4544
	ds_read_b64 v[168:169], v171 offset:512
	ds_read_b64 v[160:161], v163 offset:512
	s_waitcnt lgkmcnt(5)
	v_mfma_f32_16x16x32_bf16 v[140:143], v[100:103], v[124:127], 0
	s_waitcnt lgkmcnt(4)
	v_mfma_f32_16x16x32_bf16 v[140:143], v[104:107], v[128:131], v[140:143]
	s_waitcnt lgkmcnt(3)
	v_mfma_f32_16x16x32_bf16 v[140:143], v[108:111], v[132:135], v[140:143]
	s_waitcnt lgkmcnt(2)
	v_mfma_f32_16x16x32_bf16 v[140:143], v[112:115], v[136:139], v[140:143]
	s_nop 9
	s_waitcnt lgkmcnt(0)
	v_lshlrev_b32_e32 v182, 16, v168
	v_and_b32_e32 v183, 0xffff0000, v168
	v_lshlrev_b32_e32 v184, 16, v169
	v_and_b32_e32 v185, 0xffff0000, v169
	v_add_f32_e32 v182, v182, v140
	v_add_f32_e32 v183, v183, v141
	v_add_f32_e32 v184, v184, v142
	v_add_f32_e32 v185, v185, v143
	v_lshlrev_b32_e32 v186, 16, v160
	v_and_b32_e32 v187, 0xffff0000, v160
	v_lshlrev_b32_e32 v188, 16, v161
	v_and_b32_e32 v189, 0xffff0000, v161
	v_fmac_f32_e32 v182, v164, v186
	v_fmac_f32_e32 v183, v165, v187
	v_fmac_f32_e32 v184, v166, v188
	v_fmac_f32_e32 v185, v167, v189
	v_mul_f32_e32 v186, 0x3d372713, v182
	v_mul_f32_e32 v187, 0x3d372713, v183
	v_mul_f32_e32 v188, 0x3d372713, v184
	v_mul_f32_e32 v189, 0x3d372713, v185
	v_mul_f32_e32 v186, v182, v186
	v_mul_f32_e32 v187, v183, v187
	v_mul_f32_e32 v188, v184, v188
	v_mul_f32_e32 v189, v185, v189
	v_fma_f32 v186, v182, v186, v182
	v_fma_f32 v187, v183, v187, v183
	v_fma_f32 v188, v184, v188, v184
	v_fma_f32 v189, v185, v189, v185
	v_mul_f32_e32 v186, 0xbfcc422a, v186
	v_mul_f32_e32 v187, 0xbfcc422a, v187
	v_mul_f32_e32 v188, 0xbfcc422a, v188
	v_mul_f32_e32 v189, 0xbfcc422a, v189
	v_mul_f32_e32 v186, 0x3fb8aa3b, v186
	v_mul_f32_e32 v187, 0x3fb8aa3b, v187
	v_mul_f32_e32 v188, 0x3fb8aa3b, v188
	v_mul_f32_e32 v189, 0x3fb8aa3b, v189
	v_exp_f32_e32 v186, v186
	v_exp_f32_e32 v187, v187
	v_exp_f32_e32 v188, v188
	v_exp_f32_e32 v189, v189
	v_add_f32_e32 v186, 1.0, v186
	v_add_f32_e32 v187, 1.0, v187
	v_add_f32_e32 v188, 1.0, v188
	v_add_f32_e32 v189, 1.0, v189
	v_rcp_f32_e32 v186, v186
	v_rcp_f32_e32 v187, v187
	v_rcp_f32_e32 v188, v188
	v_rcp_f32_e32 v189, v189
	v_mul_f32_e32 v182, v182, v186
	v_mul_f32_e32 v183, v183, v187
	v_mul_f32_e32 v184, v184, v188
	v_mul_f32_e32 v185, v185, v189
	v_cvt_pk_bf16_f32 v148, v182, v183
	v_cvt_pk_bf16_f32 v149, v184, v185
	global_store_dwordx2 v159, v[148:149], s[12:13]
	s_sub_u32 s12, s12, 65536
	s_subb_u32 s13, s13, 0
	s_sub_u32 s36, s36, 1024
	v_add_u32_e32 v171, s36, v155
	v_fmac_f32_e32 v63, v116, v120
	v_fmac_f32_e32 v79, v118, v121
	v_fmac_f32_dpp v63, v120, v122 quad_perm:[1,0,3,2] row_mask:0xf bank_mask:0xf
	v_fmac_f32_dpp v79, v121, v123 quad_perm:[1,0,3,2] row_mask:0xf bank_mask:0xf
	v_cvt_pk_bf16_f32 v148, v63, v79
	ds_write_b32 v151, v148 offset:8432
	v_fmac_f32_e32 v62, v116, v63
	v_fmac_f32_e32 v78, v118, v79
	v_fmac_f32_dpp v62, v63, v122 quad_perm:[1,0,3,2] row_mask:0xf bank_mask:0xf
	v_fmac_f32_dpp v78, v79, v123 quad_perm:[1,0,3,2] row_mask:0xf bank_mask:0xf
	v_cvt_pk_bf16_f32 v149, v62, v78
	ds_write_b32 v151, v149 offset:8160
	v_fmac_f32_e32 v61, v116, v62
	v_fmac_f32_e32 v77, v118, v78
	v_fmac_f32_dpp v61, v62, v122 quad_perm:[1,0,3,2] row_mask:0xf bank_mask:0xf
	v_fmac_f32_dpp v77, v78, v123 quad_perm:[1,0,3,2] row_mask:0xf bank_mask:0xf
	v_cvt_pk_bf16_f32 v148, v61, v77
	ds_write_b32 v151, v148 offset:7888
	v_fmac_f32_e32 v60, v116, v61
	v_fmac_f32_e32 v76, v118, v77
	v_fmac_f32_dpp v60, v61, v122 quad_perm:[1,0,3,2] row_mask:0xf bank_mask:0xf
	v_fmac_f32_dpp v76, v77, v123 quad_perm:[1,0,3,2] row_mask:0xf bank_mask:0xf
	v_cvt_pk_bf16_f32 v149, v60, v76
	ds_write_b32 v151, v149 offset:7616
	v_fmac_f32_e32 v59, v116, v60
	v_fmac_f32_e32 v75, v118, v76
	v_fmac_f32_dpp v59, v60, v122 quad_perm:[1,0,3,2] row_mask:0xf bank_mask:0xf
	v_fmac_f32_dpp v75, v76, v123 quad_perm:[1,0,3,2] row_mask:0xf bank_mask:0xf
	v_cvt_pk_bf16_f32 v148, v59, v75
	ds_write_b32 v151, v148 offset:7344
	v_fmac_f32_e32 v58, v116, v59
	v_fmac_f32_e32 v74, v118, v75
	v_fmac_f32_dpp v58, v59, v122 quad_perm:[1,0,3,2] row_mask:0xf bank_mask:0xf
	v_fmac_f32_dpp v74, v75, v123 quad_perm:[1,0,3,2] row_mask:0xf bank_mask:0xf
	v_cvt_pk_bf16_f32 v149, v58, v74
	ds_write_b32 v151, v149 offset:7072
	v_fmac_f32_e32 v57, v116, v58
	v_fmac_f32_e32 v73, v118, v74
	v_fmac_f32_dpp v57, v58, v122 quad_perm:[1,0,3,2] row_mask:0xf bank_mask:0xf
	v_fmac_f32_dpp v73, v74, v123 quad_perm:[1,0,3,2] row_mask:0xf bank_mask:0xf
	v_cvt_pk_bf16_f32 v148, v57, v73
	ds_write_b32 v151, v148 offset:6800
	v_fmac_f32_e32 v56, v116, v57
	v_fmac_f32_e32 v72, v118, v73
	v_fmac_f32_dpp v56, v57, v122 quad_perm:[1,0,3,2] row_mask:0xf bank_mask:0xf
	v_fmac_f32_dpp v72, v73, v123 quad_perm:[1,0,3,2] row_mask:0xf bank_mask:0xf
	v_cvt_pk_bf16_f32 v149, v56, v72
	ds_write_b32 v151, v149 offset:6528
	v_fmac_f32_e32 v55, v116, v56
	v_fmac_f32_e32 v71, v118, v72
	v_fmac_f32_dpp v55, v56, v122 quad_perm:[1,0,3,2] row_mask:0xf bank_mask:0xf
	v_fmac_f32_dpp v71, v72, v123 quad_perm:[1,0,3,2] row_mask:0xf bank_mask:0xf
	v_cvt_pk_bf16_f32 v148, v55, v71
	ds_write_b32 v151, v148 offset:6256
	v_fmac_f32_e32 v54, v116, v55
	v_fmac_f32_e32 v70, v118, v71
	v_fmac_f32_dpp v54, v55, v122 quad_perm:[1,0,3,2] row_mask:0xf bank_mask:0xf
	v_fmac_f32_dpp v70, v71, v123 quad_perm:[1,0,3,2] row_mask:0xf bank_mask:0xf
	v_cvt_pk_bf16_f32 v149, v54, v70
	ds_write_b32 v151, v149 offset:5984
	v_fmac_f32_e32 v53, v116, v54
	v_fmac_f32_e32 v69, v118, v70
	v_fmac_f32_dpp v53, v54, v122 quad_perm:[1,0,3,2] row_mask:0xf bank_mask:0xf
	v_fmac_f32_dpp v69, v70, v123 quad_perm:[1,0,3,2] row_mask:0xf bank_mask:0xf
	v_cvt_pk_bf16_f32 v148, v53, v69
	ds_write_b32 v151, v148 offset:5712
	v_fmac_f32_e32 v52, v116, v53
	v_fmac_f32_e32 v68, v118, v69
	v_fmac_f32_dpp v52, v53, v122 quad_perm:[1,0,3,2] row_mask:0xf bank_mask:0xf
	v_fmac_f32_dpp v68, v69, v123 quad_perm:[1,0,3,2] row_mask:0xf bank_mask:0xf
	v_cvt_pk_bf16_f32 v149, v52, v68
	ds_write_b32 v151, v149 offset:5440
	v_fmac_f32_e32 v51, v116, v52
	v_fmac_f32_e32 v67, v118, v68
	v_fmac_f32_dpp v51, v52, v122 quad_perm:[1,0,3,2] row_mask:0xf bank_mask:0xf
	v_fmac_f32_dpp v67, v68, v123 quad_perm:[1,0,3,2] row_mask:0xf bank_mask:0xf
	v_cvt_pk_bf16_f32 v148, v51, v67
	ds_write_b32 v151, v148 offset:5168
	v_fmac_f32_e32 v50, v116, v51
	v_fmac_f32_e32 v66, v118, v67
	v_fmac_f32_dpp v50, v51, v122 quad_perm:[1,0,3,2] row_mask:0xf bank_mask:0xf
	v_fmac_f32_dpp v66, v67, v123 quad_perm:[1,0,3,2] row_mask:0xf bank_mask:0xf
	v_cvt_pk_bf16_f32 v149, v50, v66
	ds_write_b32 v151, v149 offset:4896
	v_fmac_f32_e32 v49, v116, v50
	v_fmac_f32_e32 v65, v118, v66
	v_fmac_f32_dpp v49, v50, v122 quad_perm:[1,0,3,2] row_mask:0xf bank_mask:0xf
	v_fmac_f32_dpp v65, v66, v123 quad_perm:[1,0,3,2] row_mask:0xf bank_mask:0xf
	v_cvt_pk_bf16_f32 v148, v49, v65
	ds_write_b32 v151, v148 offset:4624
	v_fmac_f32_e32 v48, v116, v49
	v_fmac_f32_e32 v64, v118, v65
	v_fmac_f32_dpp v48, v49, v122 quad_perm:[1,0,3,2] row_mask:0xf bank_mask:0xf
	v_fmac_f32_dpp v64, v65, v123 quad_perm:[1,0,3,2] row_mask:0xf bank_mask:0xf
	v_cvt_pk_bf16_f32 v149, v48, v64
	ds_write_b32 v151, v149 offset:4352
	s_waitcnt vmcnt(5)
	ds_write_b128 v162, v[80:83] offset:512
	v_cndmask_b32_e64 v182, 0, v80, s[66:67]
	v_cndmask_b32_e64 v183, 0, v81, s[66:67]
	v_cndmask_b32_e64 v184, 0, v82, s[66:67]
	v_cndmask_b32_e64 v185, 0, v83, s[66:67]
	v_cndmask_b32_e64 v186, 0, v80, s[68:69]
	v_cndmask_b32_e64 v187, 0, v81, s[68:69]
	v_cndmask_b32_e64 v188, 0, v82, s[68:69]
	v_cndmask_b32_e64 v189, 0, v83, s[68:69]
	global_load_dwordx4 v[80:83], v150, s[10:11] offset:512
	v_fmac_f32_e32 v31, v116, v48
	v_fmac_f32_e32 v47, v118, v64
	v_fmac_f32_dpp v31, v48, v122 quad_perm:[1,0,3,2] row_mask:0xf bank_mask:0xf
	v_fmac_f32_dpp v47, v64, v123 quad_perm:[1,0,3,2] row_mask:0xf bank_mask:0xf
	v_cvt_pk_bf16_f32 v148, v31, v47
	ds_write_b32 v151, v148 offset:4080
	v_fmac_f32_e32 v30, v116, v31
	v_fmac_f32_e32 v46, v118, v47
	v_fmac_f32_dpp v30, v31, v122 quad_perm:[1,0,3,2] row_mask:0xf bank_mask:0xf
	v_fmac_f32_dpp v46, v47, v123 quad_perm:[1,0,3,2] row_mask:0xf bank_mask:0xf
	v_cvt_pk_bf16_f32 v149, v30, v46
	ds_write_b32 v151, v149 offset:3808
	v_mfma_f32_32x32x16_bf16 v[48:63], v[182:185], v[84:87], 0
	v_fmac_f32_e32 v29, v116, v30
	v_fmac_f32_e32 v45, v118, v46
	v_fmac_f32_dpp v29, v30, v122 quad_perm:[1,0,3,2] row_mask:0xf bank_mask:0xf
	v_fmac_f32_dpp v45, v46, v123 quad_perm:[1,0,3,2] row_mask:0xf bank_mask:0xf
	v_cvt_pk_bf16_f32 v148, v29, v45
	ds_write_b32 v151, v148 offset:3536
	v_fmac_f32_e32 v28, v116, v29
	v_fmac_f32_e32 v44, v118, v45
	v_fmac_f32_dpp v28, v29, v122 quad_perm:[1,0,3,2] row_mask:0xf bank_mask:0xf
	v_fmac_f32_dpp v44, v45, v123 quad_perm:[1,0,3,2] row_mask:0xf bank_mask:0xf
	v_cvt_pk_bf16_f32 v149, v28, v44
	ds_write_b32 v151, v149 offset:3264
	v_mfma_f32_32x32x16_bf16 v[64:79], v[182:185], v[88:91], 0
	v_fmac_f32_e32 v27, v116, v28
	v_fmac_f32_e32 v43, v118, v44
	v_fmac_f32_dpp v27, v28, v122 quad_perm:[1,0,3,2] row_mask:0xf bank_mask:0xf
	v_fmac_f32_dpp v43, v44, v123 quad_perm:[1,0,3,2] row_mask:0xf bank_mask:0xf
	v_cvt_pk_bf16_f32 v148, v27, v43
	ds_write_b32 v151, v148 offset:2992
	v_fmac_f32_e32 v26, v116, v27
	v_fmac_f32_e32 v42, v118, v43
	v_fmac_f32_dpp v26, v27, v122 quad_perm:[1,0,3,2] row_mask:0xf bank_mask:0xf
	v_fmac_f32_dpp v42, v43, v123 quad_perm:[1,0,3,2] row_mask:0xf bank_mask:0xf
	v_cvt_pk_bf16_f32 v149, v26, v42
	ds_write_b32 v151, v149 offset:2720
	v_mfma_f32_32x32x16_bf16 v[48:63], v[186:189], v[92:95], v[48:63]
	v_fmac_f32_e32 v25, v116, v26
	v_fmac_f32_e32 v41, v118, v42
	v_fmac_f32_dpp v25, v26, v122 quad_perm:[1,0,3,2] row_mask:0xf bank_mask:0xf
	v_fmac_f32_dpp v41, v42, v123 quad_perm:[1,0,3,2] row_mask:0xf bank_mask:0xf
	v_cvt_pk_bf16_f32 v148, v25, v41
	ds_write_b32 v151, v148 offset:2448
	v_fmac_f32_e32 v24, v116, v25
	v_fmac_f32_e32 v40, v118, v41
	v_fmac_f32_dpp v24, v25, v122 quad_perm:[1,0,3,2] row_mask:0xf bank_mask:0xf
	v_fmac_f32_dpp v40, v41, v123 quad_perm:[1,0,3,2] row_mask:0xf bank_mask:0xf
	v_cvt_pk_bf16_f32 v149, v24, v40
	ds_write_b32 v151, v149 offset:2176
	v_mfma_f32_32x32x16_bf16 v[64:79], v[186:189], v[96:99], v[64:79]
	v_fmac_f32_e32 v23, v116, v24
	v_fmac_f32_e32 v39, v118, v40
	v_fmac_f32_dpp v23, v24, v122 quad_perm:[1,0,3,2] row_mask:0xf bank_mask:0xf
	v_fmac_f32_dpp v39, v40, v123 quad_perm:[1,0,3,2] row_mask:0xf bank_mask:0xf
	v_cvt_pk_bf16_f32 v148, v23, v39
	ds_write_b32 v151, v148 offset:1904
	v_fmac_f32_e32 v22, v116, v23
	v_fmac_f32_e32 v38, v118, v39
	v_fmac_f32_dpp v22, v23, v122 quad_perm:[1,0,3,2] row_mask:0xf bank_mask:0xf
	v_fmac_f32_dpp v38, v39, v123 quad_perm:[1,0,3,2] row_mask:0xf bank_mask:0xf
	v_cvt_pk_bf16_f32 v149, v22, v38
	ds_write_b32 v151, v149 offset:1632
	v_fmac_f32_e32 v21, v116, v22
	v_fmac_f32_e32 v37, v118, v38
	v_fmac_f32_dpp v21, v22, v122 quad_perm:[1,0,3,2] row_mask:0xf bank_mask:0xf
	v_fmac_f32_dpp v37, v38, v123 quad_perm:[1,0,3,2] row_mask:0xf bank_mask:0xf
	v_cvt_pk_bf16_f32 v148, v21, v37
	ds_write_b32 v151, v148 offset:1360
	v_fmac_f32_e32 v20, v116, v21
	v_fmac_f32_e32 v36, v118, v37
	v_fmac_f32_dpp v20, v21, v122 quad_perm:[1,0,3,2] row_mask:0xf bank_mask:0xf
	v_fmac_f32_dpp v36, v37, v123 quad_perm:[1,0,3,2] row_mask:0xf bank_mask:0xf
	v_cvt_pk_bf16_f32 v149, v20, v36
	ds_write_b32 v151, v149 offset:1088
	v_fmac_f32_e32 v19, v116, v20
	v_fmac_f32_e32 v35, v118, v36
	v_fmac_f32_dpp v19, v20, v122 quad_perm:[1,0,3,2] row_mask:0xf bank_mask:0xf
	v_fmac_f32_dpp v35, v36, v123 quad_perm:[1,0,3,2] row_mask:0xf bank_mask:0xf
	v_cvt_pk_bf16_f32 v148, v19, v35
	ds_write_b32 v151, v148 offset:816
	v_fmac_f32_e32 v18, v116, v19
	v_fmac_f32_e32 v34, v118, v35
	v_fmac_f32_dpp v18, v19, v122 quad_perm:[1,0,3,2] row_mask:0xf bank_mask:0xf
	v_fmac_f32_dpp v34, v35, v123 quad_perm:[1,0,3,2] row_mask:0xf bank_mask:0xf
	v_cvt_pk_bf16_f32 v149, v18, v34
	ds_write_b32 v151, v149 offset:544
	v_fmac_f32_e32 v17, v116, v18
	v_fmac_f32_e32 v33, v118, v34
	v_fmac_f32_dpp v17, v18, v122 quad_perm:[1,0,3,2] row_mask:0xf bank_mask:0xf
	v_fmac_f32_dpp v33, v34, v123 quad_perm:[1,0,3,2] row_mask:0xf bank_mask:0xf
	v_cvt_pk_bf16_f32 v148, v17, v33
	ds_write_b32 v151, v148 offset:272
	v_fmac_f32_e32 v16, v116, v17
	v_fmac_f32_e32 v32, v118, v33
	v_fmac_f32_dpp v16, v17, v122 quad_perm:[1,0,3,2] row_mask:0xf bank_mask:0xf
	v_fmac_f32_dpp v32, v33, v123 quad_perm:[1,0,3,2] row_mask:0xf bank_mask:0xf
	v_cvt_pk_bf16_f32 v149, v16, v32
	ds_write_b32 v151, v149
	v_mov_b32_e32 v120, v16
	v_mov_b32_e32 v121, v32
	s_waitcnt vmcnt(5)
	ds_write_b128 v162, v[194:197]
	v_cndmask_b32_e64 v182, 0, v194, s[66:67]
	v_cndmask_b32_e64 v183, 0, v195, s[66:67]
	v_cndmask_b32_e64 v184, 0, v196, s[66:67]
	v_cndmask_b32_e64 v185, 0, v197, s[66:67]
	v_cndmask_b32_e64 v186, 0, v194, s[68:69]
	v_cndmask_b32_e64 v187, 0, v195, s[68:69]
	v_cndmask_b32_e64 v188, 0, v196, s[68:69]
	v_cndmask_b32_e64 v189, 0, v197, s[68:69]
	global_load_dwordx4 v[194:197], v150, s[10:11]
	s_add_u32 s29, s14, 5
	s_cmp_lt_u32 s29, 8
	s_cselect_b32 s29, 1024, 0
	s_sub_u32 s10, s10, s29
	s_subb_u32 s11, s11, 0
	ds_read_b128 v[124:127], v152
	ds_read_b128 v[128:131], v152 offset:64
	ds_read_b128 v[132:135], v152 offset:128
	ds_read_b128 v[136:139], v152 offset:192
	ds_read_b64 v[168:169], v171
	ds_read_b64 v[160:161], v163 offset:1024
	v_mfma_f32_32x32x16_bf16 v[16:31], v[182:185], v[84:87], 0
	v_mfma_f32_32x32x16_bf16 v[32:47], v[182:185], v[88:91], 0
	v_mfma_f32_32x32x16_bf16 v[16:31], v[186:189], v[92:95], v[16:31]
	v_mfma_f32_32x32x16_bf16 v[32:47], v[186:189], v[96:99], v[32:47]
	s_waitcnt lgkmcnt(5)
	v_mfma_f32_16x16x32_bf16 v[140:143], v[100:103], v[124:127], 0
	s_waitcnt lgkmcnt(4)
	v_mfma_f32_16x16x32_bf16 v[140:143], v[104:107], v[128:131], v[140:143]
	s_waitcnt lgkmcnt(3)
	v_mfma_f32_16x16x32_bf16 v[140:143], v[108:111], v[132:135], v[140:143]
	s_waitcnt lgkmcnt(2)
	v_mfma_f32_16x16x32_bf16 v[140:143], v[112:115], v[136:139], v[140:143]
	s_nop 9
	s_waitcnt lgkmcnt(0)
	v_lshlrev_b32_e32 v182, 16, v168
	v_and_b32_e32 v183, 0xffff0000, v168
	v_lshlrev_b32_e32 v184, 16, v169
	v_and_b32_e32 v185, 0xffff0000, v169
	v_add_f32_e32 v182, v182, v140
	v_add_f32_e32 v183, v183, v141
	v_add_f32_e32 v184, v184, v142
	v_add_f32_e32 v185, v185, v143
	v_lshlrev_b32_e32 v186, 16, v160
	v_and_b32_e32 v187, 0xffff0000, v160
	v_lshlrev_b32_e32 v188, 16, v161
	v_and_b32_e32 v189, 0xffff0000, v161
	v_fmac_f32_e32 v182, v164, v186
	v_fmac_f32_e32 v183, v165, v187
	v_fmac_f32_e32 v184, v166, v188
	v_fmac_f32_e32 v185, v167, v189
	v_mul_f32_e32 v186, 0x3d372713, v182
	v_mul_f32_e32 v187, 0x3d372713, v183
	v_mul_f32_e32 v188, 0x3d372713, v184
	v_mul_f32_e32 v189, 0x3d372713, v185
	v_mul_f32_e32 v186, v182, v186
	v_mul_f32_e32 v187, v183, v187
	v_mul_f32_e32 v188, v184, v188
	v_mul_f32_e32 v189, v185, v189
	v_fma_f32 v186, v182, v186, v182
	v_fma_f32 v187, v183, v187, v183
	v_fma_f32 v188, v184, v188, v184
	v_fma_f32 v189, v185, v189, v185
	v_mul_f32_e32 v186, 0xbfcc422a, v186
	v_mul_f32_e32 v187, 0xbfcc422a, v187
	v_mul_f32_e32 v188, 0xbfcc422a, v188
	v_mul_f32_e32 v189, 0xbfcc422a, v189
	v_mul_f32_e32 v186, 0x3fb8aa3b, v186
	v_mul_f32_e32 v187, 0x3fb8aa3b, v187
	v_mul_f32_e32 v188, 0x3fb8aa3b, v188
	v_mul_f32_e32 v189, 0x3fb8aa3b, v189
	v_exp_f32_e32 v186, v186
	v_exp_f32_e32 v187, v187
	v_exp_f32_e32 v188, v188
	v_exp_f32_e32 v189, v189
	v_add_f32_e32 v186, 1.0, v186
	v_add_f32_e32 v187, 1.0, v187
	v_add_f32_e32 v188, 1.0, v188
	v_add_f32_e32 v189, 1.0, v189
	v_rcp_f32_e32 v186, v186
	v_rcp_f32_e32 v187, v187
	v_rcp_f32_e32 v188, v188
	v_rcp_f32_e32 v189, v189
	v_mul_f32_e32 v182, v182, v186
	v_mul_f32_e32 v183, v183, v187
	v_mul_f32_e32 v184, v184, v188
	v_mul_f32_e32 v185, v185, v189
	v_cvt_pk_bf16_f32 v148, v182, v183
	v_cvt_pk_bf16_f32 v149, v184, v185
	global_store_dwordx2 v156, v[148:149], s[12:13]
	ds_read_b128 v[124:127], v152 offset:4352
	ds_read_b128 v[128:131], v152 offset:4416
	ds_read_b128 v[132:135], v152 offset:4480
	ds_read_b128 v[136:139], v152 offset:4544
	ds_read_b64 v[168:169], v171 offset:512
	ds_read_b64 v[160:161], v163 offset:1536
	s_waitcnt lgkmcnt(5)
	v_mfma_f32_16x16x32_bf16 v[140:143], v[100:103], v[124:127], 0
	s_waitcnt lgkmcnt(4)
	v_mfma_f32_16x16x32_bf16 v[140:143], v[104:107], v[128:131], v[140:143]
	s_waitcnt lgkmcnt(3)
	v_mfma_f32_16x16x32_bf16 v[140:143], v[108:111], v[132:135], v[140:143]
	s_waitcnt lgkmcnt(2)
	v_mfma_f32_16x16x32_bf16 v[140:143], v[112:115], v[136:139], v[140:143]
	s_nop 9
	s_waitcnt lgkmcnt(0)
	v_lshlrev_b32_e32 v182, 16, v168
	v_and_b32_e32 v183, 0xffff0000, v168
	v_lshlrev_b32_e32 v184, 16, v169
	v_and_b32_e32 v185, 0xffff0000, v169
	v_add_f32_e32 v182, v182, v140
	v_add_f32_e32 v183, v183, v141
	v_add_f32_e32 v184, v184, v142
	v_add_f32_e32 v185, v185, v143
	v_lshlrev_b32_e32 v186, 16, v160
	v_and_b32_e32 v187, 0xffff0000, v160
	v_lshlrev_b32_e32 v188, 16, v161
	v_and_b32_e32 v189, 0xffff0000, v161
	v_fmac_f32_e32 v182, v164, v186
	v_fmac_f32_e32 v183, v165, v187
	v_fmac_f32_e32 v184, v166, v188
	v_fmac_f32_e32 v185, v167, v189
	v_mul_f32_e32 v186, 0x3d372713, v182
	v_mul_f32_e32 v187, 0x3d372713, v183
	v_mul_f32_e32 v188, 0x3d372713, v184
	v_mul_f32_e32 v189, 0x3d372713, v185
	v_mul_f32_e32 v186, v182, v186
	v_mul_f32_e32 v187, v183, v187
	v_mul_f32_e32 v188, v184, v188
	v_mul_f32_e32 v189, v185, v189
	v_fma_f32 v186, v182, v186, v182
	v_fma_f32 v187, v183, v187, v183
	v_fma_f32 v188, v184, v188, v184
	v_fma_f32 v189, v185, v189, v185
	v_mul_f32_e32 v186, 0xbfcc422a, v186
	v_mul_f32_e32 v187, 0xbfcc422a, v187
	v_mul_f32_e32 v188, 0xbfcc422a, v188
	v_mul_f32_e32 v189, 0xbfcc422a, v189
	v_mul_f32_e32 v186, 0x3fb8aa3b, v186
	v_mul_f32_e32 v187, 0x3fb8aa3b, v187
	v_mul_f32_e32 v188, 0x3fb8aa3b, v188
	v_mul_f32_e32 v189, 0x3fb8aa3b, v189
	v_exp_f32_e32 v186, v186
	v_exp_f32_e32 v187, v187
	v_exp_f32_e32 v188, v188
	v_exp_f32_e32 v189, v189
	v_add_f32_e32 v186, 1.0, v186
	v_add_f32_e32 v187, 1.0, v187
	v_add_f32_e32 v188, 1.0, v188
	v_add_f32_e32 v189, 1.0, v189
	v_rcp_f32_e32 v186, v186
	v_rcp_f32_e32 v187, v187
	v_rcp_f32_e32 v188, v188
	v_rcp_f32_e32 v189, v189
	v_mul_f32_e32 v182, v182, v186
	v_mul_f32_e32 v183, v183, v187
	v_mul_f32_e32 v184, v184, v188
	v_mul_f32_e32 v185, v185, v189
	v_cvt_pk_bf16_f32 v148, v182, v183
	v_cvt_pk_bf16_f32 v149, v184, v185
	global_store_dwordx2 v159, v[148:149], s[12:13]
	s_sub_u32 s12, s12, 65536
	s_subb_u32 s13, s13, 0
	s_sub_u32 s36, s36, 1024
	s_add_u32 s14, s14, 2
	s_cmp_lt_u32 s14, 8
	s_cbranch_scc1 .Lssm_tile_d1m2
	s_add_u32 s30, s30, 0x8000000
	s_add_u32 s16, s60, s30
	s_addc_u32 s17, s61, 0
	global_store_dword v180, v120, s[16:17]
	global_store_dword v180, v121, s[16:17] offset:64
	s_waitcnt vmcnt(0) lgkmcnt(0)
	s_add_u32 s27, s27, 1
	s_cmp_lt_u32 s27, 2
	s_cbranch_scc1 .Lssm_ctx_loop
